# hyena: spec loads batched per loop trip and conv-tap cache lines touched up front; EpiProj deferred gate load hoisted; GEMM-in round order for cache residency; mixA V dwordx4; first seam uses XCD barr
# speedup vs baseline: 1.0228x; 1.0189x over previous
; #define PG8_STAGE(bufoff, gbase, voff) do { _Pragma("unroll") for (int _i = 0; _i < 2; ++_i) \
;         __builtin_amdgcn_global_load_lds((const unsigned*)((const char*)(gbase) + (voff)[_i]), (LAS unsigned*)(lds + (bufoff) + ldsw + _i * 8192), 16, 0, 0); } while (0)
; #define PG8_LDA(dst, b, h) do { _Pragma("unroll") for (int m = 0; m < 4; ++m) _Pragma("unroll") for (int k = 0; k < 2; ++k) dst[m][k] = *(const LAS bf16x8*)(lds + PG8_SA(b, h) + aoff + m * 2048 + k * 1024); } while (0)
; #define PG8_LDB(dst, b, h) do { _Pragma("unroll") for (int n = 0; n < 2; ++n) _Pragma("unroll") for (int k = 0; k < 2; ++k) dst[n][k] = *(const LAS bf16x8*)(lds + PG8_SB(b, h) + boff + n * 2048 + k * 1024); } while (0)
; #define PG8_MMA(ai, bj, At, Bt) do { __builtin_amdgcn_s_setprio(1); _Pragma("unroll") for (int m = 0; m < 4; ++m) _Pragma("unroll") for (int n = 0; n < 2; ++n) _Pragma("unroll") for (int k = 0; k < 2; ++k) \
;         acc[ai][bj][m][n] = __builtin_amdgcn_mfma_f32_16x16x32_bf16(Bt[n][k], At[m][k], acc[ai][bj][m][n], 0, 0, 0); __builtin_amdgcn_s_setprio(0); } while (0)
; #define PG8_WAIT_L(n) asm volatile("s_waitcnt lgkmcnt(" #n ")" ::: "memory")
; #define PG8_BAR __builtin_amdgcn_s_barrier()
; #define PG8_SCHED __builtin_amdgcn_sched_barrier(0)
; template <class Epi, class Sched>
; DI void gemm_phase(LAS unsigned char* lds, const Gemm g, const Sched& S, const Epi& E) {
;     ...
;             PG8_LDB(B0, 0, 0); PG8_SCHED; PG8_LDA(At, 0, 0); PG8_STAGE(PG8_SA(1, 1), a1 + hstep, voffA);
;             PG8_WAIT_L(8); PG8_BAR; PG8_WAIT_L(0); PG8_MMA(0, 0, At, B0); PG8_BAR; PG8_SCHED;
;             PG8_LDB(B1, 0, 1); PG8_STAGE(PG8_SB(0, 0), b2, voffB);
;             PG8_BAR; PG8_WAIT_L(0); PG8_MMA(0, 1, At, B1); PG8_BAR;
;             PG8_LDA(At, 0, 1); PG8_STAGE(PG8_SA(0, 0), a2, voffA);
;             PG8_BAR; PG8_WAIT_L(0); PG8_MMA(1, 0, At, B0); PG8_BAR; PG8_SCHED;
.LBB0_186:
	s_add_u32 s18, s16, 0xfffc0080
	s_addc_u32 s19, s17, -1
	s_add_i32 s62, 0, 0x10000
	v_add_u32_e32 v96, s62, v245
	ds_read_b128 v[132:135], v96
	ds_read_b128 v[136:139], v96 offset:1024
	ds_read_b128 v[140:143], v96 offset:2048
	ds_read_b128 v[144:147], v96 offset:3072
	s_cmp_eq_u32 s61, 12
	s_cselect_b32 s21, s9, s19
	s_cselect_b32 s20, s42, s18
	s_cselect_b32 s19, s11, s60
	s_cselect_b32 s18, s43, s59
	v_lshl_add_u64 v[98:99], s[16:17], 0, v[172:173]
	s_add_i32 m0, s48, 0xc000
	ds_read_b128 v[148:151], v246
	ds_read_b128 v[152:155], v246 offset:1024
	ds_read_b128 v[156:159], v246 offset:2048
	ds_read_b128 v[160:163], v246 offset:3072
	ds_read_b128 v[174:177], v246 offset:4096
	ds_read_b128 v[184:187], v246 offset:5120
	ds_read_b128 v[188:191], v246 offset:6144
	ds_read_b128 v[192:195], v246 offset:7168
	global_load_lds_dwordx4 v[98:99], off
	v_lshl_add_u64 v[98:99], s[16:17], 0, v[170:171]
	s_add_i32 m0, s48, 0xe000
	s_nop 0
	global_load_lds_dwordx4 v[98:99], off
	s_waitcnt lgkmcnt(8)
	s_barrier
	s_waitcnt lgkmcnt(0)
	s_setprio 1
	s_waitcnt lgkmcnt(0)
	v_mfma_f32_16x16x32_bf16 v[0:3], v[132:135], v[148:151], v[0:3]
	v_mfma_f32_16x16x32_bf16 v[128:131], v[140:143], v[148:151], v[128:131]
	v_mfma_f32_16x16x32_bf16 v[124:127], v[132:135], v[156:159], v[124:127]
	v_mfma_f32_16x16x32_bf16 v[120:123], v[140:143], v[156:159], v[120:123]
	v_mfma_f32_16x16x32_bf16 v[116:119], v[132:135], v[174:177], v[116:119]
	v_mfma_f32_16x16x32_bf16 v[112:115], v[140:143], v[174:177], v[112:115]
	v_mfma_f32_16x16x32_bf16 v[108:111], v[132:135], v[188:191], v[108:111]
	v_mfma_f32_16x16x32_bf16 v[104:107], v[140:143], v[188:191], v[104:107]
	v_mfma_f32_16x16x32_bf16 v[0:3], v[136:139], v[152:155], v[0:3]
	v_mfma_f32_16x16x32_bf16 v[128:131], v[144:147], v[152:155], v[128:131]
	v_mfma_f32_16x16x32_bf16 v[124:127], v[136:139], v[160:163], v[124:127]
	v_mfma_f32_16x16x32_bf16 v[120:123], v[144:147], v[160:163], v[120:123]
	v_mfma_f32_16x16x32_bf16 v[116:119], v[136:139], v[184:187], v[116:119]
	v_mfma_f32_16x16x32_bf16 v[112:115], v[144:147], v[184:187], v[112:115]
	v_mfma_f32_16x16x32_bf16 v[108:111], v[136:139], v[192:195], v[108:111]
	v_mfma_f32_16x16x32_bf16 v[104:107], v[144:147], v[192:195], v[104:107]
	s_setprio 0
	s_barrier
	s_add_i32 s74, 0, 0x14000
	s_add_i32 s62, s62, s45
	v_add_u32_e32 v96, s74, v245
	v_lshl_add_u64 v[212:213], s[18:19], 0, v[166:167]
	s_mov_b32 m0, s62
	ds_read_b128 v[196:199], v96
	ds_read_b128 v[200:203], v96 offset:1024
	ds_read_b128 v[204:207], v96 offset:2048
	ds_read_b128 v[208:211], v96 offset:3072
	global_load_lds_dwordx4 v[212:213], off
	v_lshl_add_u64 v[214:215], s[18:19], 0, v[164:165]
	s_add_i32 m0, s62, 0x2000
	s_nop 0
	global_load_lds_dwordx4 v[214:215], off
	s_barrier
	s_waitcnt lgkmcnt(0)
	s_setprio 1
	s_waitcnt lgkmcnt(0)
	v_mfma_f32_16x16x32_bf16 v[98:101], v[196:199], v[148:151], v[100:103]
	v_mfma_f32_16x16x32_bf16 v[92:95], v[204:207], v[148:151], v[92:95]
	v_mfma_f32_16x16x32_bf16 v[88:91], v[196:199], v[156:159], v[88:91]
	v_mfma_f32_16x16x32_bf16 v[84:87], v[204:207], v[156:159], v[84:87]
	v_mfma_f32_16x16x32_bf16 v[80:83], v[196:199], v[174:177], v[80:83]
	v_mfma_f32_16x16x32_bf16 v[76:79], v[204:207], v[174:177], v[76:79]
	v_mfma_f32_16x16x32_bf16 v[72:75], v[196:199], v[188:191], v[72:75]
	v_mfma_f32_16x16x32_bf16 v[68:71], v[204:207], v[188:191], v[68:71]
	v_mfma_f32_16x16x32_bf16 v[98:101], v[200:203], v[152:155], v[98:101]
	v_mfma_f32_16x16x32_bf16 v[92:95], v[208:211], v[152:155], v[92:95]
	v_mfma_f32_16x16x32_bf16 v[88:91], v[200:203], v[160:163], v[88:91]
	v_mfma_f32_16x16x32_bf16 v[84:87], v[208:211], v[160:163], v[84:87]
	v_mfma_f32_16x16x32_bf16 v[80:83], v[200:203], v[184:187], v[80:83]
	v_mfma_f32_16x16x32_bf16 v[76:79], v[208:211], v[184:187], v[76:79]
	v_mfma_f32_16x16x32_bf16 v[72:75], v[200:203], v[192:195], v[72:75]
	v_mfma_f32_16x16x32_bf16 v[68:71], v[208:211], v[192:195], v[68:71]
	s_setprio 0
	s_mov_b32 m0, s48
	v_lshl_add_u64 v[216:217], s[20:21], 0, v[166:167]
	s_barrier
	ds_read_b128 v[148:151], v246 offset:16384
	ds_read_b128 v[152:155], v246 offset:17408
	ds_read_b128 v[156:159], v246 offset:18432
	ds_read_b128 v[160:163], v246 offset:19456
	ds_read_b128 v[174:177], v246 offset:20480
	ds_read_b128 v[184:187], v246 offset:21504
	ds_read_b128 v[188:191], v246 offset:22528
	ds_read_b128 v[192:195], v246 offset:23552
	global_load_lds_dwordx4 v[216:217], off
	v_lshl_add_u64 v[218:219], s[20:21], 0, v[164:165]
	s_mov_b32 m0, s49
	s_nop 0
	global_load_lds_dwordx4 v[218:219], off
	s_barrier
	s_waitcnt lgkmcnt(0)
	s_setprio 1
	s_waitcnt lgkmcnt(0)
	v_mfma_f32_16x16x32_bf16 v[64:67], v[132:135], v[148:151], v[64:67]
	v_mfma_f32_16x16x32_bf16 v[60:63], v[140:143], v[148:151], v[60:63]
	v_mfma_f32_16x16x32_bf16 v[56:59], v[132:135], v[156:159], v[56:59]
	v_mfma_f32_16x16x32_bf16 v[52:55], v[140:143], v[156:159], v[52:55]
	v_mfma_f32_16x16x32_bf16 v[48:51], v[132:135], v[174:177], v[48:51]
	v_mfma_f32_16x16x32_bf16 v[44:47], v[140:143], v[174:177], v[44:47]
	v_mfma_f32_16x16x32_bf16 v[40:43], v[132:135], v[188:191], v[40:43]
	v_mfma_f32_16x16x32_bf16 v[36:39], v[140:143], v[188:191], v[36:39]
	v_mfma_f32_16x16x32_bf16 v[64:67], v[136:139], v[152:155], v[64:67]
	v_mfma_f32_16x16x32_bf16 v[60:63], v[144:147], v[152:155], v[60:63]
	v_mfma_f32_16x16x32_bf16 v[56:59], v[136:139], v[160:163], v[56:59]
	v_mfma_f32_16x16x32_bf16 v[52:55], v[144:147], v[160:163], v[52:55]
	v_mfma_f32_16x16x32_bf16 v[48:51], v[136:139], v[184:187], v[48:51]
	v_mfma_f32_16x16x32_bf16 v[44:47], v[144:147], v[184:187], v[44:47]
	v_mfma_f32_16x16x32_bf16 v[40:43], v[136:139], v[192:195], v[40:43]
	v_mfma_f32_16x16x32_bf16 v[36:39], v[144:147], v[192:195], v[36:39]
	s_setprio 0
	s_barrier
; #define PG8_STAGE(bufoff, gbase, voff) do { _Pragma("unroll") for (int _i = 0; _i < 2; ++_i) \
;         __builtin_amdgcn_global_load_lds((const unsigned*)((const char*)(gbase) + (voff)[_i]), (LAS unsigned*)(lds + (bufoff) + ldsw + _i * 8192), 16, 0, 0); } while (0)
; #define PG8_LDA(dst, b, h) do { _Pragma("unroll") for (int m = 0; m < 4; ++m) _Pragma("unroll") for (int k = 0; k < 2; ++k) dst[m][k] = *(const LAS bf16x8*)(lds + PG8_SA(b, h) + aoff + m * 2048 + k * 1024); } while (0)
; #define PG8_LDB(dst, b, h) do { _Pragma("unroll") for (int n = 0; n < 2; ++n) _Pragma("unroll") for (int k = 0; k < 2; ++k) dst[n][k] = *(const LAS bf16x8*)(lds + PG8_SB(b, h) + boff + n * 2048 + k * 1024); } while (0)
; #define PG8_MMA(ai, bj, At, Bt) do { __builtin_amdgcn_s_setprio(1); _Pragma("unroll") for (int m = 0; m < 4; ++m) _Pragma("unroll") for (int n = 0; n < 2; ++n) _Pragma("unroll") for (int k = 0; k < 2; ++k) \
;         acc[ai][bj][m][n] = __builtin_amdgcn_mfma_f32_16x16x32_bf16(Bt[n][k], At[m][k], acc[ai][bj][m][n], 0, 0, 0); __builtin_amdgcn_s_setprio(0); } while (0)
; #define PG8_WAIT_V(n) asm volatile("s_waitcnt vmcnt(" #n ")" ::: "memory")
; #define PG8_WAIT_L(n) asm volatile("s_waitcnt lgkmcnt(" #n ")" ::: "memory")
; #define PG8_BAR __builtin_amdgcn_s_barrier()
; #define PG8_SCHED __builtin_amdgcn_sched_barrier(0)
; template <class Epi, class Sched>
; DI void gemm_phase(LAS unsigned char* lds, const Gemm g, const Sched& S, const Epi& E) {
;     ...
;             PG8_BAR; PG8_WAIT_L(0); PG8_MMA(1, 0, At, B0); PG8_BAR; PG8_SCHED;
;             PG8_STAGE(PG8_SB(0, 1), b2 + hstep, voffB);
;             PG8_WAIT_V(6); PG8_BAR; PG8_MMA(1, 1, At, B1); PG8_BAR;
;             PG8_LDB(B0, 1, 0); PG8_SCHED; PG8_LDA(At, 1, 0); PG8_STAGE(PG8_SA(0, 1), a2 + hstep, voffA);
;             PG8_WAIT_L(8); PG8_BAR; PG8_WAIT_L(0); PG8_MMA(0, 0, At, B0); PG8_BAR; PG8_SCHED;
;             PG8_LDB(B1, 1, 1); PG8_STAGE(PG8_SB(1, 0), b3, voffB);
;             PG8_BAR; PG8_WAIT_L(0); PG8_MMA(0, 1, At, B1); PG8_BAR;
;             PG8_LDA(At, 1, 1); PG8_STAGE(PG8_SA(1, 0), a3, voffA);
;             PG8_BAR; PG8_WAIT_L(0); PG8_MMA(1, 0, At, B0); PG8_BAR; PG8_SCHED;
	s_add_u32 s62, s18, 0x40000
	s_addc_u32 s63, s19, 0
	s_add_i32 s74, s74, s45
	v_lshl_add_u64 v[102:103], s[62:63], 0, v[166:167]
	s_mov_b32 m0, s74
	s_nop 0
	global_load_lds_dwordx4 v[102:103], off
	v_lshl_add_u64 v[102:103], s[62:63], 0, v[164:165]
	s_add_i32 m0, s74, 0x2000
	s_nop 0
	global_load_lds_dwordx4 v[102:103], off
	s_waitcnt vmcnt(6)
	s_barrier
	s_setprio 1
	v_mfma_f32_16x16x32_bf16 v[32:35], v[196:199], v[148:151], v[32:35]
	v_mfma_f32_16x16x32_bf16 v[28:31], v[204:207], v[148:151], v[28:31]
	v_mfma_f32_16x16x32_bf16 v[24:27], v[196:199], v[156:159], v[24:27]
	v_mfma_f32_16x16x32_bf16 v[20:23], v[204:207], v[156:159], v[20:23]
	v_mfma_f32_16x16x32_bf16 v[16:19], v[196:199], v[174:177], v[16:19]
	v_mfma_f32_16x16x32_bf16 v[12:15], v[204:207], v[174:177], v[12:15]
	v_mfma_f32_16x16x32_bf16 v[8:11], v[196:199], v[188:191], v[8:11]
	v_mfma_f32_16x16x32_bf16 v[4:7], v[204:207], v[188:191], v[4:7]
	v_mfma_f32_16x16x32_bf16 v[32:35], v[200:203], v[152:155], v[32:35]
	v_mfma_f32_16x16x32_bf16 v[28:31], v[208:211], v[152:155], v[28:31]
	v_mfma_f32_16x16x32_bf16 v[24:27], v[200:203], v[160:163], v[24:27]
	v_mfma_f32_16x16x32_bf16 v[20:23], v[208:211], v[160:163], v[20:23]
	v_mfma_f32_16x16x32_bf16 v[16:19], v[200:203], v[184:187], v[16:19]
	v_mfma_f32_16x16x32_bf16 v[12:15], v[208:211], v[184:187], v[12:15]
	v_mfma_f32_16x16x32_bf16 v[8:11], v[200:203], v[192:195], v[8:11]
	v_mfma_f32_16x16x32_bf16 v[4:7], v[208:211], v[192:195], v[4:7]
	s_setprio 0
	s_add_i32 s62, 0, 0x18000
	v_add_u32_e32 v96, s62, v245
	s_barrier
	ds_read_b128 v[132:135], v96
	ds_read_b128 v[136:139], v96 offset:1024
	ds_read_b128 v[140:143], v96 offset:2048
	ds_read_b128 v[144:147], v96 offset:3072
	s_add_u32 s20, s20, 0x40000
	s_addc_u32 s21, s21, 0
	s_mov_b32 m0, s50
	v_lshl_add_u64 v[102:103], s[20:21], 0, v[166:167]
	ds_read_b128 v[148:151], v246 offset:32768
	ds_read_b128 v[152:155], v246 offset:33792
	ds_read_b128 v[156:159], v246 offset:34816
	ds_read_b128 v[160:163], v246 offset:35840
	ds_read_b128 v[174:177], v246 offset:36864
	ds_read_b128 v[184:187], v246 offset:37888
	ds_read_b128 v[188:191], v246 offset:38912
	ds_read_b128 v[192:195], v246 offset:39936
	global_load_lds_dwordx4 v[102:103], off
	v_lshl_add_u64 v[102:103], s[20:21], 0, v[164:165]
	s_mov_b32 m0, s51
	s_nop 0
	global_load_lds_dwordx4 v[102:103], off
	s_waitcnt lgkmcnt(8)
	s_barrier
	s_waitcnt lgkmcnt(0)
	s_setprio 1
	s_waitcnt lgkmcnt(0)
	v_mfma_f32_16x16x32_bf16 v[0:3], v[132:135], v[148:151], v[0:3]
	v_mfma_f32_16x16x32_bf16 v[128:131], v[140:143], v[148:151], v[128:131]
	v_mfma_f32_16x16x32_bf16 v[124:127], v[132:135], v[156:159], v[124:127]
	v_mfma_f32_16x16x32_bf16 v[120:123], v[140:143], v[156:159], v[120:123]
	v_mfma_f32_16x16x32_bf16 v[116:119], v[132:135], v[174:177], v[116:119]
	v_mfma_f32_16x16x32_bf16 v[112:115], v[140:143], v[174:177], v[112:115]
	v_mfma_f32_16x16x32_bf16 v[108:111], v[132:135], v[188:191], v[108:111]
	v_mfma_f32_16x16x32_bf16 v[102:105], v[140:143], v[188:191], v[104:107]
	v_mfma_f32_16x16x32_bf16 v[0:3], v[136:139], v[152:155], v[0:3]
	v_mfma_f32_16x16x32_bf16 v[128:131], v[144:147], v[152:155], v[128:131]
	v_mfma_f32_16x16x32_bf16 v[124:127], v[136:139], v[160:163], v[124:127]
	v_mfma_f32_16x16x32_bf16 v[120:123], v[144:147], v[160:163], v[120:123]
	v_mfma_f32_16x16x32_bf16 v[116:119], v[136:139], v[184:187], v[116:119]
	v_mfma_f32_16x16x32_bf16 v[112:115], v[144:147], v[184:187], v[112:115]
	v_mfma_f32_16x16x32_bf16 v[108:111], v[136:139], v[192:195], v[108:111]
	v_mfma_f32_16x16x32_bf16 v[104:107], v[144:147], v[192:195], v[102:105]
	s_setprio 0
	s_barrier
	s_add_i32 s20, 0, 0x1c000
	s_add_i32 s21, s62, s45
	v_add_u32_e32 v96, s20, v245
	v_lshl_add_u64 v[102:103], v[212:213], 0, s[78:79]
	s_mov_b32 m0, s21
	ds_read_b128 v[196:199], v96
	ds_read_b128 v[200:203], v96 offset:1024
	ds_read_b128 v[204:207], v96 offset:2048
	ds_read_b128 v[208:211], v96 offset:3072
	global_load_lds_dwordx4 v[102:103], off
	v_lshl_add_u64 v[102:103], v[214:215], 0, s[78:79]
	s_add_i32 m0, s21, 0x2000
	s_nop 0
	global_load_lds_dwordx4 v[102:103], off
	s_barrier
	s_waitcnt lgkmcnt(0)
	s_setprio 1
	s_waitcnt lgkmcnt(0)
	v_mfma_f32_16x16x32_bf16 v[98:101], v[196:199], v[148:151], v[98:101]
	v_mfma_f32_16x16x32_bf16 v[92:95], v[204:207], v[148:151], v[92:95]
	v_mfma_f32_16x16x32_bf16 v[88:91], v[196:199], v[156:159], v[88:91]
	v_mfma_f32_16x16x32_bf16 v[84:87], v[204:207], v[156:159], v[84:87]
	v_mfma_f32_16x16x32_bf16 v[80:83], v[196:199], v[174:177], v[80:83]
	v_mfma_f32_16x16x32_bf16 v[76:79], v[204:207], v[174:177], v[76:79]
	v_mfma_f32_16x16x32_bf16 v[72:75], v[196:199], v[188:191], v[72:75]
	v_mfma_f32_16x16x32_bf16 v[68:71], v[204:207], v[188:191], v[68:71]
	v_mfma_f32_16x16x32_bf16 v[100:103], v[200:203], v[152:155], v[98:101]
	v_mfma_f32_16x16x32_bf16 v[92:95], v[208:211], v[152:155], v[92:95]
	v_mfma_f32_16x16x32_bf16 v[88:91], v[200:203], v[160:163], v[88:91]
	v_mfma_f32_16x16x32_bf16 v[84:87], v[208:211], v[160:163], v[84:87]
	v_mfma_f32_16x16x32_bf16 v[80:83], v[200:203], v[184:187], v[80:83]
	v_mfma_f32_16x16x32_bf16 v[76:79], v[208:211], v[184:187], v[76:79]
	v_mfma_f32_16x16x32_bf16 v[72:75], v[200:203], v[192:195], v[72:75]
	v_mfma_f32_16x16x32_bf16 v[68:71], v[208:211], v[192:195], v[68:71]
	s_setprio 0
	s_mov_b32 m0, s56
	v_lshl_add_u64 v[98:99], v[216:217], 0, s[78:79]
	s_barrier
	ds_read_b128 v[148:151], v246 offset:49152
	ds_read_b128 v[152:155], v246 offset:50176
	ds_read_b128 v[156:159], v246 offset:51200
	ds_read_b128 v[160:163], v246 offset:52224
	ds_read_b128 v[174:177], v246 offset:53248
	ds_read_b128 v[184:187], v246 offset:54272
	ds_read_b128 v[188:191], v246 offset:55296
	ds_read_b128 v[192:195], v246 offset:56320
	global_load_lds_dwordx4 v[98:99], off
	v_lshl_add_u64 v[98:99], v[218:219], 0, s[78:79]
	s_mov_b32 m0, s57
	s_nop 0
	global_load_lds_dwordx4 v[98:99], off
	s_barrier
; #define PG8_STAGE(bufoff, gbase, voff) do { _Pragma("unroll") for (int _i = 0; _i < 2; ++_i) \
;         __builtin_amdgcn_global_load_lds((const unsigned*)((const char*)(gbase) + (voff)[_i]), (LAS unsigned*)(lds + (bufoff) + ldsw + _i * 8192), 16, 0, 0); } while (0)
; #define PG8_LDA(dst, b, h) do { _Pragma("unroll") for (int m = 0; m < 4; ++m) _Pragma("unroll") for (int k = 0; k < 2; ++k) dst[m][k] = *(const LAS bf16x8*)(lds + PG8_SA(b, h) + aoff + m * 2048 + k * 1024); } while (0)
; #define PG8_MMA(ai, bj, At, Bt) do { __builtin_amdgcn_s_setprio(1); _Pragma("unroll") for (int m = 0; m < 4; ++m) _Pragma("unroll") for (int n = 0; n < 2; ++n) _Pragma("unroll") for (int k = 0; k < 2; ++k) \
;         acc[ai][bj][m][n] = __builtin_amdgcn_mfma_f32_16x16x32_bf16(Bt[n][k], At[m][k], acc[ai][bj][m][n], 0, 0, 0); __builtin_amdgcn_s_setprio(0); } while (0)
; #define PG8_WAIT_V(n) asm volatile("s_waitcnt vmcnt(" #n ")" ::: "memory")
; #define PG8_WAIT_L(n) asm volatile("s_waitcnt lgkmcnt(" #n ")" ::: "memory")
; #define PG8_BAR __builtin_amdgcn_s_barrier()
; #define PG8_SCHED __builtin_amdgcn_sched_barrier(0)
; template <class Epi, class Sched>
; DI void gemm_phase(LAS unsigned char* lds, const Gemm g, const Sched& S, const Epi& E) {
;     ...
;             PG8_BAR; PG8_WAIT_L(0); PG8_MMA(0, 1, At, B1); PG8_BAR;
;             PG8_LDA(At, 1, 1); PG8_STAGE(PG8_SA(1, 0), a3, voffA);
;             PG8_BAR; PG8_WAIT_L(0); PG8_MMA(1, 0, At, B0); PG8_BAR; PG8_SCHED;
;             PG8_STAGE(PG8_SB(1, 1), b3 + hstep, voffB);
;             PG8_WAIT_V(6); PG8_BAR; PG8_MMA(1, 1, At, B1); PG8_BAR;
	s_waitcnt lgkmcnt(0)
	s_setprio 1
	s_waitcnt lgkmcnt(0)
	v_mfma_f32_16x16x32_bf16 v[64:67], v[132:135], v[148:151], v[64:67]
	v_mfma_f32_16x16x32_bf16 v[60:63], v[140:143], v[148:151], v[60:63]
	v_mfma_f32_16x16x32_bf16 v[56:59], v[132:135], v[156:159], v[56:59]
	v_mfma_f32_16x16x32_bf16 v[52:55], v[140:143], v[156:159], v[52:55]
	v_mfma_f32_16x16x32_bf16 v[48:51], v[132:135], v[174:177], v[48:51]
	v_mfma_f32_16x16x32_bf16 v[44:47], v[140:143], v[174:177], v[44:47]
	v_mfma_f32_16x16x32_bf16 v[40:43], v[132:135], v[188:191], v[40:43]
	v_mfma_f32_16x16x32_bf16 v[36:39], v[140:143], v[188:191], v[36:39]
	v_mfma_f32_16x16x32_bf16 v[64:67], v[136:139], v[152:155], v[64:67]
	v_mfma_f32_16x16x32_bf16 v[60:63], v[144:147], v[152:155], v[60:63]
	v_mfma_f32_16x16x32_bf16 v[56:59], v[136:139], v[160:163], v[56:59]
	v_mfma_f32_16x16x32_bf16 v[52:55], v[144:147], v[160:163], v[52:55]
	v_mfma_f32_16x16x32_bf16 v[48:51], v[136:139], v[184:187], v[48:51]
	v_mfma_f32_16x16x32_bf16 v[44:47], v[144:147], v[184:187], v[44:47]
	v_mfma_f32_16x16x32_bf16 v[40:43], v[136:139], v[192:195], v[40:43]
	v_mfma_f32_16x16x32_bf16 v[36:39], v[144:147], v[192:195], v[36:39]
	s_setprio 0
	s_barrier
	s_add_u32 s18, s18, 0x40080
	s_addc_u32 s19, s19, 0
	s_add_i32 s20, s20, s45
	v_lshl_add_u64 v[98:99], s[18:19], 0, v[166:167]
	s_mov_b32 m0, s20
	s_nop 0
	global_load_lds_dwordx4 v[98:99], off
	v_lshl_add_u64 v[98:99], s[18:19], 0, v[164:165]
	s_add_i32 m0, s20, 0x2000
	s_nop 0
	global_load_lds_dwordx4 v[98:99], off
	s_waitcnt vmcnt(6)
	s_barrier
	s_setprio 1
	v_mfma_f32_16x16x32_bf16 v[32:35], v[196:199], v[148:151], v[32:35]
	v_mfma_f32_16x16x32_bf16 v[28:31], v[204:207], v[148:151], v[28:31]
	v_mfma_f32_16x16x32_bf16 v[24:27], v[196:199], v[156:159], v[24:27]
	v_mfma_f32_16x16x32_bf16 v[20:23], v[204:207], v[156:159], v[20:23]
	v_mfma_f32_16x16x32_bf16 v[16:19], v[196:199], v[174:177], v[16:19]
	v_mfma_f32_16x16x32_bf16 v[12:15], v[204:207], v[174:177], v[12:15]
	v_mfma_f32_16x16x32_bf16 v[8:11], v[196:199], v[188:191], v[8:11]
	v_mfma_f32_16x16x32_bf16 v[4:7], v[204:207], v[188:191], v[4:7]
	v_mfma_f32_16x16x32_bf16 v[32:35], v[200:203], v[152:155], v[32:35]
	v_mfma_f32_16x16x32_bf16 v[28:31], v[208:211], v[152:155], v[28:31]
	v_mfma_f32_16x16x32_bf16 v[24:27], v[200:203], v[160:163], v[24:27]
	v_mfma_f32_16x16x32_bf16 v[20:23], v[208:211], v[160:163], v[20:23]
	v_mfma_f32_16x16x32_bf16 v[16:19], v[200:203], v[184:187], v[16:19]
	v_mfma_f32_16x16x32_bf16 v[12:15], v[208:211], v[184:187], v[12:15]
	v_mfma_f32_16x16x32_bf16 v[8:11], v[200:203], v[192:195], v[8:11]
	v_mfma_f32_16x16x32_bf16 v[4:7], v[208:211], v[192:195], v[4:7]
	s_setprio 0
	s_add_i32 s61, s61, 2
	s_add_u32 s59, s59, 0x100
	s_addc_u32 s60, s60, 0
	s_add_u32 s16, s16, 0x100
	s_addc_u32 s17, s17, 0
	s_cmp_gt_u32 s61, 13
	s_barrier
	s_cbranch_scc0 .LBB0_186
; DI unsigned pk2(float lo, float hi) { f32x2 v = {lo, hi}; return __builtin_bit_cast(unsigned, __builtin_convertvector(v, bf16x2n)); }
; DI float bflo(unsigned u) { return __uint_as_float(u << 16); }
;     DI bool operator()(f32x4 (&acc)[2][2][4][2], const pg8::Unit& u, int wr, int wc, int fr, int fq) const {
;     ...
;             for (int n = 0; n < 2; ++n) { bc[bj][n] = *(const f32x4*)(mb + nb * D + col0 + bj * 128 + n * 16); bn[bj][n] = *(const f32x4*)(mb + nn * D + col0 + bj * 128 + n * 16); }
; #pragma unroll
;         for (int ai = 0; ai < 2; ++ai)
; #pragma unroll
;             for (int mp = 0; mp < 2; ++mp) {
;                 u32x2 gc[2][2][2], gn[2][2][2];
; #pragma unroll
;                 for (int mi = 0; mi < 2; ++mi) { const int row = row0 + ai * 128 + (2 * mp + mi) * 16;
; #pragma unroll
;                     for (int bj = 0; bj < 2; ++bj)
; #pragma unroll
;                         for (int n = 0; n < 2; ++n) { const int col = col0 + bj * 128 + n * 16;
;                             gc[mi][bj][n] = *(const u32x2*)(proj + PIDX(row, C_MERGE + nb * D + col));
;                             gn[mi][bj][n] = *(const u32x2*)(proj + PIDX(row, C_MERGE + nn * D + col)); } }
; #pragma unroll
;                 for (int mi = 0; mi < 2; ++mi) { const int m = 2 * mp + mi; const int row = row0 + ai * 128 + m * 16;
; #pragma unroll
;                     for (int bj = 0; bj < 2; ++bj)
; #pragma unroll
;                         for (int n = 0; n < 2; ++n) { const int col = col0 + bj * 128 + n * 16;
;                             const u32x2 c2 = gc[mi][bj][n], n2 = gn[mi][bj][n]; const f32x4 cb = bc[bj][n], nbv = bn[bj][n];
;                             const float xc[4] = {bflo(c2[0]) + cb[0], bfhi(c2[0]) + cb[1], bflo(c2[1]) + cb[2], bfhi(c2[1]) + cb[3]};
;                             const float xn[4] = {bflo(n2[0]) + nbv[0], bfhi(n2[0]) + nbv[1], bflo(n2[1]) + nbv[2], bfhi(n2[1]) + nbv[3]};
;                             if (nb < 2) {
; #pragma unroll
;                                 for (int e = 0; e < 4; ++e) acc[ai][bj][m][n][e] *= (1.0f + __expf(-xn[e])) * __builtin_amdgcn_rcpf(1.0f + __expf(-xc[e]));
;                             } else {
;                                 const f32x4 a = acc[ai][bj][m][n];
;                                 u32x2 o = {pk2(a[0] * sigm_f(xc[0]), a[1] * sigm_f(xc[1])), pk2(a[2] * sigm_f(xc[2]), a[3] * sigm_f(xc[3]))};
	s_ashr_i32 s9, s23, 5
	s_cmp_gt_i32 s9, 1
	s_cselect_b64 s[20:21], -1, 0
	s_cmp_lt_i32 s9, 2
	s_cselect_b64 s[16:17], -1, 0
	s_cmp_lg_u64 s[16:17], 0
	s_addc_u32 s11, s9, 0
	s_lshl_b32 s16, s23, 8
	s_and_b32 s59, s16, 0x1f00
	s_lshl_b32 s16, s22, 8
	s_and_b32 s60, s16, 0x700
	s_lshl_b32 s16, s9, 11
	s_ashr_i32 s17, s16, 31
	s_lshl_b64 s[18:19], s[16:17], 2
	s_add_u32 s18, s54, s18
	s_addc_u32 s19, s55, s19
	s_lshl_b32 s22, s11, 11
	s_ashr_i32 s23, s22, 31
	s_lshl_b64 s[42:43], s[22:23], 2
	s_add_u32 s42, s54, s42
	s_addc_u32 s43, s55, s43
	s_or_b32 s9, s16, s60
	s_addk_i32 s9, 0x4800
	v_or_b32_e32 v236, s60, v168
	s_ashr_i32 s16, s9, 8
	s_or_b32 s9, s22, s60
	v_lshlrev_b32_e32 v96, 2, v236
	s_addk_i32 s9, 0x4800
	global_load_dwordx4 v[160:163], v96, s[18:19]
	global_load_dwordx4 v[152:155], v96, s[18:19] offset:64
	global_load_dwordx4 v[156:159], v96, s[42:43]
	global_load_dwordx4 v[148:151], v96, s[42:43] offset:64
	global_load_dwordx4 v[144:147], v96, s[18:19] offset:512
	global_load_dwordx4 v[136:139], v96, s[18:19] offset:576
	global_load_dwordx4 v[140:143], v96, s[42:43] offset:512
	global_load_dwordx4 v[132:135], v96, s[42:43] offset:576
	s_ashr_i32 s18, s9, 8
	s_ashr_i32 s17, s16, 31
	s_ashr_i32 s19, s18, 31
	s_lshl_b64 s[16:17], s[16:17], 22
	s_lshl_b64 s[18:19], s[18:19], 22
	v_add_u32_e32 v174, s59, v169
	s_add_u32 s16, s52, s16
	s_addc_u32 s17, s53, s17
	v_ashrrev_i32_e32 v175, 31, v174
	s_movk_i32 s9, 0x7c
	s_add_u32 s18, s52, s18
	v_lshlrev_b64 v[98:99], 9, v[174:175]
	v_bitop3_b32 v176, v168, s9, 16 bitop3:0xc8
	v_or_b32_e32 v202, 16, v174
	s_addc_u32 s19, s53, s19
	v_lshl_add_u64 v[188:189], s[16:17], 0, v[98:99]
	v_lshlrev_b32_e32 v96, 1, v168
	v_lshlrev_b32_e32 v184, 1, v176
	v_mov_b32_e32 v185, v97
	v_ashrrev_i32_e32 v203, 31, v202
	v_lshl_add_u64 v[220:221], s[18:19], 0, v[98:99]
	v_lshl_add_u64 v[98:99], v[188:189], 0, v[96:97]
	v_lshl_add_u64 v[186:187], v[188:189], 0, v[184:185]
	v_lshlrev_b32_e32 v176, 1, v247
	v_mov_b32_e32 v177, v97
	v_lshlrev_b64 v[194:195], 9, v[202:203]
	v_lshl_add_u64 v[190:191], v[220:221], 0, v[184:185]
	v_lshl_add_u64 v[192:193], v[188:189], 0, v[176:177]
	global_load_dwordx2 v[98:99], v[98:99], off
	s_nop 0
	global_load_dwordx2 v[218:219], v[186:187], off
	global_load_dwordx2 v[216:217], v[190:191], off
	global_load_dwordx2 v[214:215], v[192:193], off
	v_lshlrev_b32_e32 v186, 1, v248
	v_mov_b32_e32 v187, v97
	v_lshl_add_u64 v[208:209], s[16:17], 0, v[194:195]
	v_lshl_add_u64 v[190:191], v[220:221], 0, v[176:177]
	v_lshl_add_u64 v[188:189], v[188:189], 0, v[186:187]
	v_lshl_add_u64 v[234:235], s[18:19], 0, v[194:195]
	v_lshl_add_u64 v[194:195], v[208:209], 0, v[96:97]
	v_lshl_add_u64 v[192:193], v[220:221], 0, v[186:187]
	global_load_dwordx2 v[212:213], v[190:191], off
	global_load_dwordx2 v[210:211], v[188:189], off
	global_load_dwordx2 v[206:207], v[192:193], off
	global_load_dwordx2 v[204:205], v[194:195], off
	v_lshl_add_u64 v[188:189], v[234:235], 0, v[96:97]
	v_lshl_add_u64 v[190:191], v[208:209], 0, v[184:185]
	v_lshl_add_u64 v[194:195], v[208:209], 0, v[176:177]
	v_lshl_add_u64 v[192:193], v[234:235], 0, v[184:185]
	global_load_dwordx2 v[200:201], v[188:189], off
	global_load_dwordx2 v[198:199], v[190:191], off
	global_load_dwordx2 v[196:197], v[192:193], off
	s_nop 0
	global_load_dwordx2 v[194:195], v[194:195], off
	v_lshl_add_u64 v[188:189], v[234:235], 0, v[176:177]
	v_lshl_add_u64 v[190:191], v[208:209], 0, v[186:187]
	v_lshl_add_u64 v[208:209], v[234:235], 0, v[186:187]
	global_load_dwordx2 v[192:193], v[188:189], off
	s_nop 0
	global_load_dwordx2 v[190:191], v[190:191], off
	s_nop 0
	global_load_dwordx2 v[188:189], v[208:209], off
	v_lshlrev_b64 v[208:209], 12, v[174:175]
	s_mov_b64 s[22:23], -1
	s_and_b64 vcc, exec, s[20:21]
	v_lshl_add_u64 v[208:209], s[6:7], 0, v[208:209]
	v_lshl_add_u64 v[220:221], v[220:221], 0, v[96:97]
	global_load_dwordx2 v[220:221], v[220:221], off
	s_waitcnt vmcnt(0)
	v_lshlrev_b32_e32 v175, 16, v98
	v_and_b32_e32 v98, 0xffff0000, v98
	v_lshlrev_b32_e32 v177, 16, v99
	v_and_b32_e32 v99, 0xffff0000, v99
	v_add_f32_e32 v175, v160, v175
	v_add_f32_e32 v98, v161, v98
	v_add_f32_e32 v177, v162, v177
	v_add_f32_e32 v99, v163, v99
	v_mul_f32_e32 v175, 0xbfb8aa3b, v175
	v_mul_f32_e32 v98, 0xbfb8aa3b, v98
	v_mul_f32_e32 v177, 0xbfb8aa3b, v177
	v_mul_f32_e32 v99, 0xbfb8aa3b, v99
	v_exp_f32_e32 v187, v175
	v_exp_f32_e32 v185, v98
	v_exp_f32_e32 v177, v177
	v_exp_f32_e32 v175, v99
	v_lshlrev_b32_e32 v98, 1, v236
	s_cbranch_vccz .LBB0_189
	v_add_f32_e32 v99, 1.0, v187
	v_rcp_f32_e32 v234, v99
	v_add_f32_e32 v99, 1.0, v185
	v_rcp_f32_e32 v235, v99
	v_add_f32_e32 v99, 1.0, v177
	v_rcp_f32_e32 v236, v99
	v_add_f32_e32 v99, 1.0, v175
	v_rcp_f32_e32 v237, v99
	v_pk_mul_f32 v[234:235], v[0:1], v[234:235]
	v_mov_b32_e32 v99, v97
	v_cvt_pk_bf16_f32 v234, v234, v235
	v_pk_mul_f32 v[236:237], v[2:3], v[236:237]
	s_mov_b64 s[22:23], 0
	v_cvt_pk_bf16_f32 v235, v236, v237
	v_lshl_add_u64 v[236:237], v[208:209], 0, v[98:99]
	global_store_dwordx2 v[236:237], v[234:235], off
.LBB0_189:
	s_andn2_b64 vcc, exec, s[22:23]
	v_readlane_b32 s61, v255, 33
	s_mov_b32 s60, 0x78a5c000
	s_cbranch_vccnz .LBB0_191
	v_add_f32_e32 v99, 1.0, v187
	v_add_f32_e32 v185, 1.0, v185
	v_rcp_f32_e32 v234, v99
	v_rcp_f32_e32 v235, v185
	v_add_f32_e32 v177, 1.0, v177
	v_add_f32_e32 v175, 1.0, v175
	v_rcp_f32_e32 v238, v177
	v_rcp_f32_e32 v239, v175
	v_and_b32_e32 v99, 0xffff0000, v221
	v_lshlrev_b32_e32 v185, 16, v221
	v_and_b32_e32 v187, 0xffff0000, v220
	v_lshlrev_b32_e32 v220, 16, v220
	v_add_f32_e32 v99, v159, v99
	v_add_f32_e32 v185, v158, v185
	v_add_f32_e32 v187, v157, v187
	v_add_f32_e32 v220, v156, v220
	v_mul_f32_e32 v220, 0xbfb8aa3b, v220
	v_mul_f32_e32 v187, 0xbfb8aa3b, v187
	v_mul_f32_e32 v185, 0xbfb8aa3b, v185
	v_mul_f32_e32 v99, 0xbfb8aa3b, v99
	v_exp_f32_e32 v220, v220
	v_exp_f32_e32 v236, v185
	v_exp_f32_e32 v237, v99
	v_exp_f32_e32 v221, v187
	v_pk_add_f32 v[236:237], v[236:237], 1.0 op_sel_hi:[1,0]
	v_pk_add_f32 v[220:221], v[220:221], 1.0 op_sel_hi:[1,0]
	s_nop 0
	v_pk_mul_f32 v[220:221], v[234:235], v[220:221]
	v_pk_mul_f32 v[234:235], v[238:239], v[236:237]
	v_pk_mul_f32 v[0:1], v[0:1], v[220:221]
	v_pk_mul_f32 v[2:3], v[2:3], v[234:235]

; DI unsigned pk2(float lo, float hi) { f32x2 v = {lo, hi}; return __builtin_bit_cast(unsigned, __builtin_convertvector(v, bf16x2n)); }
; DI float bflo(unsigned u) { return __uint_as_float(u << 16); }
; DI float bfhi(unsigned u) { return __uint_as_float(u & 0xffff0000u); }
; DI float sigm_f(float x) { return __builtin_amdgcn_rcpf(1.0f + __expf(-x)); }
; DI size_t PIDX(int row, int col) { return ((size_t)(col >> 8) * S + row) * 256 + (col & 255); }
;     DI bool operator()(f32x4 (&acc)[2][2][4][2], const pg8::Unit& u, int wr, int wc, int fr, int fq) const {
;     ...
;                 for (int mi = 0; mi < 2; ++mi) { const int row = row0 + ai * 128 + (2 * mp + mi) * 16;
; #pragma unroll
;                     for (int bj = 0; bj < 2; ++bj)
; #pragma unroll
;                         for (int n = 0; n < 2; ++n) { const int col = col0 + bj * 128 + n * 16;
;                             gc[mi][bj][n] = *(const u32x2*)(proj + PIDX(row, C_MERGE + nb * D + col));
;                             gn[mi][bj][n] = *(const u32x2*)(proj + PIDX(row, C_MERGE + nn * D + col)); } }
; #pragma unroll
;                 for (int mi = 0; mi < 2; ++mi) { const int m = 2 * mp + mi; const int row = row0 + ai * 128 + m * 16;
; #pragma unroll
;                     for (int bj = 0; bj < 2; ++bj)
; #pragma unroll
;                         for (int n = 0; n < 2; ++n) { const int col = col0 + bj * 128 + n * 16;
;                             const u32x2 c2 = gc[mi][bj][n], n2 = gn[mi][bj][n]; const f32x4 cb = bc[bj][n], nbv = bn[bj][n];
;                             const float xc[4] = {bflo(c2[0]) + cb[0], bfhi(c2[0]) + cb[1], bflo(c2[1]) + cb[2], bfhi(c2[1]) + cb[3]};
;                             const float xn[4] = {bflo(n2[0]) + nbv[0], bfhi(n2[0]) + nbv[1], bflo(n2[1]) + nbv[2], bfhi(n2[1]) + nbv[3]};
;                             if (nb < 2) {
; #pragma unroll
;                                 for (int e = 0; e < 4; ++e) acc[ai][bj][m][n][e] *= (1.0f + __expf(-xn[e])) * __builtin_amdgcn_rcpf(1.0f + __expf(-xc[e]));
;                             } else {
;                                 const f32x4 a = acc[ai][bj][m][n];
;                                 u32x2 o = {pk2(a[0] * sigm_f(xc[0]), a[1] * sigm_f(xc[1])), pk2(a[2] * sigm_f(xc[2]), a[3] * sigm_f(xc[3]))};
.LBB0_219:
	v_or_b32_e32 v208, 32, v174
	v_ashrrev_i32_e32 v209, 31, v208
	v_lshlrev_b64 v[188:189], 9, v[208:209]
	v_lshl_add_u64 v[190:191], s[16:17], 0, v[188:189]
	v_lshl_add_u64 v[220:221], s[18:19], 0, v[188:189]
	v_mov_b32_e32 v185, v97
	v_or_b32_e32 v202, 48, v174
	v_lshl_add_u64 v[188:189], v[190:191], 0, v[96:97]
	v_lshl_add_u64 v[194:195], v[220:221], 0, v[184:185]
	v_mov_b32_e32 v177, v97
	v_ashrrev_i32_e32 v203, 31, v202
	v_lshl_add_u64 v[192:193], v[190:191], 0, v[184:185]
	v_lshl_add_u64 v[196:197], v[190:191], 0, v[176:177]
	global_load_dwordx2 v[234:235], v[188:189], off
	global_load_dwordx2 v[218:219], v[192:193], off
	global_load_dwordx2 v[216:217], v[194:195], off
	global_load_dwordx2 v[214:215], v[196:197], off
	v_lshlrev_b64 v[194:195], 9, v[202:203]
	v_mov_b32_e32 v187, v97
	v_lshl_add_u64 v[236:237], s[16:17], 0, v[194:195]
	v_lshl_add_u64 v[188:189], v[220:221], 0, v[176:177]
	v_lshl_add_u64 v[190:191], v[190:191], 0, v[186:187]
	v_lshl_add_u64 v[238:239], s[18:19], 0, v[194:195]
	v_lshl_add_u64 v[194:195], v[236:237], 0, v[96:97]
	v_lshl_add_u64 v[192:193], v[220:221], 0, v[186:187]
	global_load_dwordx2 v[212:213], v[188:189], off
	global_load_dwordx2 v[210:211], v[190:191], off
	global_load_dwordx2 v[206:207], v[192:193], off
	global_load_dwordx2 v[204:205], v[194:195], off
	v_lshl_add_u64 v[188:189], v[238:239], 0, v[96:97]
	v_lshl_add_u64 v[190:191], v[236:237], 0, v[184:185]
	v_lshl_add_u64 v[194:195], v[236:237], 0, v[176:177]
	v_lshl_add_u64 v[192:193], v[238:239], 0, v[184:185]
	global_load_dwordx2 v[200:201], v[188:189], off
	global_load_dwordx2 v[198:199], v[190:191], off
	global_load_dwordx2 v[196:197], v[192:193], off
	s_nop 0
	global_load_dwordx2 v[194:195], v[194:195], off
	v_lshl_add_u64 v[188:189], v[238:239], 0, v[176:177]
	v_lshl_add_u64 v[190:191], v[236:237], 0, v[186:187]
	v_lshl_add_u64 v[236:237], v[238:239], 0, v[186:187]
	global_load_dwordx2 v[192:193], v[188:189], off
	s_nop 0
	global_load_dwordx2 v[190:191], v[190:191], off
	s_nop 0
	global_load_dwordx2 v[188:189], v[236:237], off
	v_lshlrev_b64 v[208:209], 12, v[208:209]
	s_mov_b64 s[20:21], -1
	s_and_b64 vcc, exec, s[42:43]
	v_lshl_add_u64 v[208:209], s[6:7], 0, v[208:209]
	v_lshl_add_u64 v[220:221], v[220:221], 0, v[96:97]
	global_load_dwordx2 v[220:221], v[220:221], off
	s_waitcnt vmcnt(0)
	v_lshlrev_b32_e32 v99, 16, v234
	v_and_b32_e32 v175, 0xffff0000, v234
	v_lshlrev_b32_e32 v177, 16, v235
	v_and_b32_e32 v185, 0xffff0000, v235
	v_add_f32_e32 v99, v160, v99
	v_add_f32_e32 v175, v161, v175
	v_add_f32_e32 v177, v162, v177
	v_add_f32_e32 v185, v163, v185
	v_mul_f32_e32 v99, 0xbfb8aa3b, v99
	v_mul_f32_e32 v175, 0xbfb8aa3b, v175
	v_mul_f32_e32 v177, 0xbfb8aa3b, v177
	v_mul_f32_e32 v234, 0xbfb8aa3b, v185
	v_exp_f32_e32 v187, v99
	v_exp_f32_e32 v185, v175
	v_exp_f32_e32 v177, v177
	v_exp_f32_e32 v175, v234
	s_cbranch_vccnz .LBB0_221
	v_add_f32_e32 v99, 1.0, v187
	v_rcp_f32_e32 v234, v99
	v_add_f32_e32 v99, 1.0, v185
	v_rcp_f32_e32 v235, v99
	v_add_f32_e32 v99, 1.0, v177
	v_rcp_f32_e32 v236, v99
	v_add_f32_e32 v99, 1.0, v175
	v_rcp_f32_e32 v237, v99
	v_pk_mul_f32 v[234:235], v[116:117], v[234:235]
	v_mov_b32_e32 v99, v97
	v_cvt_pk_bf16_f32 v234, v234, v235
	v_pk_mul_f32 v[236:237], v[118:119], v[236:237]
	s_mov_b64 s[20:21], 0
	v_cvt_pk_bf16_f32 v235, v236, v237
	v_lshl_add_u64 v[236:237], v[208:209], 0, v[98:99]
	global_store_dwordx2 v[236:237], v[234:235], off
.LBB0_221:
	s_andn2_b64 vcc, exec, s[20:21]
	s_cbranch_vccnz .LBB0_223
	v_add_f32_e32 v99, 1.0, v187
	v_add_f32_e32 v185, 1.0, v185
	v_rcp_f32_e32 v234, v99
	v_rcp_f32_e32 v235, v185
	v_add_f32_e32 v177, 1.0, v177
	v_add_f32_e32 v175, 1.0, v175
	v_rcp_f32_e32 v238, v177
	v_rcp_f32_e32 v239, v175
	v_and_b32_e32 v99, 0xffff0000, v221
	v_lshlrev_b32_e32 v185, 16, v221
	v_and_b32_e32 v187, 0xffff0000, v220
	v_lshlrev_b32_e32 v220, 16, v220
	v_add_f32_e32 v99, v159, v99
	v_add_f32_e32 v185, v158, v185
	v_add_f32_e32 v187, v157, v187
	v_add_f32_e32 v220, v156, v220
	v_mul_f32_e32 v220, 0xbfb8aa3b, v220
	v_mul_f32_e32 v187, 0xbfb8aa3b, v187
	v_mul_f32_e32 v185, 0xbfb8aa3b, v185
	v_mul_f32_e32 v99, 0xbfb8aa3b, v99
	v_exp_f32_e32 v220, v220
	v_exp_f32_e32 v236, v185
	v_exp_f32_e32 v237, v99
	v_exp_f32_e32 v221, v187
	v_pk_add_f32 v[236:237], v[236:237], 1.0 op_sel_hi:[1,0]
	v_pk_add_f32 v[220:221], v[220:221], 1.0 op_sel_hi:[1,0]
	s_nop 0
	v_pk_mul_f32 v[220:221], v[234:235], v[220:221]
	v_pk_mul_f32 v[234:235], v[238:239], v[236:237]
	v_pk_mul_f32 v[116:117], v[116:117], v[220:221]
	v_pk_mul_f32 v[118:119], v[118:119], v[234:235]

; DI unsigned pk2(float lo, float hi) { f32x2 v = {lo, hi}; return __builtin_bit_cast(unsigned, __builtin_convertvector(v, bf16x2n)); }
; DI float bflo(unsigned u) { return __uint_as_float(u << 16); }
; DI float bfhi(unsigned u) { return __uint_as_float(u & 0xffff0000u); }
; DI float sigm_f(float x) { return __builtin_amdgcn_rcpf(1.0f + __expf(-x)); }
; DI size_t PIDX(int row, int col) { return ((size_t)(col >> 8) * S + row) * 256 + (col & 255); }
;     DI bool operator()(f32x4 (&acc)[2][2][4][2], const pg8::Unit& u, int wr, int wc, int fr, int fq) const {
;     ...
;                 for (int mi = 0; mi < 2; ++mi) { const int row = row0 + ai * 128 + (2 * mp + mi) * 16;
; #pragma unroll
;                     for (int bj = 0; bj < 2; ++bj)
; #pragma unroll
;                         for (int n = 0; n < 2; ++n) { const int col = col0 + bj * 128 + n * 16;
;                             gc[mi][bj][n] = *(const u32x2*)(proj + PIDX(row, C_MERGE + nb * D + col));
;                             gn[mi][bj][n] = *(const u32x2*)(proj + PIDX(row, C_MERGE + nn * D + col)); } }
; #pragma unroll
;                 for (int mi = 0; mi < 2; ++mi) { const int m = 2 * mp + mi; const int row = row0 + ai * 128 + m * 16;
; #pragma unroll
;                     for (int bj = 0; bj < 2; ++bj)
; #pragma unroll
;                         for (int n = 0; n < 2; ++n) { const int col = col0 + bj * 128 + n * 16;
;                             const u32x2 c2 = gc[mi][bj][n], n2 = gn[mi][bj][n]; const f32x4 cb = bc[bj][n], nbv = bn[bj][n];
;                             const float xc[4] = {bflo(c2[0]) + cb[0], bfhi(c2[0]) + cb[1], bflo(c2[1]) + cb[2], bfhi(c2[1]) + cb[3]};
;                             const float xn[4] = {bflo(n2[0]) + nbv[0], bfhi(n2[0]) + nbv[1], bflo(n2[1]) + nbv[2], bfhi(n2[1]) + nbv[3]};
;                             if (nb < 2) {
; #pragma unroll
;                                 for (int e = 0; e < 4; ++e) acc[ai][bj][m][n][e] *= (1.0f + __expf(-xn[e])) * __builtin_amdgcn_rcpf(1.0f + __expf(-xc[e]));
;                             } else {
;                                 const f32x4 a = acc[ai][bj][m][n];
;                                 u32x2 o = {pk2(a[0] * sigm_f(xc[0]), a[1] * sigm_f(xc[1])), pk2(a[2] * sigm_f(xc[2]), a[3] * sigm_f(xc[3]))};
.LBB0_251:
	v_add_u32_e32 v208, 0x80, v174
	v_ashrrev_i32_e32 v209, 31, v208
	v_lshlrev_b64 v[188:189], 9, v[208:209]
	v_lshl_add_u64 v[190:191], s[16:17], 0, v[188:189]
	v_lshl_add_u64 v[220:221], s[18:19], 0, v[188:189]
	v_mov_b32_e32 v185, v97
	v_add_u32_e32 v202, 0x90, v174
	v_lshl_add_u64 v[188:189], v[190:191], 0, v[96:97]
	v_lshl_add_u64 v[194:195], v[220:221], 0, v[184:185]
	v_mov_b32_e32 v177, v97
	v_ashrrev_i32_e32 v203, 31, v202
	v_lshl_add_u64 v[192:193], v[190:191], 0, v[184:185]
	v_lshl_add_u64 v[196:197], v[190:191], 0, v[176:177]
	global_load_dwordx2 v[234:235], v[188:189], off
	global_load_dwordx2 v[218:219], v[192:193], off
	global_load_dwordx2 v[216:217], v[194:195], off
	global_load_dwordx2 v[214:215], v[196:197], off
	v_lshlrev_b64 v[194:195], 9, v[202:203]
	v_mov_b32_e32 v187, v97
	v_lshl_add_u64 v[236:237], s[16:17], 0, v[194:195]
	v_lshl_add_u64 v[188:189], v[220:221], 0, v[176:177]
	v_lshl_add_u64 v[190:191], v[190:191], 0, v[186:187]
	v_lshl_add_u64 v[238:239], s[18:19], 0, v[194:195]
	v_lshl_add_u64 v[194:195], v[236:237], 0, v[96:97]
	v_lshl_add_u64 v[192:193], v[220:221], 0, v[186:187]
	global_load_dwordx2 v[212:213], v[188:189], off
	global_load_dwordx2 v[210:211], v[190:191], off
	global_load_dwordx2 v[206:207], v[192:193], off
	global_load_dwordx2 v[204:205], v[194:195], off
	v_lshl_add_u64 v[188:189], v[238:239], 0, v[96:97]
	v_lshl_add_u64 v[190:191], v[236:237], 0, v[184:185]
	v_lshl_add_u64 v[194:195], v[236:237], 0, v[176:177]
	v_lshl_add_u64 v[192:193], v[238:239], 0, v[184:185]
	global_load_dwordx2 v[200:201], v[188:189], off
	global_load_dwordx2 v[198:199], v[190:191], off
	global_load_dwordx2 v[196:197], v[192:193], off
	s_nop 0
	global_load_dwordx2 v[194:195], v[194:195], off
	v_lshl_add_u64 v[188:189], v[238:239], 0, v[176:177]
	v_lshl_add_u64 v[190:191], v[236:237], 0, v[186:187]
	v_lshl_add_u64 v[236:237], v[238:239], 0, v[186:187]
	global_load_dwordx2 v[192:193], v[188:189], off
	s_nop 0
	global_load_dwordx2 v[190:191], v[190:191], off
	s_nop 0
	global_load_dwordx2 v[188:189], v[236:237], off
	v_lshlrev_b64 v[208:209], 12, v[208:209]
	s_mov_b64 s[20:21], -1
	s_and_b64 vcc, exec, s[42:43]
	v_lshl_add_u64 v[208:209], s[6:7], 0, v[208:209]
	v_lshl_add_u64 v[220:221], v[220:221], 0, v[96:97]
	global_load_dwordx2 v[220:221], v[220:221], off
	s_waitcnt vmcnt(0)
	v_lshlrev_b32_e32 v99, 16, v234
	v_and_b32_e32 v175, 0xffff0000, v234
	v_lshlrev_b32_e32 v177, 16, v235
	v_and_b32_e32 v185, 0xffff0000, v235
	v_add_f32_e32 v99, v160, v99
	v_add_f32_e32 v175, v161, v175
	v_add_f32_e32 v177, v162, v177
	v_add_f32_e32 v185, v163, v185
	v_mul_f32_e32 v99, 0xbfb8aa3b, v99
	v_mul_f32_e32 v175, 0xbfb8aa3b, v175
	v_mul_f32_e32 v177, 0xbfb8aa3b, v177
	v_mul_f32_e32 v234, 0xbfb8aa3b, v185
	v_exp_f32_e32 v187, v99
	v_exp_f32_e32 v185, v175
	v_exp_f32_e32 v177, v177
	v_exp_f32_e32 v175, v234
	s_cbranch_vccnz .LBB0_253
	v_add_f32_e32 v99, 1.0, v187
	v_rcp_f32_e32 v234, v99
	v_add_f32_e32 v99, 1.0, v185
	v_rcp_f32_e32 v235, v99
	v_add_f32_e32 v99, 1.0, v177
	v_rcp_f32_e32 v236, v99
	v_add_f32_e32 v99, 1.0, v175
	v_rcp_f32_e32 v237, v99
	v_pk_mul_f32 v[234:235], v[64:65], v[234:235]
	v_mov_b32_e32 v99, v97
	v_cvt_pk_bf16_f32 v234, v234, v235
	v_pk_mul_f32 v[236:237], v[66:67], v[236:237]
	s_mov_b64 s[20:21], 0
	v_cvt_pk_bf16_f32 v235, v236, v237
	v_lshl_add_u64 v[236:237], v[208:209], 0, v[98:99]
	global_store_dwordx2 v[236:237], v[234:235], off
.LBB0_253:
	s_andn2_b64 vcc, exec, s[20:21]
	s_cbranch_vccnz .LBB0_255
	v_add_f32_e32 v99, 1.0, v187
	v_add_f32_e32 v185, 1.0, v185
	v_rcp_f32_e32 v234, v99
	v_rcp_f32_e32 v235, v185
	v_add_f32_e32 v177, 1.0, v177
	v_add_f32_e32 v175, 1.0, v175
	v_rcp_f32_e32 v238, v177
	v_rcp_f32_e32 v239, v175
	v_and_b32_e32 v99, 0xffff0000, v221
	v_lshlrev_b32_e32 v185, 16, v221
	v_and_b32_e32 v187, 0xffff0000, v220
	v_lshlrev_b32_e32 v220, 16, v220
	v_add_f32_e32 v99, v159, v99
	v_add_f32_e32 v185, v158, v185
	v_add_f32_e32 v187, v157, v187
	v_add_f32_e32 v220, v156, v220
	v_mul_f32_e32 v220, 0xbfb8aa3b, v220
	v_mul_f32_e32 v187, 0xbfb8aa3b, v187
	v_mul_f32_e32 v185, 0xbfb8aa3b, v185
	v_mul_f32_e32 v99, 0xbfb8aa3b, v99
	v_exp_f32_e32 v220, v220
	v_exp_f32_e32 v236, v185
	v_exp_f32_e32 v237, v99
	v_exp_f32_e32 v221, v187
	v_pk_add_f32 v[236:237], v[236:237], 1.0 op_sel_hi:[1,0]
	v_pk_add_f32 v[220:221], v[220:221], 1.0 op_sel_hi:[1,0]
	s_nop 0
	v_pk_mul_f32 v[220:221], v[234:235], v[220:221]
	v_pk_mul_f32 v[234:235], v[238:239], v[236:237]
	v_pk_mul_f32 v[64:65], v[64:65], v[220:221]
	v_pk_mul_f32 v[66:67], v[66:67], v[234:235]

; DI unsigned pk2(float lo, float hi) { f32x2 v = {lo, hi}; return __builtin_bit_cast(unsigned, __builtin_convertvector(v, bf16x2n)); }
; DI float bflo(unsigned u) { return __uint_as_float(u << 16); }
; DI float bfhi(unsigned u) { return __uint_as_float(u & 0xffff0000u); }
; DI float sigm_f(float x) { return __builtin_amdgcn_rcpf(1.0f + __expf(-x)); }
; DI size_t PIDX(int row, int col) { return ((size_t)(col >> 8) * S + row) * 256 + (col & 255); }
;     DI bool operator()(f32x4 (&acc)[2][2][4][2], const pg8::Unit& u, int wr, int wc, int fr, int fq) const {
;     ...
;                 for (int mi = 0; mi < 2; ++mi) { const int row = row0 + ai * 128 + (2 * mp + mi) * 16;
; #pragma unroll
;                     for (int bj = 0; bj < 2; ++bj)
; #pragma unroll
;                         for (int n = 0; n < 2; ++n) { const int col = col0 + bj * 128 + n * 16;
;                             gc[mi][bj][n] = *(const u32x2*)(proj + PIDX(row, C_MERGE + nb * D + col));
;                             gn[mi][bj][n] = *(const u32x2*)(proj + PIDX(row, C_MERGE + nn * D + col)); } }
; #pragma unroll
;                 for (int mi = 0; mi < 2; ++mi) { const int m = 2 * mp + mi; const int row = row0 + ai * 128 + m * 16;
; #pragma unroll
;                     for (int bj = 0; bj < 2; ++bj)
; #pragma unroll
;                         for (int n = 0; n < 2; ++n) { const int col = col0 + bj * 128 + n * 16;
;                             const u32x2 c2 = gc[mi][bj][n], n2 = gn[mi][bj][n]; const f32x4 cb = bc[bj][n], nbv = bn[bj][n];
;                             const float xc[4] = {bflo(c2[0]) + cb[0], bfhi(c2[0]) + cb[1], bflo(c2[1]) + cb[2], bfhi(c2[1]) + cb[3]};
;                             const float xn[4] = {bflo(n2[0]) + nbv[0], bfhi(n2[0]) + nbv[1], bflo(n2[1]) + nbv[2], bfhi(n2[1]) + nbv[3]};
;                             if (nb < 2) {
; #pragma unroll
;                                 for (int e = 0; e < 4; ++e) acc[ai][bj][m][n][e] *= (1.0f + __expf(-xn[e])) * __builtin_amdgcn_rcpf(1.0f + __expf(-xc[e]));
;                             } else {
;                                 const f32x4 a = acc[ai][bj][m][n];
;                                 u32x2 o = {pk2(a[0] * sigm_f(xc[0]), a[1] * sigm_f(xc[1])), pk2(a[2] * sigm_f(xc[2]), a[3] * sigm_f(xc[3]))};
.LBB0_283:
	v_add_u32_e32 v214, 0xa0, v174
	v_ashrrev_i32_e32 v215, 31, v214
	v_lshlrev_b64 v[188:189], 9, v[214:215]
	v_lshl_add_u64 v[190:191], s[16:17], 0, v[188:189]
	v_mov_b32_e32 v177, v97
	v_lshl_add_u64 v[212:213], s[18:19], 0, v[188:189]
	v_lshl_add_u64 v[188:189], v[190:191], 0, v[96:97]
	v_mov_b32_e32 v185, v97
	v_lshl_add_u64 v[196:197], v[190:191], 0, v[176:177]
	v_lshl_add_u64 v[192:193], v[190:191], 0, v[184:185]
	v_lshl_add_u64 v[194:195], v[212:213], 0, v[184:185]
	global_load_dwordx2 v[216:217], v[188:189], off
	global_load_dwordx2 v[210:211], v[192:193], off
	global_load_dwordx2 v[208:209], v[194:195], off
	global_load_dwordx2 v[206:207], v[196:197], off
	v_add_u32_e32 v196, 0xb0, v174
	v_ashrrev_i32_e32 v197, 31, v196
	v_mov_b32_e32 v187, v97
	v_lshlrev_b64 v[174:175], 9, v[196:197]
	v_lshl_add_u64 v[188:189], v[212:213], 0, v[176:177]
	v_lshl_add_u64 v[190:191], v[190:191], 0, v[186:187]
	v_lshl_add_u64 v[218:219], s[16:17], 0, v[174:175]
	v_lshl_add_u64 v[174:175], s[18:19], 0, v[174:175]
	v_lshl_add_u64 v[192:193], v[212:213], 0, v[186:187]
	v_lshl_add_u64 v[194:195], v[218:219], 0, v[96:97]
	global_load_dwordx2 v[204:205], v[188:189], off
	global_load_dwordx2 v[202:203], v[190:191], off
	global_load_dwordx2 v[200:201], v[192:193], off
	global_load_dwordx2 v[198:199], v[194:195], off
	v_lshl_add_u64 v[188:189], v[174:175], 0, v[96:97]
	v_lshl_add_u64 v[190:191], v[218:219], 0, v[184:185]
	v_lshl_add_u64 v[184:185], v[174:175], 0, v[184:185]
	v_lshl_add_u64 v[220:221], v[218:219], 0, v[176:177]
	global_load_dwordx2 v[194:195], v[188:189], off
	global_load_dwordx2 v[192:193], v[190:191], off
	s_nop 0
	global_load_dwordx2 v[190:191], v[184:185], off
	global_load_dwordx2 v[188:189], v[220:221], off
	v_lshl_add_u64 v[176:177], v[174:175], 0, v[176:177]
	v_lshl_add_u64 v[174:175], v[174:175], 0, v[186:187]
	v_lshl_add_u64 v[218:219], v[218:219], 0, v[186:187]
	global_load_dwordx2 v[184:185], v[176:177], off
	s_nop 0
	global_load_dwordx2 v[176:177], v[218:219], off
	s_nop 0
	global_load_dwordx2 v[174:175], v[174:175], off
	v_lshlrev_b64 v[186:187], 12, v[214:215]
	s_mov_b64 s[16:17], -1
	s_and_b64 vcc, exec, s[42:43]
	v_lshl_add_u64 v[186:187], s[6:7], 0, v[186:187]
	v_lshl_add_u64 v[212:213], v[212:213], 0, v[96:97]
	global_load_dwordx2 v[212:213], v[212:213], off
	s_waitcnt vmcnt(0)
	v_lshlrev_b32_e32 v99, 16, v216
	v_and_b32_e32 v214, 0xffff0000, v216
	v_lshlrev_b32_e32 v215, 16, v217
	v_and_b32_e32 v216, 0xffff0000, v217
	v_add_f32_e32 v99, v160, v99
	v_add_f32_e32 v214, v161, v214
	v_add_f32_e32 v215, v162, v215
	v_add_f32_e32 v216, v163, v216
	v_mul_f32_e32 v99, 0xbfb8aa3b, v99
	v_mul_f32_e32 v214, 0xbfb8aa3b, v214
	v_mul_f32_e32 v215, 0xbfb8aa3b, v215
	v_mul_f32_e32 v218, 0xbfb8aa3b, v216
	v_exp_f32_e32 v217, v99
	v_exp_f32_e32 v216, v214
	v_exp_f32_e32 v215, v215
	v_exp_f32_e32 v214, v218
	s_cbranch_vccnz .LBB0_285
	v_add_f32_e32 v99, 1.0, v217
	v_rcp_f32_e32 v218, v99
	v_add_f32_e32 v99, 1.0, v216
	v_rcp_f32_e32 v219, v99
	v_add_f32_e32 v99, 1.0, v215
	v_rcp_f32_e32 v220, v99
	v_add_f32_e32 v99, 1.0, v214
	v_rcp_f32_e32 v221, v99
	v_pk_mul_f32 v[218:219], v[48:49], v[218:219]
	v_mov_b32_e32 v99, v97
	v_cvt_pk_bf16_f32 v218, v218, v219
	v_pk_mul_f32 v[220:221], v[50:51], v[220:221]
	s_mov_b64 s[16:17], 0
	v_cvt_pk_bf16_f32 v219, v220, v221
	v_lshl_add_u64 v[220:221], v[186:187], 0, v[98:99]
	global_store_dwordx2 v[220:221], v[218:219], off
.LBB0_285:
	s_andn2_b64 vcc, exec, s[16:17]
	s_cbranch_vccnz .LBB0_287
	v_add_f32_e32 v96, 1.0, v217
	v_add_f32_e32 v99, 1.0, v216
	v_add_f32_e32 v218, 1.0, v215
	v_add_f32_e32 v219, 1.0, v214
	v_rcp_f32_e32 v214, v96
	v_rcp_f32_e32 v215, v99
	v_rcp_f32_e32 v218, v218
	v_rcp_f32_e32 v219, v219
	v_and_b32_e32 v96, 0xffff0000, v213
	v_lshlrev_b32_e32 v99, 16, v213
	v_and_b32_e32 v213, 0xffff0000, v212
	v_lshlrev_b32_e32 v212, 16, v212
	v_add_f32_e32 v96, v159, v96
	v_add_f32_e32 v99, v158, v99
	v_add_f32_e32 v213, v157, v213
	v_add_f32_e32 v212, v156, v212
	v_mul_f32_e32 v212, 0xbfb8aa3b, v212
	v_mul_f32_e32 v213, 0xbfb8aa3b, v213
	v_mul_f32_e32 v99, 0xbfb8aa3b, v99
	v_mul_f32_e32 v96, 0xbfb8aa3b, v96
	v_exp_f32_e32 v212, v212
	v_exp_f32_e32 v216, v99
	v_exp_f32_e32 v217, v96
	v_exp_f32_e32 v213, v213
	v_pk_add_f32 v[216:217], v[216:217], 1.0 op_sel_hi:[1,0]
	v_pk_add_f32 v[212:213], v[212:213], 1.0 op_sel_hi:[1,0]
	s_nop 0
	v_pk_mul_f32 v[212:213], v[214:215], v[212:213]
	v_pk_mul_f32 v[214:215], v[218:219], v[216:217]
	v_pk_mul_f32 v[48:49], v[48:49], v[212:213]
	v_pk_mul_f32 v[50:51], v[50:51], v[214:215]

; DI void hyena_item(const Params& p, int l, int dpr, LAS unsigned char* lds) {
;     ...
;     for (int r = 0; r < 16; ++r) { const int t = tid + NTHR * r;
;         float v[4];
; #pragma unroll
;         for (int c = 0; c < 4; ++c) v[c] = conv3(bint + (size_t)(a + c) * S, t, w[c][0], w[c][1], w[c][2]) * 0.25f;
;         X0[XI(t)] = (hc){(_Float16)v[0], (_Float16)v[1]}; X1[XI(t)] = (hc){(_Float16)v[2], (_Float16)v[3]};
;         X0[XI(t + 8192)] = hzero; X1[XI(t + 8192)] = hzero; }
.LBB0_601:
	v_add_u32_e32 v22, s7, v12
	v_mov_b32_e32 v140, v22
	v_ashrrev_i32_e32 v141, 31, v140
	v_lshlrev_b64 v[140:141], 2, v[140:141]
	v_lshl_add_u64 v[142:143], s[58:59], 0, v[140:141]
	global_load_dword v144, v[142:143], off
	v_lshl_add_u64 v[142:143], s[62:63], 0, v[140:141]
	global_load_dword v145, v[142:143], off
	v_lshl_add_u64 v[142:143], s[18:19], 0, v[140:141]
	global_load_dword v146, v[142:143], off
	v_lshl_add_u64 v[142:143], s[16:17], 0, v[140:141]
	global_load_dword v147, v[142:143], off
	v_add_u32_e32 v140, 0x200, v22
	v_ashrrev_i32_e32 v141, 31, v140
	v_lshlrev_b64 v[140:141], 2, v[140:141]
	v_lshl_add_u64 v[142:143], s[58:59], 0, v[140:141]
	global_load_dword v148, v[142:143], off
	v_lshl_add_u64 v[142:143], s[62:63], 0, v[140:141]
	global_load_dword v149, v[142:143], off
	v_lshl_add_u64 v[142:143], s[18:19], 0, v[140:141]
	global_load_dword v150, v[142:143], off
	v_lshl_add_u64 v[142:143], s[16:17], 0, v[140:141]
	global_load_dword v151, v[142:143], off
	v_add_u32_e32 v140, 0x400, v22
	v_ashrrev_i32_e32 v141, 31, v140
	v_lshlrev_b64 v[140:141], 2, v[140:141]
	v_lshl_add_u64 v[142:143], s[58:59], 0, v[140:141]
	global_load_dword v152, v[142:143], off
	v_lshl_add_u64 v[142:143], s[62:63], 0, v[140:141]
	global_load_dword v153, v[142:143], off
	v_lshl_add_u64 v[142:143], s[18:19], 0, v[140:141]
	global_load_dword v154, v[142:143], off
	v_lshl_add_u64 v[142:143], s[16:17], 0, v[140:141]
	global_load_dword v155, v[142:143], off
	v_add_u32_e32 v140, 0x600, v22
	v_ashrrev_i32_e32 v141, 31, v140
	v_lshlrev_b64 v[140:141], 2, v[140:141]
	v_lshl_add_u64 v[142:143], s[58:59], 0, v[140:141]
	global_load_dword v156, v[142:143], off
	v_lshl_add_u64 v[142:143], s[62:63], 0, v[140:141]
	global_load_dword v157, v[142:143], off
	v_lshl_add_u64 v[142:143], s[18:19], 0, v[140:141]
	global_load_dword v158, v[142:143], off
	v_lshl_add_u64 v[142:143], s[16:17], 0, v[140:141]
	global_load_dword v159, v[142:143], off
	v_ashrrev_i32_e32 v23, 31, v22
	v_max_i32_e32 v96, 1, v22
	v_min_i32_e32 v24, 0x1ffe, v22
	v_lshlrev_b64 v[26:27], 2, v[22:23]
	v_lshlrev_b64 v[30:31], 2, v[96:97]
	v_ashrrev_i32_e32 v25, 31, v24
	v_lshl_add_u64 v[28:29], s[58:59], 0, v[26:27]
	v_lshl_add_u64 v[32:33], s[58:59], 0, v[30:31]
	global_load_dword v28, v[28:29], off
	v_lshlrev_b64 v[24:25], 2, v[24:25]
	global_load_dword v23, v[32:33], off offset:-4
	v_lshl_add_u64 v[32:33], s[58:59], 0, v[24:25]
	global_load_dword v32, v[32:33], off offset:4
	v_cmp_lt_i32_e32 vcc, 0, v22
	v_cmp_gt_i32_e64 s[40:41], s29, v22
	s_addk_i32 s7, 0x800
	s_cmpk_eq_i32 s7, 0x2000
	s_waitcnt vmcnt(1)
	v_cndmask_b32_e32 v29, 0, v23, vcc
	v_pk_mul_f32 v[28:29], v[0:1], v[28:29]
	s_waitcnt vmcnt(0)
	v_cndmask_b32_e64 v23, 0, v32, s[40:41]
	v_add_f32_e32 v28, v28, v29
	v_fmac_f32_e32 v28, v4, v23
	v_mul_f32_e32 v23, 0x3e800000, v28
	v_lshl_add_u64 v[28:29], s[62:63], 0, v[26:27]
	v_lshl_add_u64 v[32:33], s[62:63], 0, v[30:31]
	global_load_dword v28, v[28:29], off
	s_nop 0
	global_load_dword v29, v[32:33], off offset:-4
	v_lshl_add_u64 v[32:33], s[62:63], 0, v[24:25]
	global_load_dword v32, v[32:33], off offset:4
	s_waitcnt vmcnt(1)
	v_cndmask_b32_e32 v29, 0, v29, vcc
	v_pk_mul_f32 v[28:29], v[8:9], v[28:29]
	s_waitcnt vmcnt(0)
	v_cndmask_b32_e64 v32, 0, v32, s[40:41]
	v_add_f32_e32 v28, v28, v29
	v_fmac_f32_e32 v28, v5, v32
	v_mul_f32_e32 v34, 0x3e800000, v28
	v_lshl_add_u64 v[28:29], s[18:19], 0, v[26:27]
	v_lshl_add_u64 v[32:33], s[18:19], 0, v[30:31]
	v_lshl_add_u64 v[26:27], s[16:17], 0, v[26:27]
	global_load_dword v28, v[28:29], off
	v_cvt_pk_f16_f32 v23, v23, v34
	global_load_dword v26, v[26:27], off
	s_nop 0
	global_load_dword v29, v[32:33], off offset:-4
	v_lshl_add_u64 v[32:33], s[18:19], 0, v[24:25]
	global_load_dword v32, v[32:33], off offset:4
	v_lshl_add_u64 v[24:25], s[16:17], 0, v[24:25]
	global_load_dword v24, v[24:25], off offset:4
	s_waitcnt vmcnt(2)
	v_cndmask_b32_e32 v29, 0, v29, vcc
	v_pk_mul_f32 v[28:29], v[2:3], v[28:29]
	s_waitcnt vmcnt(1)
	v_cndmask_b32_e64 v32, 0, v32, s[40:41]
	v_add_f32_e32 v28, v28, v29
	v_fmac_f32_e32 v28, v6, v32
	v_mul_f32_e32 v32, 0x3e800000, v28
	v_lshl_add_u64 v[28:29], s[16:17], 0, v[30:31]
	global_load_dword v27, v[28:29], off offset:-4
	s_waitcnt vmcnt(1)
	v_cndmask_b32_e64 v28, 0, v24, s[40:41]
	s_waitcnt vmcnt(0)
	v_cndmask_b32_e32 v27, 0, v27, vcc
	v_pk_mul_f32 v[24:25], v[10:11], v[26:27]
	v_ashrrev_i32_e32 v26, 8, v22
	v_add_f32_e32 v24, v24, v25
	v_ashrrev_i32_e32 v25, 4, v22
	v_add_u32_e32 v25, v25, v26
	v_fmac_f32_e32 v24, v7, v28
	v_add_lshl_u32 v25, v22, v25, 2
	v_mul_f32_e32 v24, 0x3e800000, v24
	v_add_u32_e32 v26, 0, v25
	ds_write_b32 v26, v23
	v_cvt_pk_f16_f32 v23, v32, v24
	v_add_u32_e32 v24, s66, v25
	ds_write_b32 v24, v23
	v_add_u32_e32 v23, 0x2000, v22
	v_ashrrev_i32_e32 v24, 4, v23
	v_ashrrev_i32_e32 v23, 8, v23
	v_add_u32_e32 v23, v24, v23
	v_add_lshl_u32 v23, v22, v23, 2
	v_add_u32_e32 v24, 0, v23
	v_add_u32_e32 v23, s66, v23
	ds_write_b32 v23, v97 offset:32768
	v_add_u32_e32 v23, 0x200, v22
	v_max_i32_e32 v96, 1, v23
	ds_write_b32 v24, v97 offset:32768
	v_min_i32_e32 v24, 0x1ffe, v23
	v_lshlrev_b64 v[28:29], 2, v[96:97]
	v_ashrrev_i32_e32 v25, 31, v24
	v_lshl_add_u64 v[30:31], s[58:59], 0, v[28:29]
	global_load_dword v27, v[30:31], off offset:-4
	v_lshlrev_b64 v[24:25], 2, v[24:25]
	global_load_dword v26, v[20:21], off
	v_lshl_add_u64 v[30:31], s[58:59], 0, v[24:25]
	global_load_dword v30, v[30:31], off offset:4
	v_cmp_lt_i32_e32 vcc, 0, v23
	v_cmp_gt_i32_e64 s[40:41], s29, v23
	v_lshl_add_u64 v[20:21], v[20:21], 0, s[46:47]
	s_waitcnt vmcnt(2)
	v_cndmask_b32_e32 v27, 0, v27, vcc
	s_waitcnt vmcnt(1)
; DI void hyena_item(const Params& p, int l, int dpr, LAS unsigned char* lds) {
;     ...
;     for (int r = 0; r < 16; ++r) { const int t = tid + NTHR * r;
;         float v[4];
; #pragma unroll
;         for (int c = 0; c < 4; ++c) v[c] = conv3(bint + (size_t)(a + c) * S, t, w[c][0], w[c][1], w[c][2]) * 0.25f;
;         X0[XI(t)] = (hc){(_Float16)v[0], (_Float16)v[1]}; X1[XI(t)] = (hc){(_Float16)v[2], (_Float16)v[3]};
;         X0[XI(t + 8192)] = hzero; X1[XI(t + 8192)] = hzero; }
	v_pk_mul_f32 v[26:27], v[0:1], v[26:27]
	s_nop 0
	v_add_f32_e32 v26, v26, v27
	s_waitcnt vmcnt(0)
	v_cndmask_b32_e64 v30, 0, v30, s[40:41]
	v_fmac_f32_e32 v26, v4, v30
	v_lshl_add_u64 v[30:31], s[62:63], 0, v[28:29]
	global_load_dword v27, v[30:31], off offset:-4
	v_mul_f32_e32 v32, 0x3e800000, v26
	global_load_dword v26, v[18:19], off
	v_lshl_add_u64 v[30:31], s[62:63], 0, v[24:25]
	global_load_dword v30, v[30:31], off offset:4
	v_lshl_add_u64 v[18:19], v[18:19], 0, s[46:47]
	s_waitcnt vmcnt(2)
	v_cndmask_b32_e32 v27, 0, v27, vcc
	s_waitcnt vmcnt(1)
	v_pk_mul_f32 v[26:27], v[8:9], v[26:27]
	s_nop 0
	v_add_f32_e32 v26, v26, v27
	s_waitcnt vmcnt(0)
	v_cndmask_b32_e64 v30, 0, v30, s[40:41]
	v_fmac_f32_e32 v26, v5, v30
	v_lshl_add_u64 v[30:31], s[18:19], 0, v[28:29]
	global_load_dword v27, v[30:31], off offset:-4
	v_mul_f32_e32 v33, 0x3e800000, v26
	global_load_dword v26, v[16:17], off
	v_lshl_add_u64 v[30:31], s[18:19], 0, v[24:25]
	global_load_dword v30, v[30:31], off offset:4
	v_lshl_add_u64 v[28:29], s[16:17], 0, v[28:29]
	v_lshl_add_u64 v[24:25], s[16:17], 0, v[24:25]
	v_lshl_add_u64 v[16:17], v[16:17], 0, s[46:47]
	global_load_dword v24, v[24:25], off offset:4
	s_waitcnt vmcnt(3)
	v_cndmask_b32_e32 v27, 0, v27, vcc
	s_waitcnt vmcnt(2)
	v_pk_mul_f32 v[26:27], v[2:3], v[26:27]
	s_nop 0
	v_add_f32_e32 v26, v26, v27
	global_load_dword v27, v[28:29], off offset:-4
	s_waitcnt vmcnt(2)
	v_cndmask_b32_e64 v30, 0, v30, s[40:41]
	v_fmac_f32_e32 v26, v6, v30
	v_mul_f32_e32 v30, 0x3e800000, v26
	global_load_dword v26, v[14:15], off
	v_lshl_add_u64 v[14:15], v[14:15], 0, s[46:47]
	s_waitcnt vmcnt(2)
	v_cndmask_b32_e64 v28, 0, v24, s[40:41]
	s_waitcnt vmcnt(1)
	v_cndmask_b32_e32 v27, 0, v27, vcc
	s_waitcnt vmcnt(0)
	v_pk_mul_f32 v[24:25], v[10:11], v[26:27]
	s_nop 0
	v_add_f32_e32 v24, v24, v25
	v_ashrrev_i32_e32 v26, 4, v23
	v_ashrrev_i32_e32 v23, 8, v23
	v_fmac_f32_e32 v24, v7, v28
	v_add_u32_e32 v23, v26, v23
	v_mul_f32_e32 v24, 0x3e800000, v24
	v_add_lshl_u32 v23, v22, v23, 2
	v_add_u32_e32 v26, 0, v23
	v_cvt_pk_f16_f32 v24, v30, v24
	v_add_u32_e32 v23, s66, v23
	ds_write_b32 v23, v24 offset:2048
	v_add_u32_e32 v23, 0x2200, v22
	v_ashrrev_i32_e32 v24, 4, v23
	v_ashrrev_i32_e32 v23, 8, v23
	v_add_u32_e32 v23, v24, v23
	v_add_lshl_u32 v23, v22, v23, 2
	v_cvt_pk_f16_f32 v25, v32, v33
	v_add_u32_e32 v24, 0, v23
	ds_write_b32 v26, v25 offset:2048
	ds_write_b32 v24, v97 offset:34816
	v_add_u32_e32 v24, 0x400, v22
	v_ashrrev_i32_e32 v25, 31, v24
	v_max_i32_e32 v96, 1, v24
	v_min_i32_e32 v26, 0x1ffe, v24
	v_lshlrev_b64 v[28:29], 2, v[24:25]
	v_lshlrev_b64 v[32:33], 2, v[96:97]
	v_add_u32_e32 v23, s66, v23
	v_ashrrev_i32_e32 v27, 31, v26
	v_lshl_add_u64 v[30:31], s[58:59], 0, v[28:29]
	v_lshl_add_u64 v[34:35], s[58:59], 0, v[32:33]
	ds_write_b32 v23, v97 offset:34816
	global_load_dword v30, v[30:31], off
	v_lshlrev_b64 v[26:27], 2, v[26:27]
	global_load_dword v23, v[34:35], off offset:-4
	v_lshl_add_u64 v[34:35], s[58:59], 0, v[26:27]
	global_load_dword v25, v[34:35], off offset:4
	v_cmp_lt_i32_e32 vcc, 0, v24
	v_cmp_gt_i32_e64 s[40:41], s29, v24
	v_lshl_add_u64 v[34:35], s[62:63], 0, v[32:33]
	s_waitcnt vmcnt(1)
	v_cndmask_b32_e32 v31, 0, v23, vcc
	v_pk_mul_f32 v[30:31], v[0:1], v[30:31]
	s_waitcnt vmcnt(0)
	v_cndmask_b32_e64 v23, 0, v25, s[40:41]
	v_add_f32_e32 v25, v30, v31
	v_fmac_f32_e32 v25, v4, v23
	v_lshl_add_u64 v[30:31], s[62:63], 0, v[28:29]
	v_mul_f32_e32 v23, 0x3e800000, v25
	global_load_dword v30, v[30:31], off
	s_nop 0
	global_load_dword v25, v[34:35], off offset:-4
	v_lshl_add_u64 v[34:35], s[62:63], 0, v[26:27]
	global_load_dword v34, v[34:35], off offset:4
	s_waitcnt vmcnt(1)
	v_cndmask_b32_e32 v31, 0, v25, vcc
	v_pk_mul_f32 v[30:31], v[8:9], v[30:31]
	s_waitcnt vmcnt(0)
	v_cndmask_b32_e64 v25, 0, v34, s[40:41]
	v_add_f32_e32 v30, v30, v31
	v_fmac_f32_e32 v30, v5, v25
	v_mul_f32_e32 v25, 0x3e800000, v30
	v_lshl_add_u64 v[30:31], s[18:19], 0, v[28:29]
	v_lshl_add_u64 v[34:35], s[18:19], 0, v[32:33]
	v_lshl_add_u64 v[28:29], s[16:17], 0, v[28:29]
	global_load_dword v30, v[30:31], off
	v_cvt_pk_f16_f32 v23, v23, v25
	global_load_dword v28, v[28:29], off
	v_ashrrev_i32_e32 v25, 4, v24
	global_load_dword v31, v[34:35], off offset:-4
	v_lshl_add_u64 v[34:35], s[18:19], 0, v[26:27]
	global_load_dword v34, v[34:35], off offset:4
	v_lshl_add_u64 v[26:27], s[16:17], 0, v[26:27]
	global_load_dword v26, v[26:27], off offset:4
	v_ashrrev_i32_e32 v24, 8, v24
	v_add_u32_e32 v24, v25, v24
	v_add_lshl_u32 v24, v22, v24, 2
	v_add_u32_e32 v25, 0, v24
	ds_write_b32 v25, v23 offset:4096
	v_add_u32_e32 v24, s66, v24
	s_waitcnt vmcnt(2)
; DI void hyena_item(const Params& p, int l, int dpr, LAS unsigned char* lds) {
;     ...
;     for (int r = 0; r < 16; ++r) { const int t = tid + NTHR * r;
;         float v[4];
; #pragma unroll
;         for (int c = 0; c < 4; ++c) v[c] = conv3(bint + (size_t)(a + c) * S, t, w[c][0], w[c][1], w[c][2]) * 0.25f;
;         X0[XI(t)] = (hc){(_Float16)v[0], (_Float16)v[1]}; X1[XI(t)] = (hc){(_Float16)v[2], (_Float16)v[3]};
;         X0[XI(t + 8192)] = hzero; X1[XI(t + 8192)] = hzero; }
;     __syncthreads();
	v_cndmask_b32_e32 v31, 0, v31, vcc
	v_pk_mul_f32 v[30:31], v[2:3], v[30:31]
	s_waitcnt vmcnt(1)
	v_cndmask_b32_e64 v34, 0, v34, s[40:41]
	v_add_f32_e32 v30, v30, v31
	v_fmac_f32_e32 v30, v6, v34
	v_mul_f32_e32 v34, 0x3e800000, v30
	v_lshl_add_u64 v[30:31], s[16:17], 0, v[32:33]
	global_load_dword v29, v[30:31], off offset:-4
	s_waitcnt vmcnt(1)
	v_cndmask_b32_e64 v30, 0, v26, s[40:41]
	s_waitcnt vmcnt(0)
	v_cndmask_b32_e32 v29, 0, v29, vcc
	v_pk_mul_f32 v[26:27], v[10:11], v[28:29]
	s_nop 0
	v_add_f32_e32 v26, v26, v27
	v_fmac_f32_e32 v26, v7, v30
	v_mul_f32_e32 v26, 0x3e800000, v26
	v_cvt_pk_f16_f32 v23, v34, v26
	ds_write_b32 v24, v23 offset:4096
	v_add_u32_e32 v23, 0x2400, v22
	v_ashrrev_i32_e32 v24, 4, v23
	v_ashrrev_i32_e32 v23, 8, v23
	v_add_u32_e32 v23, v24, v23
	v_add_lshl_u32 v23, v22, v23, 2
	v_add_u32_e32 v24, 0, v23
	ds_write_b32 v24, v97 offset:36864
	v_add_u32_e32 v24, 0x600, v22
	v_ashrrev_i32_e32 v25, 31, v24
	v_max_i32_e32 v96, 1, v24
	v_min_i32_e32 v26, 0x1ffe, v24
	v_lshlrev_b64 v[28:29], 2, v[24:25]
	v_lshlrev_b64 v[32:33], 2, v[96:97]
	v_add_u32_e32 v23, s66, v23
	v_ashrrev_i32_e32 v27, 31, v26
	v_lshl_add_u64 v[30:31], s[58:59], 0, v[28:29]
	v_lshl_add_u64 v[34:35], s[58:59], 0, v[32:33]
	ds_write_b32 v23, v97 offset:36864
	global_load_dword v30, v[30:31], off
	v_lshlrev_b64 v[26:27], 2, v[26:27]
	global_load_dword v23, v[34:35], off offset:-4
	v_lshl_add_u64 v[34:35], s[58:59], 0, v[26:27]
	global_load_dword v25, v[34:35], off offset:4
	v_cmp_lt_i32_e32 vcc, 0, v24
	v_cmp_gt_i32_e64 s[40:41], s29, v24
	v_lshl_add_u64 v[34:35], s[62:63], 0, v[32:33]
	s_waitcnt vmcnt(1)
	v_cndmask_b32_e32 v31, 0, v23, vcc
	v_pk_mul_f32 v[30:31], v[0:1], v[30:31]
	s_waitcnt vmcnt(0)
	v_cndmask_b32_e64 v23, 0, v25, s[40:41]
	v_add_f32_e32 v25, v30, v31
	v_fmac_f32_e32 v25, v4, v23
	v_lshl_add_u64 v[30:31], s[62:63], 0, v[28:29]
	v_mul_f32_e32 v23, 0x3e800000, v25
	global_load_dword v30, v[30:31], off
	s_nop 0
	global_load_dword v25, v[34:35], off offset:-4
	v_lshl_add_u64 v[34:35], s[62:63], 0, v[26:27]
	global_load_dword v34, v[34:35], off offset:4
	s_waitcnt vmcnt(1)
	v_cndmask_b32_e32 v31, 0, v25, vcc
	v_pk_mul_f32 v[30:31], v[8:9], v[30:31]
	s_waitcnt vmcnt(0)
	v_cndmask_b32_e64 v25, 0, v34, s[40:41]
	v_add_f32_e32 v30, v30, v31
	v_fmac_f32_e32 v30, v5, v25
	v_mul_f32_e32 v25, 0x3e800000, v30
	v_lshl_add_u64 v[30:31], s[18:19], 0, v[28:29]
	v_lshl_add_u64 v[34:35], s[18:19], 0, v[32:33]
	v_lshl_add_u64 v[28:29], s[16:17], 0, v[28:29]
	global_load_dword v30, v[30:31], off
	v_cvt_pk_f16_f32 v23, v23, v25
	global_load_dword v28, v[28:29], off
	v_ashrrev_i32_e32 v25, 4, v24
	global_load_dword v31, v[34:35], off offset:-4
	v_lshl_add_u64 v[34:35], s[18:19], 0, v[26:27]
	global_load_dword v34, v[34:35], off offset:4
	v_lshl_add_u64 v[26:27], s[16:17], 0, v[26:27]
	global_load_dword v26, v[26:27], off offset:4
	v_ashrrev_i32_e32 v24, 8, v24
	v_add_u32_e32 v24, v25, v24
	v_add_lshl_u32 v24, v22, v24, 2
	v_add_u32_e32 v25, 0, v24
	ds_write_b32 v25, v23 offset:6144
	v_add_u32_e32 v24, s66, v24
	s_waitcnt vmcnt(2)
	v_cndmask_b32_e32 v31, 0, v31, vcc
	v_pk_mul_f32 v[30:31], v[2:3], v[30:31]
	s_waitcnt vmcnt(1)
	v_cndmask_b32_e64 v34, 0, v34, s[40:41]
	v_add_f32_e32 v30, v30, v31
	v_fmac_f32_e32 v30, v6, v34
	v_mul_f32_e32 v34, 0x3e800000, v30
	v_lshl_add_u64 v[30:31], s[16:17], 0, v[32:33]
	global_load_dword v29, v[30:31], off offset:-4
	s_waitcnt vmcnt(1)
	v_cndmask_b32_e64 v30, 0, v26, s[40:41]
	s_waitcnt vmcnt(0)
	v_cndmask_b32_e32 v29, 0, v29, vcc
	v_pk_mul_f32 v[26:27], v[10:11], v[28:29]
	s_nop 0
	v_add_f32_e32 v26, v26, v27
	v_fmac_f32_e32 v26, v7, v30
	v_mul_f32_e32 v26, 0x3e800000, v26
	v_cvt_pk_f16_f32 v23, v34, v26
	ds_write_b32 v24, v23 offset:6144
	v_add_u32_e32 v23, 0x2600, v22
	v_ashrrev_i32_e32 v24, 4, v23
	v_ashrrev_i32_e32 v23, 8, v23
	v_add_u32_e32 v23, v24, v23
	v_add_lshl_u32 v22, v22, v23, 2
	v_add_u32_e32 v23, 0, v22
	v_add_u32_e32 v22, s66, v22
	ds_write_b32 v23, v97 offset:38912
	ds_write_b32 v22, v97 offset:38912
	s_cbranch_scc0 .LBB0_601
	v_mov_b32_e32 v0, v12
	s_waitcnt lgkmcnt(0)
	s_barrier
	s_nop 0
	v_cmp_gt_i32_e32 vcc, s45, v0
	s_and_saveexec_b64 s[20:21], vcc
	s_movk_i32 s6, 0xc000
	s_movk_i32 s8, 0xdff
	s_mov_b64 s[26:27], 0x10000
	s_cbranch_execz .LBB0_605
	v_lshlrev_b32_e32 v1, 2, v0
	s_mov_b64 s[22:23], 0

; #define LAS __attribute__((address_space(3)))
; DI int rev4(int pp) { const unsigned br = __brev((unsigned)pp) >> 18; return (int)(((br & 0x2AAAu) >> 1) | ((br & 0x1555u) << 1)); }
; DI void pw_h(LAS hc* X, const f32x4* spec, int tid) {
; #pragma unroll 8
;     for (int r = 0; r < 16; ++r) {
;         const int k = tid + NTHR * r; const int pp = rev4(k);
;         const f32x4 sp = spec[k]; const cf P = (cf){sp[0], sp[1]} * 256.0f, Mq = (cf){sp[2], sp[3]} * 256.0f;
;         const hc zh = X[XI(pp)]; const cf z = (cf){(float)zh.x, (float)zh.y};
;         if (k == 0) { const cf y = cmul(z, P) + cmul((cf){z.x, -z.y}, Mq); X[XI(pp)] = (hc){(_Float16)y.x, (_Float16)y.y}; }
;         else { const int pm = rev4(16384 - k); const hc zmh = X[XI(pm)]; const cf zm = (cf){(float)zmh.x, (float)zmh.y};
;             const cf y = cmul(z, P) + cmul((cf){zm.x, -zm.y}, Mq);
;             const cf t = cmul((cf){zm.x, -zm.y}, P) + cmul(z, Mq);
;             X[XI(pp)] = (hc){(_Float16)y.x, (_Float16)y.y}; X[XI(pm)] = (hc){(_Float16)t.x, (_Float16)(-t.y)}; }
.LBB0_616:
	global_load_dwordx4 v[4:7], v[0:1], off
	v_add_u32_e32 v9, s4, v12
	v_add_u32_e32 v2, 0x2000, v9
	v_bfrev_b32_e32 v2, v2
	v_lshrrev_b32_e32 v3, 19, v2
	v_lshrrev_b32_e32 v2, 17, v2
	v_and_b32_e32 v2, 0x2aaa, v2
	v_and_or_b32 v10, v3, s89, v2
	s_movk_i32 s5, 0xe000
	v_cmp_ne_u32_e32 vcc, s5, v9
	v_add_u32_e32 v100, 0x2200, v9
	v_ashrrev_i32_e32 v101, 31, v100
	v_lshl_add_u64 v[100:101], v[100:101], 4, s[20:21]
	global_load_dwordx4 v[104:107], v[100:101], off
	v_add_u32_e32 v100, 0x2400, v9
	v_ashrrev_i32_e32 v101, 31, v100
	v_lshl_add_u64 v[100:101], v[100:101], 4, s[20:21]
	global_load_dwordx4 v[108:111], v[100:101], off
	v_add_u32_e32 v100, 0x2600, v9
	v_ashrrev_i32_e32 v101, 31, v100
	v_lshl_add_u64 v[100:101], v[100:101], 4, s[20:21]
	global_load_dwordx4 v[112:115], v[100:101], off
	v_add_u32_e32 v100, 0x2800, v9
	v_ashrrev_i32_e32 v101, 31, v100
	v_lshl_add_u64 v[100:101], v[100:101], 4, s[20:21]
	global_load_dwordx4 v[116:119], v[100:101], off
	v_add_u32_e32 v100, 0x2a00, v9
	v_ashrrev_i32_e32 v101, 31, v100
	v_lshl_add_u64 v[100:101], v[100:101], 4, s[20:21]
	global_load_dwordx4 v[120:123], v[100:101], off
	v_add_u32_e32 v100, 0x2c00, v9
	v_ashrrev_i32_e32 v101, 31, v100
	v_lshl_add_u64 v[100:101], v[100:101], 4, s[20:21]
	global_load_dwordx4 v[124:127], v[100:101], off
	v_add_u32_e32 v100, 0x2e00, v9
	v_ashrrev_i32_e32 v101, 31, v100
	v_lshl_add_u64 v[100:101], v[100:101], 4, s[20:21]
	global_load_dwordx4 v[128:131], v[100:101], off
	s_waitcnt vmcnt(7)
	v_pk_mul_f32 v[2:3], v[6:7], s[90:91] op_sel_hi:[1,0]
	v_lshl_add_u32 v6, v10, 2, 0
	v_lshrrev_b32_e32 v7, 2, v10
	v_lshrrev_b32_e32 v10, 6, v10
	v_and_b32_e32 v7, 0xffc, v7
	v_and_b32_e32 v10, 0xfc, v10
	v_add3_u32 v10, v6, v7, v10
	ds_read_b32 v7, v10
	v_pk_mul_f32 v[4:5], v[4:5], s[90:91] op_sel_hi:[1,0]
	s_waitcnt lgkmcnt(0)
	v_cvt_f32_f16_e32 v6, v7
	v_cvt_f32_f16_sdwa v7, v7 dst_sel:DWORD dst_unused:UNUSED_PAD src0_sel:WORD_1
	s_and_saveexec_b64 s[22:23], vcc
	s_xor_b64 s[22:23], exec, s[22:23]
	s_cbranch_execz .LBB0_618
	v_add_u32_e32 v11, 0xe00, v8
	v_bfrev_b32_e32 v11, v11
	v_lshrrev_b32_e32 v13, 19, v11
	v_lshrrev_b32_e32 v11, 17, v11
	v_and_b32_e32 v11, 0x2aaa, v11
	v_and_or_b32 v11, v13, s89, v11
	v_lshl_add_u32 v13, v11, 2, 0
	v_lshrrev_b32_e32 v16, 2, v11
	v_lshrrev_b32_e32 v11, 6, v11
	v_and_b32_e32 v16, 0xffc, v16
	v_and_b32_e32 v11, 0xfc, v11
	v_add3_u32 v11, v13, v16, v11
	ds_read_b32 v13, v11
	v_pk_mul_f32 v[18:19], v[6:7], v[4:5] op_sel:[0,0] op_sel_hi:[0,1]
	s_waitcnt lgkmcnt(0)
	v_cvt_f32_f16_e32 v16, v13
	v_cvt_f32_f16_sdwa v17, -v13 dst_sel:DWORD dst_unused:UNUSED_PAD src0_sel:WORD_1
	v_pk_mul_f32 v[22:23], v[16:17], v[2:3] op_sel:[0,0] op_sel_hi:[0,1]
	v_pk_fma_f32 v[18:19], v[6:7], v[4:5], v[18:19] op_sel:[1,1,0] op_sel_hi:[1,0,1] neg_lo:[0,1,0]
	v_pk_fma_f32 v[22:23], v[16:17], v[2:3], v[22:23] op_sel:[1,1,0] op_sel_hi:[1,0,1] neg_lo:[0,1,0]
	v_pk_add_f32 v[18:19], v[18:19], v[22:23]
	v_pk_mul_f32 v[22:23], v[16:17], v[4:5] op_sel:[0,0] op_sel_hi:[0,1]
	v_pk_fma_f32 v[4:5], v[16:17], v[4:5], v[22:23] op_sel:[1,1,0] op_sel_hi:[1,0,1] neg_lo:[0,1,0]
	v_pk_mul_f32 v[16:17], v[6:7], v[2:3] op_sel:[0,0] op_sel_hi:[0,1]
	v_pk_fma_f32 v[2:3], v[6:7], v[2:3], v[16:17] op_sel:[1,1,0] op_sel_hi:[1,0,1] neg_lo:[0,1,0]
	s_nop 0
	v_pk_add_f32 v[2:3], v[4:5], v[2:3]
	v_cvt_pk_f16_f32 v4, v18, v19
	v_cvt_pk_f16_f32 v2, v2, -v3
	ds_write_b32 v10, v4
	ds_write_b32 v11, v2

; DI int rev4(int pp) { const unsigned br = __brev((unsigned)pp) >> 18; return (int)(((br & 0x2AAAu) >> 1) | ((br & 0x1555u) << 1)); }
; DI void pw_h(LAS hc* X, const f32x4* spec, int tid) {
;     ...
;     for (int r = 0; r < 16; ++r) {
;         const int k = tid + NTHR * r; const int pp = rev4(k);
;         const f32x4 sp = spec[k]; const cf P = (cf){sp[0], sp[1]} * 256.0f, Mq = (cf){sp[2], sp[3]} * 256.0f;
;         const hc zh = X[XI(pp)]; const cf z = (cf){(float)zh.x, (float)zh.y};
;         if (k == 0) { const cf y = cmul(z, P) + cmul((cf){z.x, -z.y}, Mq); X[XI(pp)] = (hc){(_Float16)y.x, (_Float16)y.y}; }
;         else { const int pm = rev4(16384 - k); const hc zmh = X[XI(pm)]; const cf zm = (cf){(float)zmh.x, (float)zmh.y};
;             const cf y = cmul(z, P) + cmul((cf){zm.x, -zm.y}, Mq);
;             const cf t = cmul((cf){zm.x, -zm.y}, P) + cmul(z, Mq);
;             X[XI(pp)] = (hc){(_Float16)y.x, (_Float16)y.y}; X[XI(pm)] = (hc){(_Float16)t.x, (_Float16)(-t.y)}; }
.LBB0_620:
	s_or_b64 exec, exec, s[22:23]
	v_add_u32_e32 v2, 0x2200, v9
	v_bfrev_b32_e32 v3, v2
	v_lshrrev_b32_e32 v4, 19, v3
	v_lshrrev_b32_e32 v3, 17, v3
	v_and_b32_e32 v3, 0x2aaa, v3
	v_and_or_b32 v10, v4, s89, v3
	s_movk_i32 s5, 0xde00
	v_cmp_ne_u32_e32 vcc, s5, v9
	s_waitcnt vmcnt(6)
	v_mov_b32_e32 v4, v104
	v_mov_b32_e32 v5, v105
	v_mov_b32_e32 v6, v106
	v_mov_b32_e32 v7, v107
	v_pk_mul_f32 v[2:3], v[6:7], s[90:91] op_sel_hi:[1,0]
	v_lshl_add_u32 v6, v10, 2, 0
	v_lshrrev_b32_e32 v7, 2, v10
	v_lshrrev_b32_e32 v10, 6, v10
	v_and_b32_e32 v7, 0xffc, v7
	v_and_b32_e32 v10, 0xfc, v10
	v_add3_u32 v10, v6, v7, v10
	ds_read_b32 v7, v10
	v_pk_mul_f32 v[4:5], v[4:5], s[90:91] op_sel_hi:[1,0]
	s_waitcnt lgkmcnt(0)
	v_cvt_f32_f16_e32 v6, v7
	v_cvt_f32_f16_sdwa v7, v7 dst_sel:DWORD dst_unused:UNUSED_PAD src0_sel:WORD_1
	s_and_saveexec_b64 s[22:23], vcc
	s_xor_b64 s[22:23], exec, s[22:23]
	s_cbranch_execz .LBB0_622
	v_add_u32_e32 v11, 0xc00, v8
	v_bfrev_b32_e32 v11, v11
	v_lshrrev_b32_e32 v13, 19, v11
	v_lshrrev_b32_e32 v11, 17, v11
	v_and_b32_e32 v11, 0x2aaa, v11
	v_and_or_b32 v11, v13, s89, v11
	v_lshl_add_u32 v13, v11, 2, 0
	v_lshrrev_b32_e32 v16, 2, v11
	v_lshrrev_b32_e32 v11, 6, v11
	v_and_b32_e32 v16, 0xffc, v16
	v_and_b32_e32 v11, 0xfc, v11
	v_add3_u32 v11, v13, v16, v11
	ds_read_b32 v13, v11
	v_pk_mul_f32 v[18:19], v[6:7], v[4:5] op_sel:[0,0] op_sel_hi:[0,1]
	s_waitcnt lgkmcnt(0)
	v_cvt_f32_f16_e32 v16, v13
	v_cvt_f32_f16_sdwa v17, -v13 dst_sel:DWORD dst_unused:UNUSED_PAD src0_sel:WORD_1
	v_pk_mul_f32 v[22:23], v[16:17], v[2:3] op_sel:[0,0] op_sel_hi:[0,1]
	v_pk_fma_f32 v[18:19], v[6:7], v[4:5], v[18:19] op_sel:[1,1,0] op_sel_hi:[1,0,1] neg_lo:[0,1,0]
	v_pk_fma_f32 v[22:23], v[16:17], v[2:3], v[22:23] op_sel:[1,1,0] op_sel_hi:[1,0,1] neg_lo:[0,1,0]
	v_pk_add_f32 v[18:19], v[18:19], v[22:23]
	v_pk_mul_f32 v[22:23], v[16:17], v[4:5] op_sel:[0,0] op_sel_hi:[0,1]
	v_pk_fma_f32 v[4:5], v[16:17], v[4:5], v[22:23] op_sel:[1,1,0] op_sel_hi:[1,0,1] neg_lo:[0,1,0]
	v_pk_mul_f32 v[16:17], v[6:7], v[2:3] op_sel:[0,0] op_sel_hi:[0,1]
	v_pk_fma_f32 v[2:3], v[6:7], v[2:3], v[16:17] op_sel:[1,1,0] op_sel_hi:[1,0,1] neg_lo:[0,1,0]
	s_nop 0
	v_pk_add_f32 v[2:3], v[4:5], v[2:3]
	v_cvt_pk_f16_f32 v4, v18, v19
	v_cvt_pk_f16_f32 v2, v2, -v3
	ds_write_b32 v10, v4
	ds_write_b32 v11, v2

; DI int rev4(int pp) { const unsigned br = __brev((unsigned)pp) >> 18; return (int)(((br & 0x2AAAu) >> 1) | ((br & 0x1555u) << 1)); }
; DI void pw_h(LAS hc* X, const f32x4* spec, int tid) {
;     ...
;     for (int r = 0; r < 16; ++r) {
;         const int k = tid + NTHR * r; const int pp = rev4(k);
;         const f32x4 sp = spec[k]; const cf P = (cf){sp[0], sp[1]} * 256.0f, Mq = (cf){sp[2], sp[3]} * 256.0f;
;         const hc zh = X[XI(pp)]; const cf z = (cf){(float)zh.x, (float)zh.y};
;         if (k == 0) { const cf y = cmul(z, P) + cmul((cf){z.x, -z.y}, Mq); X[XI(pp)] = (hc){(_Float16)y.x, (_Float16)y.y}; }
;         else { const int pm = rev4(16384 - k); const hc zmh = X[XI(pm)]; const cf zm = (cf){(float)zmh.x, (float)zmh.y};
;             const cf y = cmul(z, P) + cmul((cf){zm.x, -zm.y}, Mq);
;             const cf t = cmul((cf){zm.x, -zm.y}, P) + cmul(z, Mq);
;             X[XI(pp)] = (hc){(_Float16)y.x, (_Float16)y.y}; X[XI(pm)] = (hc){(_Float16)t.x, (_Float16)(-t.y)}; }
.LBB0_624:
	s_or_b64 exec, exec, s[22:23]
	v_add_u32_e32 v2, 0x2400, v9
	v_bfrev_b32_e32 v3, v2
	v_lshrrev_b32_e32 v4, 19, v3
	v_lshrrev_b32_e32 v3, 17, v3
	v_and_b32_e32 v3, 0x2aaa, v3
	v_and_or_b32 v10, v4, s89, v3
	s_movk_i32 s5, 0xdc00
	v_cmp_ne_u32_e32 vcc, s5, v9
	s_waitcnt vmcnt(5)
	v_mov_b32_e32 v4, v108
	v_mov_b32_e32 v5, v109
	v_mov_b32_e32 v6, v110
	v_mov_b32_e32 v7, v111
	v_pk_mul_f32 v[2:3], v[6:7], s[90:91] op_sel_hi:[1,0]
	v_lshl_add_u32 v6, v10, 2, 0
	v_lshrrev_b32_e32 v7, 2, v10
	v_lshrrev_b32_e32 v10, 6, v10
	v_and_b32_e32 v7, 0xffc, v7
	v_and_b32_e32 v10, 0xfc, v10
	v_add3_u32 v10, v6, v7, v10
	ds_read_b32 v7, v10
	v_pk_mul_f32 v[4:5], v[4:5], s[90:91] op_sel_hi:[1,0]
	s_waitcnt lgkmcnt(0)
	v_cvt_f32_f16_e32 v6, v7
	v_cvt_f32_f16_sdwa v7, v7 dst_sel:DWORD dst_unused:UNUSED_PAD src0_sel:WORD_1
	s_and_saveexec_b64 s[22:23], vcc
	s_xor_b64 s[22:23], exec, s[22:23]
	s_cbranch_execz .LBB0_626
	v_add_u32_e32 v11, 0xa00, v8
	v_bfrev_b32_e32 v11, v11
	v_lshrrev_b32_e32 v13, 19, v11
	v_lshrrev_b32_e32 v11, 17, v11
	v_and_b32_e32 v11, 0x2aaa, v11
	v_and_or_b32 v11, v13, s89, v11
	v_lshl_add_u32 v13, v11, 2, 0
	v_lshrrev_b32_e32 v16, 2, v11
	v_lshrrev_b32_e32 v11, 6, v11
	v_and_b32_e32 v16, 0xffc, v16
	v_and_b32_e32 v11, 0xfc, v11
	v_add3_u32 v11, v13, v16, v11
	ds_read_b32 v13, v11
	v_pk_mul_f32 v[18:19], v[6:7], v[4:5] op_sel:[0,0] op_sel_hi:[0,1]
	s_waitcnt lgkmcnt(0)
	v_cvt_f32_f16_e32 v16, v13
	v_cvt_f32_f16_sdwa v17, -v13 dst_sel:DWORD dst_unused:UNUSED_PAD src0_sel:WORD_1
	v_pk_mul_f32 v[22:23], v[16:17], v[2:3] op_sel:[0,0] op_sel_hi:[0,1]
	v_pk_fma_f32 v[18:19], v[6:7], v[4:5], v[18:19] op_sel:[1,1,0] op_sel_hi:[1,0,1] neg_lo:[0,1,0]
	v_pk_fma_f32 v[22:23], v[16:17], v[2:3], v[22:23] op_sel:[1,1,0] op_sel_hi:[1,0,1] neg_lo:[0,1,0]
	v_pk_add_f32 v[18:19], v[18:19], v[22:23]
	v_pk_mul_f32 v[22:23], v[16:17], v[4:5] op_sel:[0,0] op_sel_hi:[0,1]
	v_pk_fma_f32 v[4:5], v[16:17], v[4:5], v[22:23] op_sel:[1,1,0] op_sel_hi:[1,0,1] neg_lo:[0,1,0]
	v_pk_mul_f32 v[16:17], v[6:7], v[2:3] op_sel:[0,0] op_sel_hi:[0,1]
	v_pk_fma_f32 v[2:3], v[6:7], v[2:3], v[16:17] op_sel:[1,1,0] op_sel_hi:[1,0,1] neg_lo:[0,1,0]
	s_nop 0
	v_pk_add_f32 v[2:3], v[4:5], v[2:3]
	v_cvt_pk_f16_f32 v4, v18, v19
	v_cvt_pk_f16_f32 v2, v2, -v3
	ds_write_b32 v10, v4
	ds_write_b32 v11, v2

; DI int rev4(int pp) { const unsigned br = __brev((unsigned)pp) >> 18; return (int)(((br & 0x2AAAu) >> 1) | ((br & 0x1555u) << 1)); }
; DI void pw_h(LAS hc* X, const f32x4* spec, int tid) {
;     ...
;     for (int r = 0; r < 16; ++r) {
;         const int k = tid + NTHR * r; const int pp = rev4(k);
;         const f32x4 sp = spec[k]; const cf P = (cf){sp[0], sp[1]} * 256.0f, Mq = (cf){sp[2], sp[3]} * 256.0f;
;         const hc zh = X[XI(pp)]; const cf z = (cf){(float)zh.x, (float)zh.y};
;         if (k == 0) { const cf y = cmul(z, P) + cmul((cf){z.x, -z.y}, Mq); X[XI(pp)] = (hc){(_Float16)y.x, (_Float16)y.y}; }
;         else { const int pm = rev4(16384 - k); const hc zmh = X[XI(pm)]; const cf zm = (cf){(float)zmh.x, (float)zmh.y};
;             const cf y = cmul(z, P) + cmul((cf){zm.x, -zm.y}, Mq);
;             const cf t = cmul((cf){zm.x, -zm.y}, P) + cmul(z, Mq);
;             X[XI(pp)] = (hc){(_Float16)y.x, (_Float16)y.y}; X[XI(pm)] = (hc){(_Float16)t.x, (_Float16)(-t.y)}; }
.LBB0_628:
	s_or_b64 exec, exec, s[22:23]
	v_add_u32_e32 v2, 0x2600, v9
	v_bfrev_b32_e32 v3, v2
	v_lshrrev_b32_e32 v4, 19, v3
	v_lshrrev_b32_e32 v3, 17, v3
	v_and_b32_e32 v3, 0x2aaa, v3
	v_and_or_b32 v10, v4, s89, v3
	s_movk_i32 s5, 0xda00
	v_cmp_ne_u32_e32 vcc, s5, v9
	s_waitcnt vmcnt(4)
	v_mov_b32_e32 v4, v112
	v_mov_b32_e32 v5, v113
	v_mov_b32_e32 v6, v114
	v_mov_b32_e32 v7, v115
	v_pk_mul_f32 v[2:3], v[6:7], s[90:91] op_sel_hi:[1,0]
	v_lshl_add_u32 v6, v10, 2, 0
	v_lshrrev_b32_e32 v7, 2, v10
	v_lshrrev_b32_e32 v10, 6, v10
	v_and_b32_e32 v7, 0xffc, v7
	v_and_b32_e32 v10, 0xfc, v10
	v_add3_u32 v10, v6, v7, v10
	ds_read_b32 v7, v10
	v_pk_mul_f32 v[4:5], v[4:5], s[90:91] op_sel_hi:[1,0]
	s_waitcnt lgkmcnt(0)
	v_cvt_f32_f16_e32 v6, v7
	v_cvt_f32_f16_sdwa v7, v7 dst_sel:DWORD dst_unused:UNUSED_PAD src0_sel:WORD_1
	s_and_saveexec_b64 s[22:23], vcc
	s_xor_b64 s[22:23], exec, s[22:23]
	s_cbranch_execz .LBB0_630
	v_add_u32_e32 v11, 0x800, v8
	v_bfrev_b32_e32 v11, v11
	v_lshrrev_b32_e32 v13, 19, v11
	v_lshrrev_b32_e32 v11, 17, v11
	v_and_b32_e32 v11, 0x2aaa, v11
	v_and_or_b32 v11, v13, s89, v11
	v_lshl_add_u32 v13, v11, 2, 0
	v_lshrrev_b32_e32 v16, 2, v11
	v_lshrrev_b32_e32 v11, 6, v11
	v_and_b32_e32 v16, 0xffc, v16
	v_and_b32_e32 v11, 0xfc, v11
	v_add3_u32 v11, v13, v16, v11
	ds_read_b32 v13, v11
	v_pk_mul_f32 v[18:19], v[6:7], v[4:5] op_sel:[0,0] op_sel_hi:[0,1]
	s_waitcnt lgkmcnt(0)
	v_cvt_f32_f16_e32 v16, v13
	v_cvt_f32_f16_sdwa v17, -v13 dst_sel:DWORD dst_unused:UNUSED_PAD src0_sel:WORD_1
	v_pk_mul_f32 v[22:23], v[16:17], v[2:3] op_sel:[0,0] op_sel_hi:[0,1]
	v_pk_fma_f32 v[18:19], v[6:7], v[4:5], v[18:19] op_sel:[1,1,0] op_sel_hi:[1,0,1] neg_lo:[0,1,0]
	v_pk_fma_f32 v[22:23], v[16:17], v[2:3], v[22:23] op_sel:[1,1,0] op_sel_hi:[1,0,1] neg_lo:[0,1,0]
	v_pk_add_f32 v[18:19], v[18:19], v[22:23]
	v_pk_mul_f32 v[22:23], v[16:17], v[4:5] op_sel:[0,0] op_sel_hi:[0,1]
	v_pk_fma_f32 v[4:5], v[16:17], v[4:5], v[22:23] op_sel:[1,1,0] op_sel_hi:[1,0,1] neg_lo:[0,1,0]
	v_pk_mul_f32 v[16:17], v[6:7], v[2:3] op_sel:[0,0] op_sel_hi:[0,1]
	v_pk_fma_f32 v[2:3], v[6:7], v[2:3], v[16:17] op_sel:[1,1,0] op_sel_hi:[1,0,1] neg_lo:[0,1,0]
	s_nop 0
	v_pk_add_f32 v[2:3], v[4:5], v[2:3]
	v_cvt_pk_f16_f32 v4, v18, v19
	v_cvt_pk_f16_f32 v2, v2, -v3
	ds_write_b32 v10, v4
	ds_write_b32 v11, v2

; DI int rev4(int pp) { const unsigned br = __brev((unsigned)pp) >> 18; return (int)(((br & 0x2AAAu) >> 1) | ((br & 0x1555u) << 1)); }
; DI void pw_h(LAS hc* X, const f32x4* spec, int tid) {
;     ...
;     for (int r = 0; r < 16; ++r) {
;         const int k = tid + NTHR * r; const int pp = rev4(k);
;         const f32x4 sp = spec[k]; const cf P = (cf){sp[0], sp[1]} * 256.0f, Mq = (cf){sp[2], sp[3]} * 256.0f;
;         const hc zh = X[XI(pp)]; const cf z = (cf){(float)zh.x, (float)zh.y};
;         if (k == 0) { const cf y = cmul(z, P) + cmul((cf){z.x, -z.y}, Mq); X[XI(pp)] = (hc){(_Float16)y.x, (_Float16)y.y}; }
;         else { const int pm = rev4(16384 - k); const hc zmh = X[XI(pm)]; const cf zm = (cf){(float)zmh.x, (float)zmh.y};
;             const cf y = cmul(z, P) + cmul((cf){zm.x, -zm.y}, Mq);
;             const cf t = cmul((cf){zm.x, -zm.y}, P) + cmul(z, Mq);
;             X[XI(pp)] = (hc){(_Float16)y.x, (_Float16)y.y}; X[XI(pm)] = (hc){(_Float16)t.x, (_Float16)(-t.y)}; }
.LBB0_632:
	s_or_b64 exec, exec, s[22:23]
	v_add_u32_e32 v2, 0x2800, v9
	v_bfrev_b32_e32 v3, v2
	v_lshrrev_b32_e32 v4, 19, v3
	v_lshrrev_b32_e32 v3, 17, v3
	v_and_b32_e32 v3, 0x2aaa, v3
	v_and_or_b32 v10, v4, s89, v3
	s_movk_i32 s5, 0xd800
	v_cmp_ne_u32_e32 vcc, s5, v9
	s_waitcnt vmcnt(3)
	v_mov_b32_e32 v4, v116
	v_mov_b32_e32 v5, v117
	v_mov_b32_e32 v6, v118
	v_mov_b32_e32 v7, v119
	v_pk_mul_f32 v[2:3], v[6:7], s[90:91] op_sel_hi:[1,0]
	v_lshl_add_u32 v6, v10, 2, 0
	v_lshrrev_b32_e32 v7, 2, v10
	v_lshrrev_b32_e32 v10, 6, v10
	v_and_b32_e32 v7, 0xffc, v7
	v_and_b32_e32 v10, 0xfc, v10
	v_add3_u32 v10, v6, v7, v10
	ds_read_b32 v7, v10
	v_pk_mul_f32 v[4:5], v[4:5], s[90:91] op_sel_hi:[1,0]
	s_waitcnt lgkmcnt(0)
	v_cvt_f32_f16_e32 v6, v7
	v_cvt_f32_f16_sdwa v7, v7 dst_sel:DWORD dst_unused:UNUSED_PAD src0_sel:WORD_1
	s_and_saveexec_b64 s[22:23], vcc
	s_xor_b64 s[22:23], exec, s[22:23]
	s_cbranch_execz .LBB0_634
	v_add_u32_e32 v11, 0x600, v8
	v_bfrev_b32_e32 v11, v11
	v_lshrrev_b32_e32 v13, 19, v11
	v_lshrrev_b32_e32 v11, 17, v11
	v_and_b32_e32 v11, 0x2aaa, v11
	v_and_or_b32 v11, v13, s89, v11
	v_lshl_add_u32 v13, v11, 2, 0
	v_lshrrev_b32_e32 v16, 2, v11
	v_lshrrev_b32_e32 v11, 6, v11
	v_and_b32_e32 v16, 0xffc, v16
	v_and_b32_e32 v11, 0xfc, v11
	v_add3_u32 v11, v13, v16, v11
	ds_read_b32 v13, v11
	v_pk_mul_f32 v[18:19], v[6:7], v[4:5] op_sel:[0,0] op_sel_hi:[0,1]
	s_waitcnt lgkmcnt(0)
	v_cvt_f32_f16_e32 v16, v13
	v_cvt_f32_f16_sdwa v17, -v13 dst_sel:DWORD dst_unused:UNUSED_PAD src0_sel:WORD_1
	v_pk_mul_f32 v[22:23], v[16:17], v[2:3] op_sel:[0,0] op_sel_hi:[0,1]
	v_pk_fma_f32 v[18:19], v[6:7], v[4:5], v[18:19] op_sel:[1,1,0] op_sel_hi:[1,0,1] neg_lo:[0,1,0]
	v_pk_fma_f32 v[22:23], v[16:17], v[2:3], v[22:23] op_sel:[1,1,0] op_sel_hi:[1,0,1] neg_lo:[0,1,0]
	v_pk_add_f32 v[18:19], v[18:19], v[22:23]
	v_pk_mul_f32 v[22:23], v[16:17], v[4:5] op_sel:[0,0] op_sel_hi:[0,1]
	v_pk_fma_f32 v[4:5], v[16:17], v[4:5], v[22:23] op_sel:[1,1,0] op_sel_hi:[1,0,1] neg_lo:[0,1,0]
	v_pk_mul_f32 v[16:17], v[6:7], v[2:3] op_sel:[0,0] op_sel_hi:[0,1]
	v_pk_fma_f32 v[2:3], v[6:7], v[2:3], v[16:17] op_sel:[1,1,0] op_sel_hi:[1,0,1] neg_lo:[0,1,0]
	s_nop 0
	v_pk_add_f32 v[2:3], v[4:5], v[2:3]
	v_cvt_pk_f16_f32 v4, v18, v19
	v_cvt_pk_f16_f32 v2, v2, -v3
	ds_write_b32 v10, v4
	ds_write_b32 v11, v2

; DI int rev4(int pp) { const unsigned br = __brev((unsigned)pp) >> 18; return (int)(((br & 0x2AAAu) >> 1) | ((br & 0x1555u) << 1)); }
; DI void pw_h(LAS hc* X, const f32x4* spec, int tid) {
;     ...
;     for (int r = 0; r < 16; ++r) {
;         const int k = tid + NTHR * r; const int pp = rev4(k);
;         const f32x4 sp = spec[k]; const cf P = (cf){sp[0], sp[1]} * 256.0f, Mq = (cf){sp[2], sp[3]} * 256.0f;
;         const hc zh = X[XI(pp)]; const cf z = (cf){(float)zh.x, (float)zh.y};
;         if (k == 0) { const cf y = cmul(z, P) + cmul((cf){z.x, -z.y}, Mq); X[XI(pp)] = (hc){(_Float16)y.x, (_Float16)y.y}; }
;         else { const int pm = rev4(16384 - k); const hc zmh = X[XI(pm)]; const cf zm = (cf){(float)zmh.x, (float)zmh.y};
;             const cf y = cmul(z, P) + cmul((cf){zm.x, -zm.y}, Mq);
;             const cf t = cmul((cf){zm.x, -zm.y}, P) + cmul(z, Mq);
;             X[XI(pp)] = (hc){(_Float16)y.x, (_Float16)y.y}; X[XI(pm)] = (hc){(_Float16)t.x, (_Float16)(-t.y)}; }
.LBB0_636:
	s_or_b64 exec, exec, s[22:23]
	v_add_u32_e32 v2, 0x2a00, v9
	v_bfrev_b32_e32 v3, v2
	v_lshrrev_b32_e32 v4, 19, v3
	v_lshrrev_b32_e32 v3, 17, v3
	v_and_b32_e32 v3, 0x2aaa, v3
	v_and_or_b32 v10, v4, s89, v3
	s_movk_i32 s5, 0xd600
	v_cmp_ne_u32_e32 vcc, s5, v9
	s_waitcnt vmcnt(2)
	v_mov_b32_e32 v4, v120
	v_mov_b32_e32 v5, v121
	v_mov_b32_e32 v6, v122
	v_mov_b32_e32 v7, v123
	v_pk_mul_f32 v[2:3], v[6:7], s[90:91] op_sel_hi:[1,0]
	v_lshl_add_u32 v6, v10, 2, 0
	v_lshrrev_b32_e32 v7, 2, v10
	v_lshrrev_b32_e32 v10, 6, v10
	v_and_b32_e32 v7, 0xffc, v7
	v_and_b32_e32 v10, 0xfc, v10
	v_add3_u32 v10, v6, v7, v10
	ds_read_b32 v7, v10
	v_pk_mul_f32 v[4:5], v[4:5], s[90:91] op_sel_hi:[1,0]
	s_waitcnt lgkmcnt(0)
	v_cvt_f32_f16_e32 v6, v7
	v_cvt_f32_f16_sdwa v7, v7 dst_sel:DWORD dst_unused:UNUSED_PAD src0_sel:WORD_1
	s_and_saveexec_b64 s[22:23], vcc
	s_xor_b64 s[22:23], exec, s[22:23]
	s_cbranch_execz .LBB0_638
	v_add_u32_e32 v11, 0x400, v8
	v_bfrev_b32_e32 v11, v11
	v_lshrrev_b32_e32 v13, 19, v11
	v_lshrrev_b32_e32 v11, 17, v11
	v_and_b32_e32 v11, 0x2aaa, v11
	v_and_or_b32 v11, v13, s89, v11
	v_lshl_add_u32 v13, v11, 2, 0
	v_lshrrev_b32_e32 v16, 2, v11
	v_lshrrev_b32_e32 v11, 6, v11
	v_and_b32_e32 v16, 0xffc, v16
	v_and_b32_e32 v11, 0xfc, v11
	v_add3_u32 v11, v13, v16, v11
	ds_read_b32 v13, v11
	v_pk_mul_f32 v[18:19], v[6:7], v[4:5] op_sel:[0,0] op_sel_hi:[0,1]
	s_waitcnt lgkmcnt(0)
	v_cvt_f32_f16_e32 v16, v13
	v_cvt_f32_f16_sdwa v17, -v13 dst_sel:DWORD dst_unused:UNUSED_PAD src0_sel:WORD_1
	v_pk_mul_f32 v[22:23], v[16:17], v[2:3] op_sel:[0,0] op_sel_hi:[0,1]
	v_pk_fma_f32 v[18:19], v[6:7], v[4:5], v[18:19] op_sel:[1,1,0] op_sel_hi:[1,0,1] neg_lo:[0,1,0]
	v_pk_fma_f32 v[22:23], v[16:17], v[2:3], v[22:23] op_sel:[1,1,0] op_sel_hi:[1,0,1] neg_lo:[0,1,0]
	v_pk_add_f32 v[18:19], v[18:19], v[22:23]
	v_pk_mul_f32 v[22:23], v[16:17], v[4:5] op_sel:[0,0] op_sel_hi:[0,1]
	v_pk_fma_f32 v[4:5], v[16:17], v[4:5], v[22:23] op_sel:[1,1,0] op_sel_hi:[1,0,1] neg_lo:[0,1,0]
	v_pk_mul_f32 v[16:17], v[6:7], v[2:3] op_sel:[0,0] op_sel_hi:[0,1]
	v_pk_fma_f32 v[2:3], v[6:7], v[2:3], v[16:17] op_sel:[1,1,0] op_sel_hi:[1,0,1] neg_lo:[0,1,0]
	s_nop 0
	v_pk_add_f32 v[2:3], v[4:5], v[2:3]
	v_cvt_pk_f16_f32 v4, v18, v19
	v_cvt_pk_f16_f32 v2, v2, -v3
	ds_write_b32 v10, v4
	ds_write_b32 v11, v2

; DI int rev4(int pp) { const unsigned br = __brev((unsigned)pp) >> 18; return (int)(((br & 0x2AAAu) >> 1) | ((br & 0x1555u) << 1)); }
; DI void pw_h(LAS hc* X, const f32x4* spec, int tid) {
;     ...
;     for (int r = 0; r < 16; ++r) {
;         const int k = tid + NTHR * r; const int pp = rev4(k);
;         const f32x4 sp = spec[k]; const cf P = (cf){sp[0], sp[1]} * 256.0f, Mq = (cf){sp[2], sp[3]} * 256.0f;
;         const hc zh = X[XI(pp)]; const cf z = (cf){(float)zh.x, (float)zh.y};
;         if (k == 0) { const cf y = cmul(z, P) + cmul((cf){z.x, -z.y}, Mq); X[XI(pp)] = (hc){(_Float16)y.x, (_Float16)y.y}; }
;         else { const int pm = rev4(16384 - k); const hc zmh = X[XI(pm)]; const cf zm = (cf){(float)zmh.x, (float)zmh.y};
;             const cf y = cmul(z, P) + cmul((cf){zm.x, -zm.y}, Mq);
;             const cf t = cmul((cf){zm.x, -zm.y}, P) + cmul(z, Mq);
;             X[XI(pp)] = (hc){(_Float16)y.x, (_Float16)y.y}; X[XI(pm)] = (hc){(_Float16)t.x, (_Float16)(-t.y)}; }
.LBB0_640:
	s_or_b64 exec, exec, s[22:23]
	v_add_u32_e32 v2, 0x2c00, v9
	v_bfrev_b32_e32 v3, v2
	v_lshrrev_b32_e32 v4, 19, v3
	v_lshrrev_b32_e32 v3, 17, v3
	v_and_b32_e32 v3, 0x2aaa, v3
	v_and_or_b32 v10, v4, s89, v3
	v_cmp_ne_u32_e32 vcc, s96, v9
	s_waitcnt vmcnt(1)
	v_mov_b32_e32 v4, v124
	v_mov_b32_e32 v5, v125
	v_mov_b32_e32 v6, v126
	v_mov_b32_e32 v7, v127
	v_pk_mul_f32 v[2:3], v[6:7], s[90:91] op_sel_hi:[1,0]
	v_lshl_add_u32 v6, v10, 2, 0
	v_lshrrev_b32_e32 v7, 2, v10
	v_lshrrev_b32_e32 v10, 6, v10
	v_and_b32_e32 v7, 0xffc, v7
	v_and_b32_e32 v10, 0xfc, v10
	v_add3_u32 v10, v6, v7, v10
	ds_read_b32 v7, v10
	v_pk_mul_f32 v[4:5], v[4:5], s[90:91] op_sel_hi:[1,0]
	s_waitcnt lgkmcnt(0)
	v_cvt_f32_f16_e32 v6, v7
	v_cvt_f32_f16_sdwa v7, v7 dst_sel:DWORD dst_unused:UNUSED_PAD src0_sel:WORD_1
	s_and_saveexec_b64 s[22:23], vcc
	s_xor_b64 s[22:23], exec, s[22:23]
	s_cbranch_execz .LBB0_642
	v_add_u32_e32 v11, 0x200, v8
	v_bfrev_b32_e32 v11, v11
	v_lshrrev_b32_e32 v13, 19, v11
	v_lshrrev_b32_e32 v11, 17, v11
	v_and_b32_e32 v11, 0x2aaa, v11
	v_and_or_b32 v11, v13, s89, v11
	v_lshl_add_u32 v13, v11, 2, 0
	v_lshrrev_b32_e32 v16, 2, v11
	v_lshrrev_b32_e32 v11, 6, v11
	v_and_b32_e32 v16, 0xffc, v16
	v_and_b32_e32 v11, 0xfc, v11
	v_add3_u32 v11, v13, v16, v11
	ds_read_b32 v13, v11
	v_pk_mul_f32 v[18:19], v[6:7], v[4:5] op_sel:[0,0] op_sel_hi:[0,1]
	s_waitcnt lgkmcnt(0)
	v_cvt_f32_f16_e32 v16, v13
	v_cvt_f32_f16_sdwa v17, -v13 dst_sel:DWORD dst_unused:UNUSED_PAD src0_sel:WORD_1
	v_pk_mul_f32 v[22:23], v[16:17], v[2:3] op_sel:[0,0] op_sel_hi:[0,1]
	v_pk_fma_f32 v[18:19], v[6:7], v[4:5], v[18:19] op_sel:[1,1,0] op_sel_hi:[1,0,1] neg_lo:[0,1,0]
	v_pk_fma_f32 v[22:23], v[16:17], v[2:3], v[22:23] op_sel:[1,1,0] op_sel_hi:[1,0,1] neg_lo:[0,1,0]
	v_pk_add_f32 v[18:19], v[18:19], v[22:23]
	v_pk_mul_f32 v[22:23], v[16:17], v[4:5] op_sel:[0,0] op_sel_hi:[0,1]
	v_pk_fma_f32 v[4:5], v[16:17], v[4:5], v[22:23] op_sel:[1,1,0] op_sel_hi:[1,0,1] neg_lo:[0,1,0]
	v_pk_mul_f32 v[16:17], v[6:7], v[2:3] op_sel:[0,0] op_sel_hi:[0,1]
	v_pk_fma_f32 v[2:3], v[6:7], v[2:3], v[16:17] op_sel:[1,1,0] op_sel_hi:[1,0,1] neg_lo:[0,1,0]
	s_nop 0
	v_pk_add_f32 v[2:3], v[4:5], v[2:3]
	v_cvt_pk_f16_f32 v4, v18, v19
	v_cvt_pk_f16_f32 v2, v2, -v3
	ds_write_b32 v10, v4
	ds_write_b32 v11, v2

; DI int rev4(int pp) { const unsigned br = __brev((unsigned)pp) >> 18; return (int)(((br & 0x2AAAu) >> 1) | ((br & 0x1555u) << 1)); }
; DI void pw_h(LAS hc* X, const f32x4* spec, int tid) {
;     ...
;     for (int r = 0; r < 16; ++r) {
;         const int k = tid + NTHR * r; const int pp = rev4(k);
;         const f32x4 sp = spec[k]; const cf P = (cf){sp[0], sp[1]} * 256.0f, Mq = (cf){sp[2], sp[3]} * 256.0f;
;         const hc zh = X[XI(pp)]; const cf z = (cf){(float)zh.x, (float)zh.y};
;         if (k == 0) { const cf y = cmul(z, P) + cmul((cf){z.x, -z.y}, Mq); X[XI(pp)] = (hc){(_Float16)y.x, (_Float16)y.y}; }
;         else { const int pm = rev4(16384 - k); const hc zmh = X[XI(pm)]; const cf zm = (cf){(float)zmh.x, (float)zmh.y};
;             const cf y = cmul(z, P) + cmul((cf){zm.x, -zm.y}, Mq);
;             const cf t = cmul((cf){zm.x, -zm.y}, P) + cmul(z, Mq);
;             X[XI(pp)] = (hc){(_Float16)y.x, (_Float16)y.y}; X[XI(pm)] = (hc){(_Float16)t.x, (_Float16)(-t.y)}; }
.LBB0_644:
	s_or_b64 exec, exec, s[22:23]
	v_add_u32_e32 v2, 0x2e00, v9
	v_bfrev_b32_e32 v3, v2
	v_lshrrev_b32_e32 v4, 19, v3
	v_lshrrev_b32_e32 v3, 17, v3
	v_and_b32_e32 v3, 0x2aaa, v3
	v_and_or_b32 v10, v4, s89, v3
	v_cmp_ne_u32_e32 vcc, s84, v9
	s_waitcnt vmcnt(0)
	v_mov_b32_e32 v4, v128
	v_mov_b32_e32 v5, v129
	v_mov_b32_e32 v6, v130
	v_mov_b32_e32 v7, v131
	v_pk_mul_f32 v[2:3], v[6:7], s[90:91] op_sel_hi:[1,0]
	v_lshl_add_u32 v6, v10, 2, 0
	v_lshrrev_b32_e32 v7, 2, v10
	v_lshrrev_b32_e32 v10, 6, v10
	v_and_b32_e32 v7, 0xffc, v7
	v_and_b32_e32 v10, 0xfc, v10
	v_add3_u32 v10, v6, v7, v10
	ds_read_b32 v7, v10
	v_pk_mul_f32 v[4:5], v[4:5], s[90:91] op_sel_hi:[1,0]
	s_waitcnt lgkmcnt(0)
	v_cvt_f32_f16_e32 v6, v7
	v_cvt_f32_f16_sdwa v7, v7 dst_sel:DWORD dst_unused:UNUSED_PAD src0_sel:WORD_1
	s_and_saveexec_b64 s[22:23], vcc
	s_xor_b64 s[22:23], exec, s[22:23]
	s_cbranch_execz .LBB0_646
	v_bfrev_b32_e32 v9, v8
	v_lshrrev_b32_e32 v11, 19, v9
	v_lshrrev_b32_e32 v9, 17, v9
	v_and_b32_e32 v9, 0x2aaa, v9
	v_and_or_b32 v9, v11, s89, v9
	v_lshl_add_u32 v11, v9, 2, 0
	v_lshrrev_b32_e32 v13, 2, v9
	v_lshrrev_b32_e32 v9, 6, v9
	v_and_b32_e32 v13, 0xffc, v13
	v_and_b32_e32 v9, 0xfc, v9
	v_add3_u32 v9, v11, v13, v9
	ds_read_b32 v11, v9
	v_pk_mul_f32 v[18:19], v[6:7], v[4:5] op_sel:[0,0] op_sel_hi:[0,1]
	s_waitcnt lgkmcnt(0)
	v_cvt_f32_f16_e32 v16, v11
	v_cvt_f32_f16_sdwa v17, -v11 dst_sel:DWORD dst_unused:UNUSED_PAD src0_sel:WORD_1
	v_pk_mul_f32 v[22:23], v[16:17], v[2:3] op_sel:[0,0] op_sel_hi:[0,1]
	v_pk_fma_f32 v[18:19], v[6:7], v[4:5], v[18:19] op_sel:[1,1,0] op_sel_hi:[1,0,1] neg_lo:[0,1,0]
	v_pk_fma_f32 v[22:23], v[16:17], v[2:3], v[22:23] op_sel:[1,1,0] op_sel_hi:[1,0,1] neg_lo:[0,1,0]
	v_pk_add_f32 v[18:19], v[18:19], v[22:23]
	v_pk_mul_f32 v[22:23], v[16:17], v[4:5] op_sel:[0,0] op_sel_hi:[0,1]
	v_pk_fma_f32 v[4:5], v[16:17], v[4:5], v[22:23] op_sel:[1,1,0] op_sel_hi:[1,0,1] neg_lo:[0,1,0]
	v_pk_mul_f32 v[16:17], v[6:7], v[2:3] op_sel:[0,0] op_sel_hi:[0,1]
	v_pk_fma_f32 v[2:3], v[6:7], v[2:3], v[16:17] op_sel:[1,1,0] op_sel_hi:[1,0,1] neg_lo:[0,1,0]
	s_nop 0
	v_pk_add_f32 v[2:3], v[4:5], v[2:3]
	v_cvt_pk_f16_f32 v4, v18, v19
	v_cvt_pk_f16_f32 v2, v2, -v3
	ds_write_b32 v10, v4
	ds_write_b32 v9, v2

; #define LAS __attribute__((address_space(3)))
; DI int rev4(int pp) { const unsigned br = __brev((unsigned)pp) >> 18; return (int)(((br & 0x2AAAu) >> 1) | ((br & 0x1555u) << 1)); }
; DI void pw_h(LAS hc* X, const f32x4* spec, int tid) {
; #pragma unroll 8
;     for (int r = 0; r < 16; ++r) {
;         const int k = tid + NTHR * r; const int pp = rev4(k);
;         const f32x4 sp = spec[k]; const cf P = (cf){sp[0], sp[1]} * 256.0f, Mq = (cf){sp[2], sp[3]} * 256.0f;
;         const hc zh = X[XI(pp)]; const cf z = (cf){(float)zh.x, (float)zh.y};
;         if (k == 0) { const cf y = cmul(z, P) + cmul((cf){z.x, -z.y}, Mq); X[XI(pp)] = (hc){(_Float16)y.x, (_Float16)y.y}; }
;         else { const int pm = rev4(16384 - k); const hc zmh = X[XI(pm)]; const cf zm = (cf){(float)zmh.x, (float)zmh.y};
;             const cf y = cmul(z, P) + cmul((cf){zm.x, -zm.y}, Mq);
;             const cf t = cmul((cf){zm.x, -zm.y}, P) + cmul(z, Mq);
;             X[XI(pp)] = (hc){(_Float16)y.x, (_Float16)y.y}; X[XI(pm)] = (hc){(_Float16)t.x, (_Float16)(-t.y)}; }
.LBB0_652:
	global_load_dwordx4 v[4:7], v[0:1], off
	v_add_u32_e32 v9, s4, v12
	v_add_u32_e32 v2, 0x2000, v9
	v_bfrev_b32_e32 v2, v2
	v_lshrrev_b32_e32 v3, 19, v2
	v_lshrrev_b32_e32 v2, 17, v2
	v_and_b32_e32 v2, 0x2aaa, v2
	v_and_or_b32 v10, v3, s89, v2
	s_movk_i32 s5, 0xe000
	v_cmp_ne_u32_e64 s[40:41], s5, v9
	v_add_u32_e32 v100, 0x2200, v9
	v_ashrrev_i32_e32 v101, 31, v100
	v_lshl_add_u64 v[100:101], v[100:101], 4, s[20:21]
	global_load_dwordx4 v[104:107], v[100:101], off
	v_add_u32_e32 v100, 0x2400, v9
	v_ashrrev_i32_e32 v101, 31, v100
	v_lshl_add_u64 v[100:101], v[100:101], 4, s[20:21]
	global_load_dwordx4 v[108:111], v[100:101], off
	v_add_u32_e32 v100, 0x2600, v9
	v_ashrrev_i32_e32 v101, 31, v100
	v_lshl_add_u64 v[100:101], v[100:101], 4, s[20:21]
	global_load_dwordx4 v[112:115], v[100:101], off
	v_add_u32_e32 v100, 0x2800, v9
	v_ashrrev_i32_e32 v101, 31, v100
	v_lshl_add_u64 v[100:101], v[100:101], 4, s[20:21]
	global_load_dwordx4 v[116:119], v[100:101], off
	v_add_u32_e32 v100, 0x2a00, v9
	v_ashrrev_i32_e32 v101, 31, v100
	v_lshl_add_u64 v[100:101], v[100:101], 4, s[20:21]
	global_load_dwordx4 v[120:123], v[100:101], off
	v_add_u32_e32 v100, 0x2c00, v9
	v_ashrrev_i32_e32 v101, 31, v100
	v_lshl_add_u64 v[100:101], v[100:101], 4, s[20:21]
	global_load_dwordx4 v[124:127], v[100:101], off
	v_add_u32_e32 v100, 0x2e00, v9
	v_ashrrev_i32_e32 v101, 31, v100
	v_lshl_add_u64 v[100:101], v[100:101], 4, s[20:21]
	global_load_dwordx4 v[128:131], v[100:101], off
	s_waitcnt vmcnt(7)
	v_pk_mul_f32 v[2:3], v[6:7], s[90:91] op_sel_hi:[1,0]
	v_lshl_add_u32 v6, v10, 2, s66
	v_lshrrev_b32_e32 v7, 2, v10
	v_lshrrev_b32_e32 v10, 6, v10
	v_and_b32_e32 v7, 0xffc, v7
	v_and_b32_e32 v10, 0xfc, v10
	v_add3_u32 v10, v6, v7, v10
	ds_read_b32 v7, v10
	v_pk_mul_f32 v[4:5], v[4:5], s[90:91] op_sel_hi:[1,0]
	s_waitcnt lgkmcnt(0)
	v_cvt_f32_f16_e32 v6, v7
	v_cvt_f32_f16_sdwa v7, v7 dst_sel:DWORD dst_unused:UNUSED_PAD src0_sel:WORD_1
	s_and_saveexec_b64 s[22:23], s[40:41]
	s_xor_b64 s[22:23], exec, s[22:23]
	s_cbranch_execz .LBB0_654
	v_add_u32_e32 v11, 0xe00, v8
	v_bfrev_b32_e32 v11, v11
	v_lshrrev_b32_e32 v13, 19, v11
	v_lshrrev_b32_e32 v11, 17, v11
	v_and_b32_e32 v11, 0x2aaa, v11
	v_and_or_b32 v11, v13, s89, v11
	v_lshl_add_u32 v13, v11, 2, s66
	v_lshrrev_b32_e32 v16, 2, v11
	v_lshrrev_b32_e32 v11, 6, v11
	v_and_b32_e32 v16, 0xffc, v16
	v_and_b32_e32 v11, 0xfc, v11
	v_add3_u32 v11, v13, v16, v11
	ds_read_b32 v13, v11
	v_pk_mul_f32 v[18:19], v[6:7], v[4:5] op_sel:[0,0] op_sel_hi:[0,1]
	s_waitcnt lgkmcnt(0)
	v_cvt_f32_f16_e32 v16, v13
	v_cvt_f32_f16_sdwa v17, -v13 dst_sel:DWORD dst_unused:UNUSED_PAD src0_sel:WORD_1
	v_pk_mul_f32 v[22:23], v[16:17], v[2:3] op_sel:[0,0] op_sel_hi:[0,1]
	v_pk_fma_f32 v[18:19], v[6:7], v[4:5], v[18:19] op_sel:[1,1,0] op_sel_hi:[1,0,1] neg_lo:[0,1,0]
	v_pk_fma_f32 v[22:23], v[16:17], v[2:3], v[22:23] op_sel:[1,1,0] op_sel_hi:[1,0,1] neg_lo:[0,1,0]
	v_pk_add_f32 v[18:19], v[18:19], v[22:23]
	v_pk_mul_f32 v[22:23], v[16:17], v[4:5] op_sel:[0,0] op_sel_hi:[0,1]
	v_pk_fma_f32 v[4:5], v[16:17], v[4:5], v[22:23] op_sel:[1,1,0] op_sel_hi:[1,0,1] neg_lo:[0,1,0]
	v_pk_mul_f32 v[16:17], v[6:7], v[2:3] op_sel:[0,0] op_sel_hi:[0,1]
	v_pk_fma_f32 v[2:3], v[6:7], v[2:3], v[16:17] op_sel:[1,1,0] op_sel_hi:[1,0,1] neg_lo:[0,1,0]
	s_nop 0
	v_pk_add_f32 v[2:3], v[4:5], v[2:3]
	v_cvt_pk_f16_f32 v4, v18, v19
	v_cvt_pk_f16_f32 v2, v2, -v3
	ds_write_b32 v10, v4
	ds_write_b32 v11, v2

; DI int rev4(int pp) { const unsigned br = __brev((unsigned)pp) >> 18; return (int)(((br & 0x2AAAu) >> 1) | ((br & 0x1555u) << 1)); }
; DI void pw_h(LAS hc* X, const f32x4* spec, int tid) {
;     ...
;     for (int r = 0; r < 16; ++r) {
;         const int k = tid + NTHR * r; const int pp = rev4(k);
;         const f32x4 sp = spec[k]; const cf P = (cf){sp[0], sp[1]} * 256.0f, Mq = (cf){sp[2], sp[3]} * 256.0f;
;         const hc zh = X[XI(pp)]; const cf z = (cf){(float)zh.x, (float)zh.y};
;         if (k == 0) { const cf y = cmul(z, P) + cmul((cf){z.x, -z.y}, Mq); X[XI(pp)] = (hc){(_Float16)y.x, (_Float16)y.y}; }
;         else { const int pm = rev4(16384 - k); const hc zmh = X[XI(pm)]; const cf zm = (cf){(float)zmh.x, (float)zmh.y};
;             const cf y = cmul(z, P) + cmul((cf){zm.x, -zm.y}, Mq);
;             const cf t = cmul((cf){zm.x, -zm.y}, P) + cmul(z, Mq);
;             X[XI(pp)] = (hc){(_Float16)y.x, (_Float16)y.y}; X[XI(pm)] = (hc){(_Float16)t.x, (_Float16)(-t.y)}; }
.LBB0_656:
	s_or_b64 exec, exec, s[22:23]
	v_add_u32_e32 v2, 0x2200, v9
	v_bfrev_b32_e32 v3, v2
	v_lshrrev_b32_e32 v4, 19, v3
	v_lshrrev_b32_e32 v3, 17, v3
	v_and_b32_e32 v3, 0x2aaa, v3
	v_and_or_b32 v10, v4, s89, v3
	s_movk_i32 s5, 0xde00
	v_cmp_ne_u32_e64 s[40:41], s5, v9
	s_waitcnt vmcnt(6)
	v_mov_b32_e32 v4, v104
	v_mov_b32_e32 v5, v105
	v_mov_b32_e32 v6, v106
	v_mov_b32_e32 v7, v107
	v_pk_mul_f32 v[2:3], v[6:7], s[90:91] op_sel_hi:[1,0]
	v_lshl_add_u32 v6, v10, 2, s66
	v_lshrrev_b32_e32 v7, 2, v10
	v_lshrrev_b32_e32 v10, 6, v10
	v_and_b32_e32 v7, 0xffc, v7
	v_and_b32_e32 v10, 0xfc, v10
	v_add3_u32 v10, v6, v7, v10
	ds_read_b32 v7, v10
	v_pk_mul_f32 v[4:5], v[4:5], s[90:91] op_sel_hi:[1,0]
	s_waitcnt lgkmcnt(0)
	v_cvt_f32_f16_e32 v6, v7
	v_cvt_f32_f16_sdwa v7, v7 dst_sel:DWORD dst_unused:UNUSED_PAD src0_sel:WORD_1
	s_and_saveexec_b64 s[22:23], s[40:41]
	s_xor_b64 s[22:23], exec, s[22:23]
	s_cbranch_execz .LBB0_658
	v_add_u32_e32 v11, 0xc00, v8
	v_bfrev_b32_e32 v11, v11
	v_lshrrev_b32_e32 v13, 19, v11
	v_lshrrev_b32_e32 v11, 17, v11
	v_and_b32_e32 v11, 0x2aaa, v11
	v_and_or_b32 v11, v13, s89, v11
	v_lshl_add_u32 v13, v11, 2, s66
	v_lshrrev_b32_e32 v16, 2, v11
	v_lshrrev_b32_e32 v11, 6, v11
	v_and_b32_e32 v16, 0xffc, v16
	v_and_b32_e32 v11, 0xfc, v11
	v_add3_u32 v11, v13, v16, v11
	ds_read_b32 v13, v11
	v_pk_mul_f32 v[18:19], v[6:7], v[4:5] op_sel:[0,0] op_sel_hi:[0,1]
	s_waitcnt lgkmcnt(0)
	v_cvt_f32_f16_e32 v16, v13
	v_cvt_f32_f16_sdwa v17, -v13 dst_sel:DWORD dst_unused:UNUSED_PAD src0_sel:WORD_1
	v_pk_mul_f32 v[22:23], v[16:17], v[2:3] op_sel:[0,0] op_sel_hi:[0,1]
	v_pk_fma_f32 v[18:19], v[6:7], v[4:5], v[18:19] op_sel:[1,1,0] op_sel_hi:[1,0,1] neg_lo:[0,1,0]
	v_pk_fma_f32 v[22:23], v[16:17], v[2:3], v[22:23] op_sel:[1,1,0] op_sel_hi:[1,0,1] neg_lo:[0,1,0]
	v_pk_add_f32 v[18:19], v[18:19], v[22:23]
	v_pk_mul_f32 v[22:23], v[16:17], v[4:5] op_sel:[0,0] op_sel_hi:[0,1]
	v_pk_fma_f32 v[4:5], v[16:17], v[4:5], v[22:23] op_sel:[1,1,0] op_sel_hi:[1,0,1] neg_lo:[0,1,0]
	v_pk_mul_f32 v[16:17], v[6:7], v[2:3] op_sel:[0,0] op_sel_hi:[0,1]
	v_pk_fma_f32 v[2:3], v[6:7], v[2:3], v[16:17] op_sel:[1,1,0] op_sel_hi:[1,0,1] neg_lo:[0,1,0]
	s_nop 0
	v_pk_add_f32 v[2:3], v[4:5], v[2:3]
	v_cvt_pk_f16_f32 v4, v18, v19
	v_cvt_pk_f16_f32 v2, v2, -v3
	ds_write_b32 v10, v4
	ds_write_b32 v11, v2

; DI int rev4(int pp) { const unsigned br = __brev((unsigned)pp) >> 18; return (int)(((br & 0x2AAAu) >> 1) | ((br & 0x1555u) << 1)); }
; DI void pw_h(LAS hc* X, const f32x4* spec, int tid) {
;     ...
;     for (int r = 0; r < 16; ++r) {
;         const int k = tid + NTHR * r; const int pp = rev4(k);
;         const f32x4 sp = spec[k]; const cf P = (cf){sp[0], sp[1]} * 256.0f, Mq = (cf){sp[2], sp[3]} * 256.0f;
;         const hc zh = X[XI(pp)]; const cf z = (cf){(float)zh.x, (float)zh.y};
;         if (k == 0) { const cf y = cmul(z, P) + cmul((cf){z.x, -z.y}, Mq); X[XI(pp)] = (hc){(_Float16)y.x, (_Float16)y.y}; }
;         else { const int pm = rev4(16384 - k); const hc zmh = X[XI(pm)]; const cf zm = (cf){(float)zmh.x, (float)zmh.y};
;             const cf y = cmul(z, P) + cmul((cf){zm.x, -zm.y}, Mq);
;             const cf t = cmul((cf){zm.x, -zm.y}, P) + cmul(z, Mq);
;             X[XI(pp)] = (hc){(_Float16)y.x, (_Float16)y.y}; X[XI(pm)] = (hc){(_Float16)t.x, (_Float16)(-t.y)}; }
.LBB0_660:
	s_or_b64 exec, exec, s[22:23]
	v_add_u32_e32 v2, 0x2400, v9
	v_bfrev_b32_e32 v3, v2
	v_lshrrev_b32_e32 v4, 19, v3
	v_lshrrev_b32_e32 v3, 17, v3
	v_and_b32_e32 v3, 0x2aaa, v3
	v_and_or_b32 v10, v4, s89, v3
	s_movk_i32 s5, 0xdc00
	v_cmp_ne_u32_e64 s[40:41], s5, v9
	s_waitcnt vmcnt(5)
	v_mov_b32_e32 v4, v108
	v_mov_b32_e32 v5, v109
	v_mov_b32_e32 v6, v110
	v_mov_b32_e32 v7, v111
	v_pk_mul_f32 v[2:3], v[6:7], s[90:91] op_sel_hi:[1,0]
	v_lshl_add_u32 v6, v10, 2, s66
	v_lshrrev_b32_e32 v7, 2, v10
	v_lshrrev_b32_e32 v10, 6, v10
	v_and_b32_e32 v7, 0xffc, v7
	v_and_b32_e32 v10, 0xfc, v10
	v_add3_u32 v10, v6, v7, v10
	ds_read_b32 v7, v10
	v_pk_mul_f32 v[4:5], v[4:5], s[90:91] op_sel_hi:[1,0]
	s_waitcnt lgkmcnt(0)
	v_cvt_f32_f16_e32 v6, v7
	v_cvt_f32_f16_sdwa v7, v7 dst_sel:DWORD dst_unused:UNUSED_PAD src0_sel:WORD_1
	s_and_saveexec_b64 s[22:23], s[40:41]
	s_xor_b64 s[22:23], exec, s[22:23]
	s_cbranch_execz .LBB0_662
	v_add_u32_e32 v11, 0xa00, v8
	v_bfrev_b32_e32 v11, v11
	v_lshrrev_b32_e32 v13, 19, v11
	v_lshrrev_b32_e32 v11, 17, v11
	v_and_b32_e32 v11, 0x2aaa, v11
	v_and_or_b32 v11, v13, s89, v11
	v_lshl_add_u32 v13, v11, 2, s66
	v_lshrrev_b32_e32 v16, 2, v11
	v_lshrrev_b32_e32 v11, 6, v11
	v_and_b32_e32 v16, 0xffc, v16
	v_and_b32_e32 v11, 0xfc, v11
	v_add3_u32 v11, v13, v16, v11
	ds_read_b32 v13, v11
	v_pk_mul_f32 v[18:19], v[6:7], v[4:5] op_sel:[0,0] op_sel_hi:[0,1]
	s_waitcnt lgkmcnt(0)
	v_cvt_f32_f16_e32 v16, v13
	v_cvt_f32_f16_sdwa v17, -v13 dst_sel:DWORD dst_unused:UNUSED_PAD src0_sel:WORD_1
	v_pk_mul_f32 v[22:23], v[16:17], v[2:3] op_sel:[0,0] op_sel_hi:[0,1]
	v_pk_fma_f32 v[18:19], v[6:7], v[4:5], v[18:19] op_sel:[1,1,0] op_sel_hi:[1,0,1] neg_lo:[0,1,0]
	v_pk_fma_f32 v[22:23], v[16:17], v[2:3], v[22:23] op_sel:[1,1,0] op_sel_hi:[1,0,1] neg_lo:[0,1,0]
	v_pk_add_f32 v[18:19], v[18:19], v[22:23]
	v_pk_mul_f32 v[22:23], v[16:17], v[4:5] op_sel:[0,0] op_sel_hi:[0,1]
	v_pk_fma_f32 v[4:5], v[16:17], v[4:5], v[22:23] op_sel:[1,1,0] op_sel_hi:[1,0,1] neg_lo:[0,1,0]
	v_pk_mul_f32 v[16:17], v[6:7], v[2:3] op_sel:[0,0] op_sel_hi:[0,1]
	v_pk_fma_f32 v[2:3], v[6:7], v[2:3], v[16:17] op_sel:[1,1,0] op_sel_hi:[1,0,1] neg_lo:[0,1,0]
	s_nop 0
	v_pk_add_f32 v[2:3], v[4:5], v[2:3]
	v_cvt_pk_f16_f32 v4, v18, v19
	v_cvt_pk_f16_f32 v2, v2, -v3
	ds_write_b32 v10, v4
	ds_write_b32 v11, v2

; DI int rev4(int pp) { const unsigned br = __brev((unsigned)pp) >> 18; return (int)(((br & 0x2AAAu) >> 1) | ((br & 0x1555u) << 1)); }
; DI void pw_h(LAS hc* X, const f32x4* spec, int tid) {
;     ...
;     for (int r = 0; r < 16; ++r) {
;         const int k = tid + NTHR * r; const int pp = rev4(k);
;         const f32x4 sp = spec[k]; const cf P = (cf){sp[0], sp[1]} * 256.0f, Mq = (cf){sp[2], sp[3]} * 256.0f;
;         const hc zh = X[XI(pp)]; const cf z = (cf){(float)zh.x, (float)zh.y};
;         if (k == 0) { const cf y = cmul(z, P) + cmul((cf){z.x, -z.y}, Mq); X[XI(pp)] = (hc){(_Float16)y.x, (_Float16)y.y}; }
;         else { const int pm = rev4(16384 - k); const hc zmh = X[XI(pm)]; const cf zm = (cf){(float)zmh.x, (float)zmh.y};
;             const cf y = cmul(z, P) + cmul((cf){zm.x, -zm.y}, Mq);
;             const cf t = cmul((cf){zm.x, -zm.y}, P) + cmul(z, Mq);
;             X[XI(pp)] = (hc){(_Float16)y.x, (_Float16)y.y}; X[XI(pm)] = (hc){(_Float16)t.x, (_Float16)(-t.y)}; }
.LBB0_664:
	s_or_b64 exec, exec, s[22:23]
	v_add_u32_e32 v2, 0x2600, v9
	v_bfrev_b32_e32 v3, v2
	v_lshrrev_b32_e32 v4, 19, v3
	v_lshrrev_b32_e32 v3, 17, v3
	v_and_b32_e32 v3, 0x2aaa, v3
	v_and_or_b32 v10, v4, s89, v3
	s_movk_i32 s5, 0xda00
	v_cmp_ne_u32_e64 s[40:41], s5, v9
	s_waitcnt vmcnt(4)
	v_mov_b32_e32 v4, v112
	v_mov_b32_e32 v5, v113
	v_mov_b32_e32 v6, v114
	v_mov_b32_e32 v7, v115
	v_pk_mul_f32 v[2:3], v[6:7], s[90:91] op_sel_hi:[1,0]
	v_lshl_add_u32 v6, v10, 2, s66
	v_lshrrev_b32_e32 v7, 2, v10
	v_lshrrev_b32_e32 v10, 6, v10
	v_and_b32_e32 v7, 0xffc, v7
	v_and_b32_e32 v10, 0xfc, v10
	v_add3_u32 v10, v6, v7, v10
	ds_read_b32 v7, v10
	v_pk_mul_f32 v[4:5], v[4:5], s[90:91] op_sel_hi:[1,0]
	s_waitcnt lgkmcnt(0)
	v_cvt_f32_f16_e32 v6, v7
	v_cvt_f32_f16_sdwa v7, v7 dst_sel:DWORD dst_unused:UNUSED_PAD src0_sel:WORD_1
	s_and_saveexec_b64 s[22:23], s[40:41]
	s_xor_b64 s[22:23], exec, s[22:23]
	s_cbranch_execz .LBB0_666
	v_add_u32_e32 v11, 0x800, v8
	v_bfrev_b32_e32 v11, v11
	v_lshrrev_b32_e32 v13, 19, v11
	v_lshrrev_b32_e32 v11, 17, v11
	v_and_b32_e32 v11, 0x2aaa, v11
	v_and_or_b32 v11, v13, s89, v11
	v_lshl_add_u32 v13, v11, 2, s66
	v_lshrrev_b32_e32 v16, 2, v11
	v_lshrrev_b32_e32 v11, 6, v11
	v_and_b32_e32 v16, 0xffc, v16
	v_and_b32_e32 v11, 0xfc, v11
	v_add3_u32 v11, v13, v16, v11
	ds_read_b32 v13, v11
	v_pk_mul_f32 v[18:19], v[6:7], v[4:5] op_sel:[0,0] op_sel_hi:[0,1]
	s_waitcnt lgkmcnt(0)
	v_cvt_f32_f16_e32 v16, v13
	v_cvt_f32_f16_sdwa v17, -v13 dst_sel:DWORD dst_unused:UNUSED_PAD src0_sel:WORD_1
	v_pk_mul_f32 v[22:23], v[16:17], v[2:3] op_sel:[0,0] op_sel_hi:[0,1]
	v_pk_fma_f32 v[18:19], v[6:7], v[4:5], v[18:19] op_sel:[1,1,0] op_sel_hi:[1,0,1] neg_lo:[0,1,0]
	v_pk_fma_f32 v[22:23], v[16:17], v[2:3], v[22:23] op_sel:[1,1,0] op_sel_hi:[1,0,1] neg_lo:[0,1,0]
	v_pk_add_f32 v[18:19], v[18:19], v[22:23]
	v_pk_mul_f32 v[22:23], v[16:17], v[4:5] op_sel:[0,0] op_sel_hi:[0,1]
	v_pk_fma_f32 v[4:5], v[16:17], v[4:5], v[22:23] op_sel:[1,1,0] op_sel_hi:[1,0,1] neg_lo:[0,1,0]
	v_pk_mul_f32 v[16:17], v[6:7], v[2:3] op_sel:[0,0] op_sel_hi:[0,1]
	v_pk_fma_f32 v[2:3], v[6:7], v[2:3], v[16:17] op_sel:[1,1,0] op_sel_hi:[1,0,1] neg_lo:[0,1,0]
	s_nop 0
	v_pk_add_f32 v[2:3], v[4:5], v[2:3]
	v_cvt_pk_f16_f32 v4, v18, v19
	v_cvt_pk_f16_f32 v2, v2, -v3
	ds_write_b32 v10, v4
	ds_write_b32 v11, v2

; DI int rev4(int pp) { const unsigned br = __brev((unsigned)pp) >> 18; return (int)(((br & 0x2AAAu) >> 1) | ((br & 0x1555u) << 1)); }
; DI void pw_h(LAS hc* X, const f32x4* spec, int tid) {
;     ...
;     for (int r = 0; r < 16; ++r) {
;         const int k = tid + NTHR * r; const int pp = rev4(k);
;         const f32x4 sp = spec[k]; const cf P = (cf){sp[0], sp[1]} * 256.0f, Mq = (cf){sp[2], sp[3]} * 256.0f;
;         const hc zh = X[XI(pp)]; const cf z = (cf){(float)zh.x, (float)zh.y};
;         if (k == 0) { const cf y = cmul(z, P) + cmul((cf){z.x, -z.y}, Mq); X[XI(pp)] = (hc){(_Float16)y.x, (_Float16)y.y}; }
;         else { const int pm = rev4(16384 - k); const hc zmh = X[XI(pm)]; const cf zm = (cf){(float)zmh.x, (float)zmh.y};
;             const cf y = cmul(z, P) + cmul((cf){zm.x, -zm.y}, Mq);
;             const cf t = cmul((cf){zm.x, -zm.y}, P) + cmul(z, Mq);
;             X[XI(pp)] = (hc){(_Float16)y.x, (_Float16)y.y}; X[XI(pm)] = (hc){(_Float16)t.x, (_Float16)(-t.y)}; }
.LBB0_668:
	s_or_b64 exec, exec, s[22:23]
	v_add_u32_e32 v2, 0x2800, v9
	v_bfrev_b32_e32 v3, v2
	v_lshrrev_b32_e32 v4, 19, v3
	v_lshrrev_b32_e32 v3, 17, v3
	v_and_b32_e32 v3, 0x2aaa, v3
	v_and_or_b32 v10, v4, s89, v3
	s_movk_i32 s5, 0xd800
	v_cmp_ne_u32_e64 s[40:41], s5, v9
	s_waitcnt vmcnt(3)
	v_mov_b32_e32 v4, v116
	v_mov_b32_e32 v5, v117
	v_mov_b32_e32 v6, v118
	v_mov_b32_e32 v7, v119
	v_pk_mul_f32 v[2:3], v[6:7], s[90:91] op_sel_hi:[1,0]
	v_lshl_add_u32 v6, v10, 2, s66
	v_lshrrev_b32_e32 v7, 2, v10
	v_lshrrev_b32_e32 v10, 6, v10
	v_and_b32_e32 v7, 0xffc, v7
	v_and_b32_e32 v10, 0xfc, v10
	v_add3_u32 v10, v6, v7, v10
	ds_read_b32 v7, v10
	v_pk_mul_f32 v[4:5], v[4:5], s[90:91] op_sel_hi:[1,0]
	s_waitcnt lgkmcnt(0)
	v_cvt_f32_f16_e32 v6, v7
	v_cvt_f32_f16_sdwa v7, v7 dst_sel:DWORD dst_unused:UNUSED_PAD src0_sel:WORD_1
	s_and_saveexec_b64 s[22:23], s[40:41]
	s_xor_b64 s[22:23], exec, s[22:23]
	s_cbranch_execz .LBB0_670
	v_add_u32_e32 v11, 0x600, v8
	v_bfrev_b32_e32 v11, v11
	v_lshrrev_b32_e32 v13, 19, v11
	v_lshrrev_b32_e32 v11, 17, v11
	v_and_b32_e32 v11, 0x2aaa, v11
	v_and_or_b32 v11, v13, s89, v11
	v_lshl_add_u32 v13, v11, 2, s66
	v_lshrrev_b32_e32 v16, 2, v11
	v_lshrrev_b32_e32 v11, 6, v11
	v_and_b32_e32 v16, 0xffc, v16
	v_and_b32_e32 v11, 0xfc, v11
	v_add3_u32 v11, v13, v16, v11
	ds_read_b32 v13, v11
	v_pk_mul_f32 v[18:19], v[6:7], v[4:5] op_sel:[0,0] op_sel_hi:[0,1]
	s_waitcnt lgkmcnt(0)
	v_cvt_f32_f16_e32 v16, v13
	v_cvt_f32_f16_sdwa v17, -v13 dst_sel:DWORD dst_unused:UNUSED_PAD src0_sel:WORD_1
	v_pk_mul_f32 v[22:23], v[16:17], v[2:3] op_sel:[0,0] op_sel_hi:[0,1]
	v_pk_fma_f32 v[18:19], v[6:7], v[4:5], v[18:19] op_sel:[1,1,0] op_sel_hi:[1,0,1] neg_lo:[0,1,0]
	v_pk_fma_f32 v[22:23], v[16:17], v[2:3], v[22:23] op_sel:[1,1,0] op_sel_hi:[1,0,1] neg_lo:[0,1,0]
	v_pk_add_f32 v[18:19], v[18:19], v[22:23]
	v_pk_mul_f32 v[22:23], v[16:17], v[4:5] op_sel:[0,0] op_sel_hi:[0,1]
	v_pk_fma_f32 v[4:5], v[16:17], v[4:5], v[22:23] op_sel:[1,1,0] op_sel_hi:[1,0,1] neg_lo:[0,1,0]
	v_pk_mul_f32 v[16:17], v[6:7], v[2:3] op_sel:[0,0] op_sel_hi:[0,1]
	v_pk_fma_f32 v[2:3], v[6:7], v[2:3], v[16:17] op_sel:[1,1,0] op_sel_hi:[1,0,1] neg_lo:[0,1,0]
	s_nop 0
	v_pk_add_f32 v[2:3], v[4:5], v[2:3]
	v_cvt_pk_f16_f32 v4, v18, v19
	v_cvt_pk_f16_f32 v2, v2, -v3
	ds_write_b32 v10, v4
	ds_write_b32 v11, v2

; DI int rev4(int pp) { const unsigned br = __brev((unsigned)pp) >> 18; return (int)(((br & 0x2AAAu) >> 1) | ((br & 0x1555u) << 1)); }
; DI void pw_h(LAS hc* X, const f32x4* spec, int tid) {
;     ...
;     for (int r = 0; r < 16; ++r) {
;         const int k = tid + NTHR * r; const int pp = rev4(k);
;         const f32x4 sp = spec[k]; const cf P = (cf){sp[0], sp[1]} * 256.0f, Mq = (cf){sp[2], sp[3]} * 256.0f;
;         const hc zh = X[XI(pp)]; const cf z = (cf){(float)zh.x, (float)zh.y};
;         if (k == 0) { const cf y = cmul(z, P) + cmul((cf){z.x, -z.y}, Mq); X[XI(pp)] = (hc){(_Float16)y.x, (_Float16)y.y}; }
;         else { const int pm = rev4(16384 - k); const hc zmh = X[XI(pm)]; const cf zm = (cf){(float)zmh.x, (float)zmh.y};
;             const cf y = cmul(z, P) + cmul((cf){zm.x, -zm.y}, Mq);
;             const cf t = cmul((cf){zm.x, -zm.y}, P) + cmul(z, Mq);
;             X[XI(pp)] = (hc){(_Float16)y.x, (_Float16)y.y}; X[XI(pm)] = (hc){(_Float16)t.x, (_Float16)(-t.y)}; }
.LBB0_672:
	s_or_b64 exec, exec, s[22:23]
	v_add_u32_e32 v2, 0x2a00, v9
	v_bfrev_b32_e32 v3, v2
	v_lshrrev_b32_e32 v4, 19, v3
	v_lshrrev_b32_e32 v3, 17, v3
	v_and_b32_e32 v3, 0x2aaa, v3
	v_and_or_b32 v10, v4, s89, v3
	s_movk_i32 s5, 0xd600
	v_cmp_ne_u32_e64 s[40:41], s5, v9
	s_waitcnt vmcnt(2)
	v_mov_b32_e32 v4, v120
	v_mov_b32_e32 v5, v121
	v_mov_b32_e32 v6, v122
	v_mov_b32_e32 v7, v123
	v_pk_mul_f32 v[2:3], v[6:7], s[90:91] op_sel_hi:[1,0]
	v_lshl_add_u32 v6, v10, 2, s66
	v_lshrrev_b32_e32 v7, 2, v10
	v_lshrrev_b32_e32 v10, 6, v10
	v_and_b32_e32 v7, 0xffc, v7
	v_and_b32_e32 v10, 0xfc, v10
	v_add3_u32 v10, v6, v7, v10
	ds_read_b32 v7, v10
	v_pk_mul_f32 v[4:5], v[4:5], s[90:91] op_sel_hi:[1,0]
	s_waitcnt lgkmcnt(0)
	v_cvt_f32_f16_e32 v6, v7
	v_cvt_f32_f16_sdwa v7, v7 dst_sel:DWORD dst_unused:UNUSED_PAD src0_sel:WORD_1
	s_and_saveexec_b64 s[22:23], s[40:41]
	s_xor_b64 s[22:23], exec, s[22:23]
	s_cbranch_execz .LBB0_674
	v_add_u32_e32 v11, 0x400, v8
	v_bfrev_b32_e32 v11, v11
	v_lshrrev_b32_e32 v13, 19, v11
	v_lshrrev_b32_e32 v11, 17, v11
	v_and_b32_e32 v11, 0x2aaa, v11
	v_and_or_b32 v11, v13, s89, v11
	v_lshl_add_u32 v13, v11, 2, s66
	v_lshrrev_b32_e32 v16, 2, v11
	v_lshrrev_b32_e32 v11, 6, v11
	v_and_b32_e32 v16, 0xffc, v16
	v_and_b32_e32 v11, 0xfc, v11
	v_add3_u32 v11, v13, v16, v11
	ds_read_b32 v13, v11
	v_pk_mul_f32 v[18:19], v[6:7], v[4:5] op_sel:[0,0] op_sel_hi:[0,1]
	s_waitcnt lgkmcnt(0)
	v_cvt_f32_f16_e32 v16, v13
	v_cvt_f32_f16_sdwa v17, -v13 dst_sel:DWORD dst_unused:UNUSED_PAD src0_sel:WORD_1
	v_pk_mul_f32 v[22:23], v[16:17], v[2:3] op_sel:[0,0] op_sel_hi:[0,1]
	v_pk_fma_f32 v[18:19], v[6:7], v[4:5], v[18:19] op_sel:[1,1,0] op_sel_hi:[1,0,1] neg_lo:[0,1,0]
	v_pk_fma_f32 v[22:23], v[16:17], v[2:3], v[22:23] op_sel:[1,1,0] op_sel_hi:[1,0,1] neg_lo:[0,1,0]
	v_pk_add_f32 v[18:19], v[18:19], v[22:23]
	v_pk_mul_f32 v[22:23], v[16:17], v[4:5] op_sel:[0,0] op_sel_hi:[0,1]
	v_pk_fma_f32 v[4:5], v[16:17], v[4:5], v[22:23] op_sel:[1,1,0] op_sel_hi:[1,0,1] neg_lo:[0,1,0]
	v_pk_mul_f32 v[16:17], v[6:7], v[2:3] op_sel:[0,0] op_sel_hi:[0,1]
	v_pk_fma_f32 v[2:3], v[6:7], v[2:3], v[16:17] op_sel:[1,1,0] op_sel_hi:[1,0,1] neg_lo:[0,1,0]
	s_nop 0
	v_pk_add_f32 v[2:3], v[4:5], v[2:3]
	v_cvt_pk_f16_f32 v4, v18, v19
	v_cvt_pk_f16_f32 v2, v2, -v3
	ds_write_b32 v10, v4
	ds_write_b32 v11, v2

; DI int rev4(int pp) { const unsigned br = __brev((unsigned)pp) >> 18; return (int)(((br & 0x2AAAu) >> 1) | ((br & 0x1555u) << 1)); }
; DI void pw_h(LAS hc* X, const f32x4* spec, int tid) {
;     ...
;     for (int r = 0; r < 16; ++r) {
;         const int k = tid + NTHR * r; const int pp = rev4(k);
;         const f32x4 sp = spec[k]; const cf P = (cf){sp[0], sp[1]} * 256.0f, Mq = (cf){sp[2], sp[3]} * 256.0f;
;         const hc zh = X[XI(pp)]; const cf z = (cf){(float)zh.x, (float)zh.y};
;         if (k == 0) { const cf y = cmul(z, P) + cmul((cf){z.x, -z.y}, Mq); X[XI(pp)] = (hc){(_Float16)y.x, (_Float16)y.y}; }
;         else { const int pm = rev4(16384 - k); const hc zmh = X[XI(pm)]; const cf zm = (cf){(float)zmh.x, (float)zmh.y};
;             const cf y = cmul(z, P) + cmul((cf){zm.x, -zm.y}, Mq);
;             const cf t = cmul((cf){zm.x, -zm.y}, P) + cmul(z, Mq);
;             X[XI(pp)] = (hc){(_Float16)y.x, (_Float16)y.y}; X[XI(pm)] = (hc){(_Float16)t.x, (_Float16)(-t.y)}; }
.LBB0_676:
	s_or_b64 exec, exec, s[22:23]
	v_add_u32_e32 v2, 0x2c00, v9
	v_bfrev_b32_e32 v3, v2
	v_lshrrev_b32_e32 v4, 19, v3
	v_lshrrev_b32_e32 v3, 17, v3
	v_and_b32_e32 v3, 0x2aaa, v3
	v_and_or_b32 v10, v4, s89, v3
	v_cmp_ne_u32_e64 s[40:41], s96, v9
	s_waitcnt vmcnt(1)
	v_mov_b32_e32 v4, v124
	v_mov_b32_e32 v5, v125
	v_mov_b32_e32 v6, v126
	v_mov_b32_e32 v7, v127
	v_pk_mul_f32 v[2:3], v[6:7], s[90:91] op_sel_hi:[1,0]
	v_lshl_add_u32 v6, v10, 2, s66
	v_lshrrev_b32_e32 v7, 2, v10
	v_lshrrev_b32_e32 v10, 6, v10
	v_and_b32_e32 v7, 0xffc, v7
	v_and_b32_e32 v10, 0xfc, v10
	v_add3_u32 v10, v6, v7, v10
	ds_read_b32 v7, v10
	v_pk_mul_f32 v[4:5], v[4:5], s[90:91] op_sel_hi:[1,0]
	s_waitcnt lgkmcnt(0)
	v_cvt_f32_f16_e32 v6, v7
	v_cvt_f32_f16_sdwa v7, v7 dst_sel:DWORD dst_unused:UNUSED_PAD src0_sel:WORD_1
	s_and_saveexec_b64 s[22:23], s[40:41]
	s_xor_b64 s[22:23], exec, s[22:23]
	s_cbranch_execz .LBB0_678
	v_add_u32_e32 v11, 0x200, v8
	v_bfrev_b32_e32 v11, v11
	v_lshrrev_b32_e32 v13, 19, v11
	v_lshrrev_b32_e32 v11, 17, v11
	v_and_b32_e32 v11, 0x2aaa, v11
	v_and_or_b32 v11, v13, s89, v11
	v_lshl_add_u32 v13, v11, 2, s66
	v_lshrrev_b32_e32 v16, 2, v11
	v_lshrrev_b32_e32 v11, 6, v11
	v_and_b32_e32 v16, 0xffc, v16
	v_and_b32_e32 v11, 0xfc, v11
	v_add3_u32 v11, v13, v16, v11
	ds_read_b32 v13, v11
	v_pk_mul_f32 v[18:19], v[6:7], v[4:5] op_sel:[0,0] op_sel_hi:[0,1]
	s_waitcnt lgkmcnt(0)
	v_cvt_f32_f16_e32 v16, v13
	v_cvt_f32_f16_sdwa v17, -v13 dst_sel:DWORD dst_unused:UNUSED_PAD src0_sel:WORD_1
	v_pk_mul_f32 v[22:23], v[16:17], v[2:3] op_sel:[0,0] op_sel_hi:[0,1]
	v_pk_fma_f32 v[18:19], v[6:7], v[4:5], v[18:19] op_sel:[1,1,0] op_sel_hi:[1,0,1] neg_lo:[0,1,0]
	v_pk_fma_f32 v[22:23], v[16:17], v[2:3], v[22:23] op_sel:[1,1,0] op_sel_hi:[1,0,1] neg_lo:[0,1,0]
	v_pk_add_f32 v[18:19], v[18:19], v[22:23]
	v_pk_mul_f32 v[22:23], v[16:17], v[4:5] op_sel:[0,0] op_sel_hi:[0,1]
	v_pk_fma_f32 v[4:5], v[16:17], v[4:5], v[22:23] op_sel:[1,1,0] op_sel_hi:[1,0,1] neg_lo:[0,1,0]
	v_pk_mul_f32 v[16:17], v[6:7], v[2:3] op_sel:[0,0] op_sel_hi:[0,1]
	v_pk_fma_f32 v[2:3], v[6:7], v[2:3], v[16:17] op_sel:[1,1,0] op_sel_hi:[1,0,1] neg_lo:[0,1,0]
	s_nop 0
	v_pk_add_f32 v[2:3], v[4:5], v[2:3]
	v_cvt_pk_f16_f32 v4, v18, v19
	v_cvt_pk_f16_f32 v2, v2, -v3
	ds_write_b32 v10, v4
	ds_write_b32 v11, v2

; DI int rev4(int pp) { const unsigned br = __brev((unsigned)pp) >> 18; return (int)(((br & 0x2AAAu) >> 1) | ((br & 0x1555u) << 1)); }
; DI void pw_h(LAS hc* X, const f32x4* spec, int tid) {
;     ...
;     for (int r = 0; r < 16; ++r) {
;         const int k = tid + NTHR * r; const int pp = rev4(k);
;         const f32x4 sp = spec[k]; const cf P = (cf){sp[0], sp[1]} * 256.0f, Mq = (cf){sp[2], sp[3]} * 256.0f;
;         const hc zh = X[XI(pp)]; const cf z = (cf){(float)zh.x, (float)zh.y};
;         if (k == 0) { const cf y = cmul(z, P) + cmul((cf){z.x, -z.y}, Mq); X[XI(pp)] = (hc){(_Float16)y.x, (_Float16)y.y}; }
;         else { const int pm = rev4(16384 - k); const hc zmh = X[XI(pm)]; const cf zm = (cf){(float)zmh.x, (float)zmh.y};
;             const cf y = cmul(z, P) + cmul((cf){zm.x, -zm.y}, Mq);
;             const cf t = cmul((cf){zm.x, -zm.y}, P) + cmul(z, Mq);
;             X[XI(pp)] = (hc){(_Float16)y.x, (_Float16)y.y}; X[XI(pm)] = (hc){(_Float16)t.x, (_Float16)(-t.y)}; }
.LBB0_680:
	s_or_b64 exec, exec, s[22:23]
	v_add_u32_e32 v2, 0x2e00, v9
	v_bfrev_b32_e32 v3, v2
	v_lshrrev_b32_e32 v4, 19, v3
	v_lshrrev_b32_e32 v3, 17, v3
	v_and_b32_e32 v3, 0x2aaa, v3
	v_and_or_b32 v10, v4, s89, v3
	v_cmp_ne_u32_e64 s[40:41], s84, v9
	s_waitcnt vmcnt(0)
	v_mov_b32_e32 v4, v128
	v_mov_b32_e32 v5, v129
	v_mov_b32_e32 v6, v130
	v_mov_b32_e32 v7, v131
	v_pk_mul_f32 v[2:3], v[6:7], s[90:91] op_sel_hi:[1,0]
	v_lshl_add_u32 v6, v10, 2, s66
	v_lshrrev_b32_e32 v7, 2, v10
	v_lshrrev_b32_e32 v10, 6, v10
	v_and_b32_e32 v7, 0xffc, v7
	v_and_b32_e32 v10, 0xfc, v10
	v_add3_u32 v10, v6, v7, v10
	ds_read_b32 v7, v10
	v_pk_mul_f32 v[4:5], v[4:5], s[90:91] op_sel_hi:[1,0]
	s_waitcnt lgkmcnt(0)
	v_cvt_f32_f16_e32 v6, v7
	v_cvt_f32_f16_sdwa v7, v7 dst_sel:DWORD dst_unused:UNUSED_PAD src0_sel:WORD_1
	s_and_saveexec_b64 s[22:23], s[40:41]
	s_xor_b64 s[22:23], exec, s[22:23]
	s_cbranch_execz .LBB0_682
	v_bfrev_b32_e32 v9, v8
	v_lshrrev_b32_e32 v11, 19, v9
	v_lshrrev_b32_e32 v9, 17, v9
	v_and_b32_e32 v9, 0x2aaa, v9
	v_and_or_b32 v9, v11, s89, v9
	v_lshl_add_u32 v11, v9, 2, s66
	v_lshrrev_b32_e32 v13, 2, v9
	v_lshrrev_b32_e32 v9, 6, v9
	v_and_b32_e32 v13, 0xffc, v13
	v_and_b32_e32 v9, 0xfc, v9
	v_add3_u32 v9, v11, v13, v9
	ds_read_b32 v11, v9
	v_pk_mul_f32 v[18:19], v[6:7], v[4:5] op_sel:[0,0] op_sel_hi:[0,1]
	s_waitcnt lgkmcnt(0)
	v_cvt_f32_f16_e32 v16, v11
	v_cvt_f32_f16_sdwa v17, -v11 dst_sel:DWORD dst_unused:UNUSED_PAD src0_sel:WORD_1
	v_pk_mul_f32 v[22:23], v[16:17], v[2:3] op_sel:[0,0] op_sel_hi:[0,1]
	v_pk_fma_f32 v[18:19], v[6:7], v[4:5], v[18:19] op_sel:[1,1,0] op_sel_hi:[1,0,1] neg_lo:[0,1,0]
	v_pk_fma_f32 v[22:23], v[16:17], v[2:3], v[22:23] op_sel:[1,1,0] op_sel_hi:[1,0,1] neg_lo:[0,1,0]
	v_pk_add_f32 v[18:19], v[18:19], v[22:23]
	v_pk_mul_f32 v[22:23], v[16:17], v[4:5] op_sel:[0,0] op_sel_hi:[0,1]
	v_pk_fma_f32 v[4:5], v[16:17], v[4:5], v[22:23] op_sel:[1,1,0] op_sel_hi:[1,0,1] neg_lo:[0,1,0]
	v_pk_mul_f32 v[16:17], v[6:7], v[2:3] op_sel:[0,0] op_sel_hi:[0,1]
	v_pk_fma_f32 v[2:3], v[6:7], v[2:3], v[16:17] op_sel:[1,1,0] op_sel_hi:[1,0,1] neg_lo:[0,1,0]
	s_nop 0
	v_pk_add_f32 v[2:3], v[4:5], v[2:3]
	v_cvt_pk_f16_f32 v4, v18, v19
	v_cvt_pk_f16_f32 v2, v2, -v3
	ds_write_b32 v10, v4
	ds_write_b32 v9, v2

; DI void hyena_item(const Params& p, int l, int dpr, LAS unsigned char* lds) {
;     ...
;     for (int r = 0; r < 16; ++r) { const int t = tid + NTHR * r; const hc y0 = X0[XI(t)], y1 = X1[XI(t)];
;         const float yv[4] = {(float)y0.x, (float)y0.y, (float)y1.x, (float)y1.y};
;         float z[4];
; #pragma unroll
;         for (int c = 0; c < 4; ++c) z[c] = yv[c] * (1.0f / 64.0f) * conv3(bint + (size_t)(1024 + a + c) * S, t, w[c][0], w[c][1], w[c][2]) * 0.25f;
;         X0[XI(t)] = (hc){(_Float16)z[0], (_Float16)z[1]}; X1[XI(t)] = (hc){(_Float16)z[2], (_Float16)z[3]};
;         X0[XI(t + 8192)] = hzero; X1[XI(t + 8192)] = hzero; }
.LBB0_699:
	v_add_u32_e32 v16, s74, v12
	v_mov_b32_e32 v140, v16
	v_ashrrev_i32_e32 v141, 31, v140
	v_lshlrev_b64 v[140:141], 2, v[140:141]
	v_lshl_add_u64 v[142:143], s[26:27], 0, v[140:141]
	global_load_dword v144, v[142:143], off
	v_lshl_add_u64 v[142:143], s[22:23], 0, v[140:141]
	global_load_dword v145, v[142:143], off
	v_lshl_add_u64 v[142:143], s[20:21], 0, v[140:141]
	global_load_dword v146, v[142:143], off
	v_lshl_add_u64 v[142:143], s[24:25], 0, v[140:141]
	global_load_dword v147, v[142:143], off
	v_add_u32_e32 v140, 0x200, v16
	v_ashrrev_i32_e32 v141, 31, v140
	v_lshlrev_b64 v[140:141], 2, v[140:141]
	v_lshl_add_u64 v[142:143], s[26:27], 0, v[140:141]
	global_load_dword v148, v[142:143], off
	v_lshl_add_u64 v[142:143], s[22:23], 0, v[140:141]
	global_load_dword v149, v[142:143], off
	v_lshl_add_u64 v[142:143], s[20:21], 0, v[140:141]
	global_load_dword v150, v[142:143], off
	v_lshl_add_u64 v[142:143], s[24:25], 0, v[140:141]
	global_load_dword v151, v[142:143], off
	v_add_u32_e32 v140, 0x400, v16
	v_ashrrev_i32_e32 v141, 31, v140
	v_lshlrev_b64 v[140:141], 2, v[140:141]
	v_lshl_add_u64 v[142:143], s[26:27], 0, v[140:141]
	global_load_dword v152, v[142:143], off
	v_lshl_add_u64 v[142:143], s[22:23], 0, v[140:141]
	global_load_dword v153, v[142:143], off
	v_lshl_add_u64 v[142:143], s[20:21], 0, v[140:141]
	global_load_dword v154, v[142:143], off
	v_lshl_add_u64 v[142:143], s[24:25], 0, v[140:141]
	global_load_dword v155, v[142:143], off
	v_add_u32_e32 v140, 0x600, v16
	v_ashrrev_i32_e32 v141, 31, v140
	v_lshlrev_b64 v[140:141], 2, v[140:141]
	v_lshl_add_u64 v[142:143], s[26:27], 0, v[140:141]
	global_load_dword v156, v[142:143], off
	v_lshl_add_u64 v[142:143], s[22:23], 0, v[140:141]
	global_load_dword v157, v[142:143], off
	v_lshl_add_u64 v[142:143], s[20:21], 0, v[140:141]
	global_load_dword v158, v[142:143], off
	v_lshl_add_u64 v[142:143], s[24:25], 0, v[140:141]
	global_load_dword v159, v[142:143], off
	v_ashrrev_i32_e32 v13, 4, v16
	v_ashrrev_i32_e32 v17, 8, v16
	v_add_u32_e32 v13, v13, v17
	v_ashrrev_i32_e32 v17, 31, v16
	v_max_i32_e32 v96, 1, v16
	v_min_i32_e32 v18, 0x1ffe, v16
	v_ashrrev_i32_e32 v19, 31, v18
	v_lshlrev_b64 v[22:23], 2, v[16:17]
	v_lshlrev_b64 v[26:27], 2, v[96:97]
	v_lshl_add_u64 v[24:25], s[26:27], 0, v[22:23]
	v_lshl_add_u64 v[28:29], s[26:27], 0, v[26:27]
	v_lshlrev_b64 v[18:19], 2, v[18:19]
	global_load_dword v24, v[24:25], off
	v_lshl_add_u64 v[30:31], s[20:21], 0, v[26:27]
	global_load_dword v17, v[28:29], off offset:-4
	v_lshl_add_u64 v[28:29], s[26:27], 0, v[18:19]
	global_load_dword v34, v[28:29], off offset:4
	v_lshl_add_u64 v[28:29], s[22:23], 0, v[22:23]
	global_load_dword v25, v[28:29], off
	v_lshl_add_u64 v[28:29], s[22:23], 0, v[26:27]
	global_load_dword v35, v[28:29], off offset:-4
	v_lshl_add_u64 v[28:29], s[22:23], 0, v[18:19]
	global_load_dword v36, v[28:29], off offset:4
	v_lshl_add_u64 v[28:29], s[20:21], 0, v[22:23]
	v_lshl_add_u64 v[22:23], s[24:25], 0, v[22:23]
	global_load_dword v28, v[28:29], off
	v_add_lshl_u32 v13, v16, v13, 2
	global_load_dword v37, v[30:31], off offset:-4
	global_load_dword v29, v[22:23], off
	v_lshl_add_u64 v[30:31], s[20:21], 0, v[18:19]
	v_lshl_add_u64 v[22:23], s[24:25], 0, v[26:27]
	global_load_dword v30, v[30:31], off offset:4
	v_lshl_add_u64 v[18:19], s[24:25], 0, v[18:19]
	global_load_dword v31, v[22:23], off offset:-4
	global_load_dword v38, v[18:19], off offset:4
	v_add_u32_e32 v21, 0, v13
	ds_read_b32 v32, v21
	v_add_u32_e32 v13, s66, v13
	ds_read_b32 v33, v13
	v_cmp_lt_i32_e64 s[40:41], 0, v16
	v_cmp_gt_i32_e64 s[42:43], s29, v16
	s_waitcnt lgkmcnt(1)
	v_cvt_f32_f16_e32 v18, v32
	v_cvt_f32_f16_sdwa v19, v32 dst_sel:DWORD dst_unused:UNUSED_PAD src0_sel:WORD_1
	s_addk_i32 s74, 0x800
	s_cmpk_eq_i32 s74, 0x2000
	v_pk_mul_f32 v[18:19], v[18:19], s[38:39] op_sel_hi:[1,0]
	s_waitcnt vmcnt(10)
	v_cndmask_b32_e64 v22, 0, v17, s[40:41]
	s_waitcnt vmcnt(9)
	v_cndmask_b32_e64 v26, 0, v34, s[42:43]
	s_waitcnt vmcnt(7)
	v_cndmask_b32_e64 v23, 0, v35, s[40:41]
	v_pk_mul_f32 v[22:23], v[0:1], v[22:23]
	s_waitcnt vmcnt(6)
	v_cndmask_b32_e64 v27, 0, v36, s[42:43]
	v_pk_fma_f32 v[22:23], v[4:5], v[24:25], v[22:23]
	s_waitcnt vmcnt(2)
	v_cndmask_b32_e64 v24, 0, v30, s[42:43]
	v_pk_fma_f32 v[22:23], v[8:9], v[26:27], v[22:23]
	s_waitcnt vmcnt(0)
	v_cndmask_b32_e64 v25, 0, v38, s[42:43]
	v_pk_mul_f32 v[18:19], v[18:19], v[22:23]
	v_cndmask_b32_e64 v23, 0, v31, s[40:41]
	v_pk_mul_f32 v[18:19], v[18:19], s[76:77] op_sel_hi:[1,0]
	v_cndmask_b32_e64 v22, 0, v37, s[40:41]
	v_cvt_pk_f16_f32 v17, v18, v19
	s_waitcnt lgkmcnt(0)
; DI void hyena_item(const Params& p, int l, int dpr, LAS unsigned char* lds) {
;     ...
;     for (int r = 0; r < 16; ++r) { const int t = tid + NTHR * r; const hc y0 = X0[XI(t)], y1 = X1[XI(t)];
;         const float yv[4] = {(float)y0.x, (float)y0.y, (float)y1.x, (float)y1.y};
;         float z[4];
; #pragma unroll
;         for (int c = 0; c < 4; ++c) z[c] = yv[c] * (1.0f / 64.0f) * conv3(bint + (size_t)(1024 + a + c) * S, t, w[c][0], w[c][1], w[c][2]) * 0.25f;
;         X0[XI(t)] = (hc){(_Float16)z[0], (_Float16)z[1]}; X1[XI(t)] = (hc){(_Float16)z[2], (_Float16)z[3]};
;         X0[XI(t + 8192)] = hzero; X1[XI(t + 8192)] = hzero; }
	v_cvt_f32_f16_e32 v18, v33
	v_cvt_f32_f16_sdwa v19, v33 dst_sel:DWORD dst_unused:UNUSED_PAD src0_sel:WORD_1
	v_pk_mul_f32 v[22:23], v[2:3], v[22:23]
	ds_write_b32 v21, v17
	v_pk_fma_f32 v[22:23], v[6:7], v[28:29], v[22:23]
	v_pk_mul_f32 v[18:19], v[18:19], s[38:39] op_sel_hi:[1,0]
	v_pk_fma_f32 v[22:23], v[10:11], v[24:25], v[22:23]
	s_nop 0
	v_pk_mul_f32 v[18:19], v[18:19], v[22:23]
	s_nop 0
	v_pk_mul_f32 v[18:19], v[18:19], s[76:77] op_sel_hi:[1,0]
	s_nop 0
	v_cvt_pk_f16_f32 v17, v18, v19
	ds_write_b32 v13, v17
	v_add_u32_e32 v13, 0x2000, v16
	v_ashrrev_i32_e32 v17, 4, v13
	v_ashrrev_i32_e32 v13, 8, v13
	v_add_u32_e32 v13, v17, v13
	v_add_lshl_u32 v13, v16, v13, 2
	v_add_u32_e32 v18, 0x200, v16
	v_add_u32_e32 v17, 0, v13
	v_add_u32_e32 v13, s66, v13
	v_ashrrev_i32_e32 v19, 31, v18
	v_max_i32_e32 v96, 1, v18
	v_min_i32_e32 v22, 0x1ffe, v18
	ds_write_b32 v17, v97 offset:32768
	ds_write_b32 v13, v97 offset:32768
	v_ashrrev_i32_e32 v13, 4, v18
	v_ashrrev_i32_e32 v17, 8, v18
	v_cmp_lt_i32_e64 s[40:41], 0, v18
	v_cmp_gt_i32_e64 s[42:43], s29, v18
	v_ashrrev_i32_e32 v23, 31, v22
	v_lshlrev_b64 v[18:19], 2, v[18:19]
	v_lshlrev_b64 v[26:27], 2, v[96:97]
	v_lshl_add_u64 v[24:25], s[26:27], 0, v[18:19]
	v_lshl_add_u64 v[28:29], s[26:27], 0, v[26:27]
	v_lshlrev_b64 v[22:23], 2, v[22:23]
	global_load_dword v24, v[24:25], off
	v_lshl_add_u64 v[30:31], s[20:21], 0, v[26:27]
	global_load_dword v33, v[28:29], off offset:-4
	v_lshl_add_u64 v[28:29], s[26:27], 0, v[22:23]
	global_load_dword v34, v[28:29], off offset:4
	v_lshl_add_u64 v[28:29], s[22:23], 0, v[18:19]
	global_load_dword v25, v[28:29], off
	v_lshl_add_u64 v[28:29], s[22:23], 0, v[26:27]
	global_load_dword v35, v[28:29], off offset:-4
	v_lshl_add_u64 v[28:29], s[22:23], 0, v[22:23]
	global_load_dword v36, v[28:29], off offset:4
	v_lshl_add_u64 v[28:29], s[20:21], 0, v[18:19]
	v_lshl_add_u64 v[18:19], s[24:25], 0, v[18:19]
	global_load_dword v28, v[28:29], off
	v_add_u32_e32 v13, v13, v17
	global_load_dword v37, v[30:31], off offset:-4
	global_load_dword v29, v[18:19], off
	v_lshl_add_u64 v[30:31], s[20:21], 0, v[22:23]
	v_lshl_add_u64 v[18:19], s[24:25], 0, v[26:27]
	global_load_dword v30, v[30:31], off offset:4
	v_add_lshl_u32 v13, v16, v13, 2
	global_load_dword v31, v[18:19], off offset:-4
	v_lshl_add_u64 v[18:19], s[24:25], 0, v[22:23]
	global_load_dword v38, v[18:19], off offset:4
	v_add_u32_e32 v17, 0, v13
	ds_read_b32 v21, v17 offset:2048
	v_add_u32_e32 v13, s66, v13
	ds_read_b32 v32, v13 offset:2048
	s_waitcnt lgkmcnt(1)
	v_cvt_f32_f16_e32 v18, v21
	v_cvt_f32_f16_sdwa v19, v21 dst_sel:DWORD dst_unused:UNUSED_PAD src0_sel:WORD_1
	v_pk_mul_f32 v[18:19], v[18:19], s[38:39] op_sel_hi:[1,0]
	s_waitcnt vmcnt(10)
	v_cndmask_b32_e64 v22, 0, v33, s[40:41]
	s_waitcnt vmcnt(9)
	v_cndmask_b32_e64 v26, 0, v34, s[42:43]
	s_waitcnt vmcnt(7)
	v_cndmask_b32_e64 v23, 0, v35, s[40:41]
	v_pk_mul_f32 v[22:23], v[0:1], v[22:23]
	s_waitcnt vmcnt(6)
	v_cndmask_b32_e64 v27, 0, v36, s[42:43]
	v_pk_fma_f32 v[22:23], v[4:5], v[24:25], v[22:23]
	s_waitcnt vmcnt(2)
	v_cndmask_b32_e64 v24, 0, v30, s[42:43]
	v_pk_fma_f32 v[22:23], v[8:9], v[26:27], v[22:23]
	s_waitcnt vmcnt(0)
	v_cndmask_b32_e64 v25, 0, v38, s[42:43]
	v_pk_mul_f32 v[18:19], v[18:19], v[22:23]
	v_cndmask_b32_e64 v23, 0, v31, s[40:41]
	v_pk_mul_f32 v[18:19], v[18:19], s[76:77] op_sel_hi:[1,0]
	v_cndmask_b32_e64 v22, 0, v37, s[40:41]
	v_cvt_pk_f16_f32 v18, v18, v19
	ds_write_b32 v17, v18 offset:2048
	s_waitcnt lgkmcnt(1)
	v_cvt_f32_f16_e32 v18, v32
	v_cvt_f32_f16_sdwa v19, v32 dst_sel:DWORD dst_unused:UNUSED_PAD src0_sel:WORD_1
	v_pk_mul_f32 v[22:23], v[2:3], v[22:23]
	v_pk_mul_f32 v[18:19], v[18:19], s[38:39] op_sel_hi:[1,0]
	v_pk_fma_f32 v[22:23], v[6:7], v[28:29], v[22:23]
	s_nop 0
	v_pk_fma_f32 v[22:23], v[10:11], v[24:25], v[22:23]
	s_nop 0
	v_pk_mul_f32 v[18:19], v[18:19], v[22:23]
	s_nop 0
	v_pk_mul_f32 v[18:19], v[18:19], s[76:77] op_sel_hi:[1,0]
	s_nop 0
	v_cvt_pk_f16_f32 v17, v18, v19
	ds_write_b32 v13, v17 offset:2048
	v_add_u32_e32 v13, 0x2200, v16
	v_ashrrev_i32_e32 v17, 4, v13
	v_ashrrev_i32_e32 v13, 8, v13
	v_add_u32_e32 v13, v17, v13
	v_add_lshl_u32 v13, v16, v13, 2
	v_add_u32_e32 v18, 0x400, v16
	v_add_u32_e32 v17, 0, v13
	v_add_u32_e32 v13, s66, v13
	v_ashrrev_i32_e32 v19, 31, v18
	v_max_i32_e32 v96, 1, v18
	v_min_i32_e32 v22, 0x1ffe, v18
	ds_write_b32 v17, v97 offset:34816
	ds_write_b32 v13, v97 offset:34816
	v_ashrrev_i32_e32 v13, 4, v18
	v_ashrrev_i32_e32 v17, 8, v18
	v_cmp_lt_i32_e64 s[40:41], 0, v18
	v_cmp_gt_i32_e64 s[42:43], s29, v18
	v_ashrrev_i32_e32 v23, 31, v22
	v_lshlrev_b64 v[18:19], 2, v[18:19]
	v_lshlrev_b64 v[26:27], 2, v[96:97]
	v_lshl_add_u64 v[24:25], s[26:27], 0, v[18:19]
	v_lshl_add_u64 v[28:29], s[26:27], 0, v[26:27]
	v_lshlrev_b64 v[22:23], 2, v[22:23]
	global_load_dword v24, v[24:25], off
	v_lshl_add_u64 v[30:31], s[20:21], 0, v[26:27]
	global_load_dword v33, v[28:29], off offset:-4
	v_lshl_add_u64 v[28:29], s[26:27], 0, v[22:23]
	global_load_dword v34, v[28:29], off offset:4
	v_lshl_add_u64 v[28:29], s[22:23], 0, v[18:19]
	global_load_dword v25, v[28:29], off
	v_lshl_add_u64 v[28:29], s[22:23], 0, v[26:27]
	global_load_dword v35, v[28:29], off offset:-4
	v_lshl_add_u64 v[28:29], s[22:23], 0, v[22:23]
	global_load_dword v36, v[28:29], off offset:4
	v_lshl_add_u64 v[28:29], s[20:21], 0, v[18:19]
	v_lshl_add_u64 v[18:19], s[24:25], 0, v[18:19]
	global_load_dword v28, v[28:29], off
	v_add_u32_e32 v13, v13, v17
	global_load_dword v37, v[30:31], off offset:-4
	global_load_dword v29, v[18:19], off
	v_lshl_add_u64 v[30:31], s[20:21], 0, v[22:23]
	v_lshl_add_u64 v[18:19], s[24:25], 0, v[26:27]
	global_load_dword v30, v[30:31], off offset:4
	v_add_lshl_u32 v13, v16, v13, 2
	global_load_dword v31, v[18:19], off offset:-4
	v_lshl_add_u64 v[18:19], s[24:25], 0, v[22:23]
	global_load_dword v38, v[18:19], off offset:4
	v_add_u32_e32 v17, 0, v13
	ds_read_b32 v21, v17 offset:4096
	v_add_u32_e32 v13, s66, v13
	ds_read_b32 v32, v13 offset:4096
	s_waitcnt lgkmcnt(1)
; DI void hyena_item(const Params& p, int l, int dpr, LAS unsigned char* lds) {
;     ...
;     for (int r = 0; r < 16; ++r) { const int t = tid + NTHR * r; const hc y0 = X0[XI(t)], y1 = X1[XI(t)];
;         const float yv[4] = {(float)y0.x, (float)y0.y, (float)y1.x, (float)y1.y};
;         float z[4];
; #pragma unroll
;         for (int c = 0; c < 4; ++c) z[c] = yv[c] * (1.0f / 64.0f) * conv3(bint + (size_t)(1024 + a + c) * S, t, w[c][0], w[c][1], w[c][2]) * 0.25f;
;         X0[XI(t)] = (hc){(_Float16)z[0], (_Float16)z[1]}; X1[XI(t)] = (hc){(_Float16)z[2], (_Float16)z[3]};
;         X0[XI(t + 8192)] = hzero; X1[XI(t + 8192)] = hzero; }
	v_cvt_f32_f16_e32 v18, v21
	v_cvt_f32_f16_sdwa v19, v21 dst_sel:DWORD dst_unused:UNUSED_PAD src0_sel:WORD_1
	v_pk_mul_f32 v[18:19], v[18:19], s[38:39] op_sel_hi:[1,0]
	s_waitcnt vmcnt(10)
	v_cndmask_b32_e64 v22, 0, v33, s[40:41]
	s_waitcnt vmcnt(9)
	v_cndmask_b32_e64 v26, 0, v34, s[42:43]
	s_waitcnt vmcnt(7)
	v_cndmask_b32_e64 v23, 0, v35, s[40:41]
	v_pk_mul_f32 v[22:23], v[0:1], v[22:23]
	s_waitcnt vmcnt(6)
	v_cndmask_b32_e64 v27, 0, v36, s[42:43]
	v_pk_fma_f32 v[22:23], v[4:5], v[24:25], v[22:23]
	s_waitcnt vmcnt(2)
	v_cndmask_b32_e64 v24, 0, v30, s[42:43]
	v_pk_fma_f32 v[22:23], v[8:9], v[26:27], v[22:23]
	s_waitcnt vmcnt(0)
	v_cndmask_b32_e64 v25, 0, v38, s[42:43]
	v_pk_mul_f32 v[18:19], v[18:19], v[22:23]
	v_cndmask_b32_e64 v23, 0, v31, s[40:41]
	v_pk_mul_f32 v[18:19], v[18:19], s[76:77] op_sel_hi:[1,0]
	v_cndmask_b32_e64 v22, 0, v37, s[40:41]
	v_cvt_pk_f16_f32 v18, v18, v19
	ds_write_b32 v17, v18 offset:4096
	s_waitcnt lgkmcnt(1)
	v_cvt_f32_f16_e32 v18, v32
	v_cvt_f32_f16_sdwa v19, v32 dst_sel:DWORD dst_unused:UNUSED_PAD src0_sel:WORD_1
	v_pk_mul_f32 v[22:23], v[2:3], v[22:23]
	v_pk_mul_f32 v[18:19], v[18:19], s[38:39] op_sel_hi:[1,0]
	v_pk_fma_f32 v[22:23], v[6:7], v[28:29], v[22:23]
	s_nop 0
	v_pk_fma_f32 v[22:23], v[10:11], v[24:25], v[22:23]
	s_nop 0
	v_pk_mul_f32 v[18:19], v[18:19], v[22:23]
	s_nop 0
	v_pk_mul_f32 v[18:19], v[18:19], s[76:77] op_sel_hi:[1,0]
	s_nop 0
	v_cvt_pk_f16_f32 v17, v18, v19
	ds_write_b32 v13, v17 offset:4096
	v_add_u32_e32 v13, 0x2400, v16
	v_ashrrev_i32_e32 v17, 4, v13
	v_ashrrev_i32_e32 v13, 8, v13
	v_add_u32_e32 v13, v17, v13
	v_add_lshl_u32 v13, v16, v13, 2
	v_add_u32_e32 v18, 0x600, v16
	v_add_u32_e32 v17, 0, v13
	v_add_u32_e32 v13, s66, v13
	v_ashrrev_i32_e32 v19, 31, v18
	v_max_i32_e32 v96, 1, v18
	v_min_i32_e32 v22, 0x1ffe, v18
	ds_write_b32 v17, v97 offset:36864
	ds_write_b32 v13, v97 offset:36864
	v_ashrrev_i32_e32 v13, 4, v18
	v_ashrrev_i32_e32 v17, 8, v18
	v_cmp_lt_i32_e64 s[40:41], 0, v18
	v_cmp_gt_i32_e64 s[42:43], s29, v18
	v_ashrrev_i32_e32 v23, 31, v22
	v_lshlrev_b64 v[18:19], 2, v[18:19]
	v_lshlrev_b64 v[26:27], 2, v[96:97]
	v_lshl_add_u64 v[24:25], s[26:27], 0, v[18:19]
	v_lshl_add_u64 v[28:29], s[26:27], 0, v[26:27]
	v_lshlrev_b64 v[22:23], 2, v[22:23]
	global_load_dword v24, v[24:25], off
	v_lshl_add_u64 v[30:31], s[20:21], 0, v[26:27]
	global_load_dword v33, v[28:29], off offset:-4
	v_lshl_add_u64 v[28:29], s[26:27], 0, v[22:23]
	global_load_dword v34, v[28:29], off offset:4
	v_lshl_add_u64 v[28:29], s[22:23], 0, v[18:19]
	global_load_dword v25, v[28:29], off
	v_lshl_add_u64 v[28:29], s[22:23], 0, v[26:27]
	global_load_dword v35, v[28:29], off offset:-4
	v_lshl_add_u64 v[28:29], s[22:23], 0, v[22:23]
	global_load_dword v36, v[28:29], off offset:4
	v_lshl_add_u64 v[28:29], s[20:21], 0, v[18:19]
	v_lshl_add_u64 v[18:19], s[24:25], 0, v[18:19]
	global_load_dword v28, v[28:29], off
	v_add_u32_e32 v13, v13, v17
	global_load_dword v37, v[30:31], off offset:-4
	global_load_dword v29, v[18:19], off
	v_lshl_add_u64 v[30:31], s[20:21], 0, v[22:23]
	v_lshl_add_u64 v[18:19], s[24:25], 0, v[26:27]
	global_load_dword v30, v[30:31], off offset:4
	v_add_lshl_u32 v13, v16, v13, 2
	global_load_dword v31, v[18:19], off offset:-4
	v_lshl_add_u64 v[18:19], s[24:25], 0, v[22:23]
	global_load_dword v38, v[18:19], off offset:4
	v_add_u32_e32 v17, 0, v13
	ds_read_b32 v21, v17 offset:6144
	v_add_u32_e32 v13, s66, v13
	ds_read_b32 v32, v13 offset:6144
	s_waitcnt lgkmcnt(1)
	v_cvt_f32_f16_e32 v18, v21
	v_cvt_f32_f16_sdwa v19, v21 dst_sel:DWORD dst_unused:UNUSED_PAD src0_sel:WORD_1
	v_pk_mul_f32 v[18:19], v[18:19], s[38:39] op_sel_hi:[1,0]
	s_waitcnt vmcnt(10)
	v_cndmask_b32_e64 v22, 0, v33, s[40:41]
	s_waitcnt vmcnt(9)
	v_cndmask_b32_e64 v26, 0, v34, s[42:43]
	s_waitcnt vmcnt(7)
	v_cndmask_b32_e64 v23, 0, v35, s[40:41]
	v_pk_mul_f32 v[22:23], v[0:1], v[22:23]
	s_waitcnt vmcnt(6)
	v_cndmask_b32_e64 v27, 0, v36, s[42:43]
	v_pk_fma_f32 v[22:23], v[4:5], v[24:25], v[22:23]
	s_waitcnt vmcnt(2)
	v_cndmask_b32_e64 v24, 0, v30, s[42:43]
	v_pk_fma_f32 v[22:23], v[8:9], v[26:27], v[22:23]
	s_waitcnt vmcnt(0)
	v_cndmask_b32_e64 v25, 0, v38, s[42:43]
	v_pk_mul_f32 v[18:19], v[18:19], v[22:23]
	v_cndmask_b32_e64 v23, 0, v31, s[40:41]
	v_pk_mul_f32 v[18:19], v[18:19], s[76:77] op_sel_hi:[1,0]
	v_cndmask_b32_e64 v22, 0, v37, s[40:41]
	v_cvt_pk_f16_f32 v18, v18, v19
	ds_write_b32 v17, v18 offset:6144
	s_waitcnt lgkmcnt(1)
	v_cvt_f32_f16_e32 v18, v32
	v_cvt_f32_f16_sdwa v19, v32 dst_sel:DWORD dst_unused:UNUSED_PAD src0_sel:WORD_1
	v_pk_mul_f32 v[22:23], v[2:3], v[22:23]
	v_pk_mul_f32 v[18:19], v[18:19], s[38:39] op_sel_hi:[1,0]
	v_pk_fma_f32 v[22:23], v[6:7], v[28:29], v[22:23]
	s_nop 0
	v_pk_fma_f32 v[22:23], v[10:11], v[24:25], v[22:23]
	s_nop 0
	v_pk_mul_f32 v[18:19], v[18:19], v[22:23]
	s_nop 0
	v_pk_mul_f32 v[18:19], v[18:19], s[76:77] op_sel_hi:[1,0]
	s_nop 0
	v_cvt_pk_f16_f32 v17, v18, v19
	ds_write_b32 v13, v17 offset:6144
	v_add_u32_e32 v13, 0x2600, v16
	v_ashrrev_i32_e32 v17, 4, v13
	v_ashrrev_i32_e32 v13, 8, v13
	v_add_u32_e32 v13, v17, v13
	v_add_lshl_u32 v13, v16, v13, 2
	v_add_u32_e32 v16, 0, v13
	v_add_u32_e32 v13, s66, v13
	ds_write_b32 v16, v97 offset:38912
	ds_write_b32 v13, v97 offset:38912
	s_cbranch_scc0 .LBB0_699
	v_mov_b32_e32 v0, v12
	s_waitcnt lgkmcnt(0)
	s_barrier
	s_nop 0
	v_cmp_gt_i32_e64 s[40:41], s45, v0
	s_and_saveexec_b64 s[20:21], s[40:41]
	s_movk_i32 s10, 0xc000
	s_movk_i32 s12, 0xdff
	s_cbranch_execz .LBB0_703
	v_lshlrev_b32_e32 v1, 2, v0
	s_mov_b64 s[22:23], 0

; #define LAS __attribute__((address_space(3)))
; DI int rev4(int pp) { const unsigned br = __brev((unsigned)pp) >> 18; return (int)(((br & 0x2AAAu) >> 1) | ((br & 0x1555u) << 1)); }
; DI void pw_h(LAS hc* X, const f32x4* spec, int tid) {
; #pragma unroll 8
;     for (int r = 0; r < 16; ++r) {
;         const int k = tid + NTHR * r; const int pp = rev4(k);
;         const f32x4 sp = spec[k]; const cf P = (cf){sp[0], sp[1]} * 256.0f, Mq = (cf){sp[2], sp[3]} * 256.0f;
;         const hc zh = X[XI(pp)]; const cf z = (cf){(float)zh.x, (float)zh.y};
;         if (k == 0) { const cf y = cmul(z, P) + cmul((cf){z.x, -z.y}, Mq); X[XI(pp)] = (hc){(_Float16)y.x, (_Float16)y.y}; }
;         else { const int pm = rev4(16384 - k); const hc zmh = X[XI(pm)]; const cf zm = (cf){(float)zmh.x, (float)zmh.y};
;             const cf y = cmul(z, P) + cmul((cf){zm.x, -zm.y}, Mq);
;             const cf t = cmul((cf){zm.x, -zm.y}, P) + cmul(z, Mq);
;             X[XI(pp)] = (hc){(_Float16)y.x, (_Float16)y.y}; X[XI(pm)] = (hc){(_Float16)t.x, (_Float16)(-t.y)}; }
.LBB0_714:
	global_load_dwordx4 v[4:7], v[0:1], off
	v_add_u32_e32 v9, s4, v12
	v_add_u32_e32 v2, 0x2000, v9
	v_bfrev_b32_e32 v2, v2
	v_lshrrev_b32_e32 v3, 19, v2
	v_lshrrev_b32_e32 v2, 17, v2
	v_and_b32_e32 v2, 0x2aaa, v2
	v_and_or_b32 v10, v3, s89, v2
	s_movk_i32 s5, 0xe000
	v_cmp_ne_u32_e64 s[40:41], s5, v9
	v_add_u32_e32 v100, 0x2200, v9
	v_ashrrev_i32_e32 v101, 31, v100
	v_lshl_add_u64 v[100:101], v[100:101], 4, s[20:21]
	global_load_dwordx4 v[104:107], v[100:101], off
	v_add_u32_e32 v100, 0x2400, v9
	v_ashrrev_i32_e32 v101, 31, v100
	v_lshl_add_u64 v[100:101], v[100:101], 4, s[20:21]
	global_load_dwordx4 v[108:111], v[100:101], off
	v_add_u32_e32 v100, 0x2600, v9
	v_ashrrev_i32_e32 v101, 31, v100
	v_lshl_add_u64 v[100:101], v[100:101], 4, s[20:21]
	global_load_dwordx4 v[112:115], v[100:101], off
	v_add_u32_e32 v100, 0x2800, v9
	v_ashrrev_i32_e32 v101, 31, v100
	v_lshl_add_u64 v[100:101], v[100:101], 4, s[20:21]
	global_load_dwordx4 v[116:119], v[100:101], off
	v_add_u32_e32 v100, 0x2a00, v9
	v_ashrrev_i32_e32 v101, 31, v100
	v_lshl_add_u64 v[100:101], v[100:101], 4, s[20:21]
	global_load_dwordx4 v[120:123], v[100:101], off
	v_add_u32_e32 v100, 0x2c00, v9
	v_ashrrev_i32_e32 v101, 31, v100
	v_lshl_add_u64 v[100:101], v[100:101], 4, s[20:21]
	global_load_dwordx4 v[124:127], v[100:101], off
	v_add_u32_e32 v100, 0x2e00, v9
	v_ashrrev_i32_e32 v101, 31, v100
	v_lshl_add_u64 v[100:101], v[100:101], 4, s[20:21]
	global_load_dwordx4 v[128:131], v[100:101], off
	s_waitcnt vmcnt(7)
	v_pk_mul_f32 v[2:3], v[6:7], s[90:91] op_sel_hi:[1,0]
	v_lshl_add_u32 v6, v10, 2, 0
	v_lshrrev_b32_e32 v7, 2, v10
	v_lshrrev_b32_e32 v10, 6, v10
	v_and_b32_e32 v7, 0xffc, v7
	v_and_b32_e32 v10, 0xfc, v10
	v_add3_u32 v10, v6, v7, v10
	ds_read_b32 v7, v10
	v_pk_mul_f32 v[4:5], v[4:5], s[90:91] op_sel_hi:[1,0]
	s_waitcnt lgkmcnt(0)
	v_cvt_f32_f16_e32 v6, v7
	v_cvt_f32_f16_sdwa v7, v7 dst_sel:DWORD dst_unused:UNUSED_PAD src0_sel:WORD_1
	s_and_saveexec_b64 s[22:23], s[40:41]
	s_xor_b64 s[22:23], exec, s[22:23]
	s_cbranch_execz .LBB0_716
	v_add_u32_e32 v11, 0xe00, v8
	v_bfrev_b32_e32 v11, v11
	v_lshrrev_b32_e32 v13, 19, v11
	v_lshrrev_b32_e32 v11, 17, v11
	v_and_b32_e32 v11, 0x2aaa, v11
	v_and_or_b32 v11, v13, s89, v11
	v_lshl_add_u32 v13, v11, 2, 0
	v_lshrrev_b32_e32 v16, 2, v11
	v_lshrrev_b32_e32 v11, 6, v11
	v_and_b32_e32 v16, 0xffc, v16
	v_and_b32_e32 v11, 0xfc, v11
	v_add3_u32 v11, v13, v16, v11
	ds_read_b32 v13, v11
	v_pk_mul_f32 v[18:19], v[6:7], v[4:5] op_sel:[0,0] op_sel_hi:[0,1]
	s_waitcnt lgkmcnt(0)
	v_cvt_f32_f16_e32 v16, v13
	v_cvt_f32_f16_sdwa v17, -v13 dst_sel:DWORD dst_unused:UNUSED_PAD src0_sel:WORD_1
	v_pk_mul_f32 v[22:23], v[16:17], v[2:3] op_sel:[0,0] op_sel_hi:[0,1]
	v_pk_fma_f32 v[18:19], v[6:7], v[4:5], v[18:19] op_sel:[1,1,0] op_sel_hi:[1,0,1] neg_lo:[0,1,0]
	v_pk_fma_f32 v[22:23], v[16:17], v[2:3], v[22:23] op_sel:[1,1,0] op_sel_hi:[1,0,1] neg_lo:[0,1,0]
	v_pk_add_f32 v[18:19], v[18:19], v[22:23]
	v_pk_mul_f32 v[22:23], v[16:17], v[4:5] op_sel:[0,0] op_sel_hi:[0,1]
	v_pk_fma_f32 v[4:5], v[16:17], v[4:5], v[22:23] op_sel:[1,1,0] op_sel_hi:[1,0,1] neg_lo:[0,1,0]
	v_pk_mul_f32 v[16:17], v[6:7], v[2:3] op_sel:[0,0] op_sel_hi:[0,1]
	v_pk_fma_f32 v[2:3], v[6:7], v[2:3], v[16:17] op_sel:[1,1,0] op_sel_hi:[1,0,1] neg_lo:[0,1,0]
	s_nop 0
	v_pk_add_f32 v[2:3], v[4:5], v[2:3]
	v_cvt_pk_f16_f32 v4, v18, v19
	v_cvt_pk_f16_f32 v2, v2, -v3
	ds_write_b32 v10, v4
	ds_write_b32 v11, v2

; DI int rev4(int pp) { const unsigned br = __brev((unsigned)pp) >> 18; return (int)(((br & 0x2AAAu) >> 1) | ((br & 0x1555u) << 1)); }
; DI void pw_h(LAS hc* X, const f32x4* spec, int tid) {
;     ...
;     for (int r = 0; r < 16; ++r) {
;         const int k = tid + NTHR * r; const int pp = rev4(k);
;         const f32x4 sp = spec[k]; const cf P = (cf){sp[0], sp[1]} * 256.0f, Mq = (cf){sp[2], sp[3]} * 256.0f;
;         const hc zh = X[XI(pp)]; const cf z = (cf){(float)zh.x, (float)zh.y};
;         if (k == 0) { const cf y = cmul(z, P) + cmul((cf){z.x, -z.y}, Mq); X[XI(pp)] = (hc){(_Float16)y.x, (_Float16)y.y}; }
;         else { const int pm = rev4(16384 - k); const hc zmh = X[XI(pm)]; const cf zm = (cf){(float)zmh.x, (float)zmh.y};
;             const cf y = cmul(z, P) + cmul((cf){zm.x, -zm.y}, Mq);
;             const cf t = cmul((cf){zm.x, -zm.y}, P) + cmul(z, Mq);
;             X[XI(pp)] = (hc){(_Float16)y.x, (_Float16)y.y}; X[XI(pm)] = (hc){(_Float16)t.x, (_Float16)(-t.y)}; }
.LBB0_718:
	s_or_b64 exec, exec, s[22:23]
	v_add_u32_e32 v2, 0x2200, v9
	v_bfrev_b32_e32 v3, v2
	v_lshrrev_b32_e32 v4, 19, v3
	v_lshrrev_b32_e32 v3, 17, v3
	v_and_b32_e32 v3, 0x2aaa, v3
	v_and_or_b32 v10, v4, s89, v3
	s_movk_i32 s5, 0xde00
	v_cmp_ne_u32_e64 s[40:41], s5, v9
	s_waitcnt vmcnt(6)
	v_mov_b32_e32 v4, v104
	v_mov_b32_e32 v5, v105
	v_mov_b32_e32 v6, v106
	v_mov_b32_e32 v7, v107
	v_pk_mul_f32 v[2:3], v[6:7], s[90:91] op_sel_hi:[1,0]
	v_lshl_add_u32 v6, v10, 2, 0
	v_lshrrev_b32_e32 v7, 2, v10
	v_lshrrev_b32_e32 v10, 6, v10
	v_and_b32_e32 v7, 0xffc, v7
	v_and_b32_e32 v10, 0xfc, v10
	v_add3_u32 v10, v6, v7, v10
	ds_read_b32 v7, v10
	v_pk_mul_f32 v[4:5], v[4:5], s[90:91] op_sel_hi:[1,0]
	s_waitcnt lgkmcnt(0)
	v_cvt_f32_f16_e32 v6, v7
	v_cvt_f32_f16_sdwa v7, v7 dst_sel:DWORD dst_unused:UNUSED_PAD src0_sel:WORD_1
	s_and_saveexec_b64 s[22:23], s[40:41]
	s_xor_b64 s[22:23], exec, s[22:23]
	s_cbranch_execz .LBB0_720
	v_add_u32_e32 v11, 0xc00, v8
	v_bfrev_b32_e32 v11, v11
	v_lshrrev_b32_e32 v13, 19, v11
	v_lshrrev_b32_e32 v11, 17, v11
	v_and_b32_e32 v11, 0x2aaa, v11
	v_and_or_b32 v11, v13, s89, v11
	v_lshl_add_u32 v13, v11, 2, 0
	v_lshrrev_b32_e32 v16, 2, v11
	v_lshrrev_b32_e32 v11, 6, v11
	v_and_b32_e32 v16, 0xffc, v16
	v_and_b32_e32 v11, 0xfc, v11
	v_add3_u32 v11, v13, v16, v11
	ds_read_b32 v13, v11
	v_pk_mul_f32 v[18:19], v[6:7], v[4:5] op_sel:[0,0] op_sel_hi:[0,1]
	s_waitcnt lgkmcnt(0)
	v_cvt_f32_f16_e32 v16, v13
	v_cvt_f32_f16_sdwa v17, -v13 dst_sel:DWORD dst_unused:UNUSED_PAD src0_sel:WORD_1
	v_pk_mul_f32 v[22:23], v[16:17], v[2:3] op_sel:[0,0] op_sel_hi:[0,1]
	v_pk_fma_f32 v[18:19], v[6:7], v[4:5], v[18:19] op_sel:[1,1,0] op_sel_hi:[1,0,1] neg_lo:[0,1,0]
	v_pk_fma_f32 v[22:23], v[16:17], v[2:3], v[22:23] op_sel:[1,1,0] op_sel_hi:[1,0,1] neg_lo:[0,1,0]
	v_pk_add_f32 v[18:19], v[18:19], v[22:23]
	v_pk_mul_f32 v[22:23], v[16:17], v[4:5] op_sel:[0,0] op_sel_hi:[0,1]
	v_pk_fma_f32 v[4:5], v[16:17], v[4:5], v[22:23] op_sel:[1,1,0] op_sel_hi:[1,0,1] neg_lo:[0,1,0]
	v_pk_mul_f32 v[16:17], v[6:7], v[2:3] op_sel:[0,0] op_sel_hi:[0,1]
	v_pk_fma_f32 v[2:3], v[6:7], v[2:3], v[16:17] op_sel:[1,1,0] op_sel_hi:[1,0,1] neg_lo:[0,1,0]
	s_nop 0
	v_pk_add_f32 v[2:3], v[4:5], v[2:3]
	v_cvt_pk_f16_f32 v4, v18, v19
	v_cvt_pk_f16_f32 v2, v2, -v3
	ds_write_b32 v10, v4
	ds_write_b32 v11, v2

; DI int rev4(int pp) { const unsigned br = __brev((unsigned)pp) >> 18; return (int)(((br & 0x2AAAu) >> 1) | ((br & 0x1555u) << 1)); }
; DI void pw_h(LAS hc* X, const f32x4* spec, int tid) {
;     ...
;     for (int r = 0; r < 16; ++r) {
;         const int k = tid + NTHR * r; const int pp = rev4(k);
;         const f32x4 sp = spec[k]; const cf P = (cf){sp[0], sp[1]} * 256.0f, Mq = (cf){sp[2], sp[3]} * 256.0f;
;         const hc zh = X[XI(pp)]; const cf z = (cf){(float)zh.x, (float)zh.y};
;         if (k == 0) { const cf y = cmul(z, P) + cmul((cf){z.x, -z.y}, Mq); X[XI(pp)] = (hc){(_Float16)y.x, (_Float16)y.y}; }
;         else { const int pm = rev4(16384 - k); const hc zmh = X[XI(pm)]; const cf zm = (cf){(float)zmh.x, (float)zmh.y};
;             const cf y = cmul(z, P) + cmul((cf){zm.x, -zm.y}, Mq);
;             const cf t = cmul((cf){zm.x, -zm.y}, P) + cmul(z, Mq);
;             X[XI(pp)] = (hc){(_Float16)y.x, (_Float16)y.y}; X[XI(pm)] = (hc){(_Float16)t.x, (_Float16)(-t.y)}; }
.LBB0_722:
	s_or_b64 exec, exec, s[22:23]
	v_add_u32_e32 v2, 0x2400, v9
	v_bfrev_b32_e32 v3, v2
	v_lshrrev_b32_e32 v4, 19, v3
	v_lshrrev_b32_e32 v3, 17, v3
	v_and_b32_e32 v3, 0x2aaa, v3
	v_and_or_b32 v10, v4, s89, v3
	s_movk_i32 s5, 0xdc00
	v_cmp_ne_u32_e64 s[40:41], s5, v9
	s_waitcnt vmcnt(5)
	v_mov_b32_e32 v4, v108
	v_mov_b32_e32 v5, v109
	v_mov_b32_e32 v6, v110
	v_mov_b32_e32 v7, v111
	v_pk_mul_f32 v[2:3], v[6:7], s[90:91] op_sel_hi:[1,0]
	v_lshl_add_u32 v6, v10, 2, 0
	v_lshrrev_b32_e32 v7, 2, v10
	v_lshrrev_b32_e32 v10, 6, v10
	v_and_b32_e32 v7, 0xffc, v7
	v_and_b32_e32 v10, 0xfc, v10
	v_add3_u32 v10, v6, v7, v10
	ds_read_b32 v7, v10
	v_pk_mul_f32 v[4:5], v[4:5], s[90:91] op_sel_hi:[1,0]
	s_waitcnt lgkmcnt(0)
	v_cvt_f32_f16_e32 v6, v7
	v_cvt_f32_f16_sdwa v7, v7 dst_sel:DWORD dst_unused:UNUSED_PAD src0_sel:WORD_1
	s_and_saveexec_b64 s[22:23], s[40:41]
	s_xor_b64 s[22:23], exec, s[22:23]
	s_cbranch_execz .LBB0_724
	v_add_u32_e32 v11, 0xa00, v8
	v_bfrev_b32_e32 v11, v11
	v_lshrrev_b32_e32 v13, 19, v11
	v_lshrrev_b32_e32 v11, 17, v11
	v_and_b32_e32 v11, 0x2aaa, v11
	v_and_or_b32 v11, v13, s89, v11
	v_lshl_add_u32 v13, v11, 2, 0
	v_lshrrev_b32_e32 v16, 2, v11
	v_lshrrev_b32_e32 v11, 6, v11
	v_and_b32_e32 v16, 0xffc, v16
	v_and_b32_e32 v11, 0xfc, v11
	v_add3_u32 v11, v13, v16, v11
	ds_read_b32 v13, v11
	v_pk_mul_f32 v[18:19], v[6:7], v[4:5] op_sel:[0,0] op_sel_hi:[0,1]
	s_waitcnt lgkmcnt(0)
	v_cvt_f32_f16_e32 v16, v13
	v_cvt_f32_f16_sdwa v17, -v13 dst_sel:DWORD dst_unused:UNUSED_PAD src0_sel:WORD_1
	v_pk_mul_f32 v[22:23], v[16:17], v[2:3] op_sel:[0,0] op_sel_hi:[0,1]
	v_pk_fma_f32 v[18:19], v[6:7], v[4:5], v[18:19] op_sel:[1,1,0] op_sel_hi:[1,0,1] neg_lo:[0,1,0]
	v_pk_fma_f32 v[22:23], v[16:17], v[2:3], v[22:23] op_sel:[1,1,0] op_sel_hi:[1,0,1] neg_lo:[0,1,0]
	v_pk_add_f32 v[18:19], v[18:19], v[22:23]
	v_pk_mul_f32 v[22:23], v[16:17], v[4:5] op_sel:[0,0] op_sel_hi:[0,1]
	v_pk_fma_f32 v[4:5], v[16:17], v[4:5], v[22:23] op_sel:[1,1,0] op_sel_hi:[1,0,1] neg_lo:[0,1,0]
	v_pk_mul_f32 v[16:17], v[6:7], v[2:3] op_sel:[0,0] op_sel_hi:[0,1]
	v_pk_fma_f32 v[2:3], v[6:7], v[2:3], v[16:17] op_sel:[1,1,0] op_sel_hi:[1,0,1] neg_lo:[0,1,0]
	s_nop 0
	v_pk_add_f32 v[2:3], v[4:5], v[2:3]
	v_cvt_pk_f16_f32 v4, v18, v19
	v_cvt_pk_f16_f32 v2, v2, -v3
	ds_write_b32 v10, v4
	ds_write_b32 v11, v2

; DI int rev4(int pp) { const unsigned br = __brev((unsigned)pp) >> 18; return (int)(((br & 0x2AAAu) >> 1) | ((br & 0x1555u) << 1)); }
; DI void pw_h(LAS hc* X, const f32x4* spec, int tid) {
;     ...
;     for (int r = 0; r < 16; ++r) {
;         const int k = tid + NTHR * r; const int pp = rev4(k);
;         const f32x4 sp = spec[k]; const cf P = (cf){sp[0], sp[1]} * 256.0f, Mq = (cf){sp[2], sp[3]} * 256.0f;
;         const hc zh = X[XI(pp)]; const cf z = (cf){(float)zh.x, (float)zh.y};
;         if (k == 0) { const cf y = cmul(z, P) + cmul((cf){z.x, -z.y}, Mq); X[XI(pp)] = (hc){(_Float16)y.x, (_Float16)y.y}; }
;         else { const int pm = rev4(16384 - k); const hc zmh = X[XI(pm)]; const cf zm = (cf){(float)zmh.x, (float)zmh.y};
;             const cf y = cmul(z, P) + cmul((cf){zm.x, -zm.y}, Mq);
;             const cf t = cmul((cf){zm.x, -zm.y}, P) + cmul(z, Mq);
;             X[XI(pp)] = (hc){(_Float16)y.x, (_Float16)y.y}; X[XI(pm)] = (hc){(_Float16)t.x, (_Float16)(-t.y)}; }
.LBB0_726:
	s_or_b64 exec, exec, s[22:23]
	v_add_u32_e32 v2, 0x2600, v9
	v_bfrev_b32_e32 v3, v2
	v_lshrrev_b32_e32 v4, 19, v3
	v_lshrrev_b32_e32 v3, 17, v3
	v_and_b32_e32 v3, 0x2aaa, v3
	v_and_or_b32 v10, v4, s89, v3
	s_movk_i32 s5, 0xda00
	v_cmp_ne_u32_e64 s[40:41], s5, v9
	s_waitcnt vmcnt(4)
	v_mov_b32_e32 v4, v112
	v_mov_b32_e32 v5, v113
	v_mov_b32_e32 v6, v114
	v_mov_b32_e32 v7, v115
	v_pk_mul_f32 v[2:3], v[6:7], s[90:91] op_sel_hi:[1,0]
	v_lshl_add_u32 v6, v10, 2, 0
	v_lshrrev_b32_e32 v7, 2, v10
	v_lshrrev_b32_e32 v10, 6, v10
	v_and_b32_e32 v7, 0xffc, v7
	v_and_b32_e32 v10, 0xfc, v10
	v_add3_u32 v10, v6, v7, v10
	ds_read_b32 v7, v10
	v_pk_mul_f32 v[4:5], v[4:5], s[90:91] op_sel_hi:[1,0]
	s_waitcnt lgkmcnt(0)
	v_cvt_f32_f16_e32 v6, v7
	v_cvt_f32_f16_sdwa v7, v7 dst_sel:DWORD dst_unused:UNUSED_PAD src0_sel:WORD_1
	s_and_saveexec_b64 s[22:23], s[40:41]
	s_xor_b64 s[22:23], exec, s[22:23]
	s_cbranch_execz .LBB0_728
	v_add_u32_e32 v11, 0x800, v8
	v_bfrev_b32_e32 v11, v11
	v_lshrrev_b32_e32 v13, 19, v11
	v_lshrrev_b32_e32 v11, 17, v11
	v_and_b32_e32 v11, 0x2aaa, v11
	v_and_or_b32 v11, v13, s89, v11
	v_lshl_add_u32 v13, v11, 2, 0
	v_lshrrev_b32_e32 v16, 2, v11
	v_lshrrev_b32_e32 v11, 6, v11
	v_and_b32_e32 v16, 0xffc, v16
	v_and_b32_e32 v11, 0xfc, v11
	v_add3_u32 v11, v13, v16, v11
	ds_read_b32 v13, v11
	v_pk_mul_f32 v[18:19], v[6:7], v[4:5] op_sel:[0,0] op_sel_hi:[0,1]
	s_waitcnt lgkmcnt(0)
	v_cvt_f32_f16_e32 v16, v13
	v_cvt_f32_f16_sdwa v17, -v13 dst_sel:DWORD dst_unused:UNUSED_PAD src0_sel:WORD_1
	v_pk_mul_f32 v[22:23], v[16:17], v[2:3] op_sel:[0,0] op_sel_hi:[0,1]
	v_pk_fma_f32 v[18:19], v[6:7], v[4:5], v[18:19] op_sel:[1,1,0] op_sel_hi:[1,0,1] neg_lo:[0,1,0]
	v_pk_fma_f32 v[22:23], v[16:17], v[2:3], v[22:23] op_sel:[1,1,0] op_sel_hi:[1,0,1] neg_lo:[0,1,0]
	v_pk_add_f32 v[18:19], v[18:19], v[22:23]
	v_pk_mul_f32 v[22:23], v[16:17], v[4:5] op_sel:[0,0] op_sel_hi:[0,1]
	v_pk_fma_f32 v[4:5], v[16:17], v[4:5], v[22:23] op_sel:[1,1,0] op_sel_hi:[1,0,1] neg_lo:[0,1,0]
	v_pk_mul_f32 v[16:17], v[6:7], v[2:3] op_sel:[0,0] op_sel_hi:[0,1]
	v_pk_fma_f32 v[2:3], v[6:7], v[2:3], v[16:17] op_sel:[1,1,0] op_sel_hi:[1,0,1] neg_lo:[0,1,0]
	s_nop 0
	v_pk_add_f32 v[2:3], v[4:5], v[2:3]
	v_cvt_pk_f16_f32 v4, v18, v19
	v_cvt_pk_f16_f32 v2, v2, -v3
	ds_write_b32 v10, v4
	ds_write_b32 v11, v2

; DI int rev4(int pp) { const unsigned br = __brev((unsigned)pp) >> 18; return (int)(((br & 0x2AAAu) >> 1) | ((br & 0x1555u) << 1)); }
; DI void pw_h(LAS hc* X, const f32x4* spec, int tid) {
;     ...
;     for (int r = 0; r < 16; ++r) {
;         const int k = tid + NTHR * r; const int pp = rev4(k);
;         const f32x4 sp = spec[k]; const cf P = (cf){sp[0], sp[1]} * 256.0f, Mq = (cf){sp[2], sp[3]} * 256.0f;
;         const hc zh = X[XI(pp)]; const cf z = (cf){(float)zh.x, (float)zh.y};
;         if (k == 0) { const cf y = cmul(z, P) + cmul((cf){z.x, -z.y}, Mq); X[XI(pp)] = (hc){(_Float16)y.x, (_Float16)y.y}; }
;         else { const int pm = rev4(16384 - k); const hc zmh = X[XI(pm)]; const cf zm = (cf){(float)zmh.x, (float)zmh.y};
;             const cf y = cmul(z, P) + cmul((cf){zm.x, -zm.y}, Mq);
;             const cf t = cmul((cf){zm.x, -zm.y}, P) + cmul(z, Mq);
;             X[XI(pp)] = (hc){(_Float16)y.x, (_Float16)y.y}; X[XI(pm)] = (hc){(_Float16)t.x, (_Float16)(-t.y)}; }
.LBB0_730:
	s_or_b64 exec, exec, s[22:23]
	v_add_u32_e32 v2, 0x2800, v9
	v_bfrev_b32_e32 v3, v2
	v_lshrrev_b32_e32 v4, 19, v3
	v_lshrrev_b32_e32 v3, 17, v3
	v_and_b32_e32 v3, 0x2aaa, v3
	v_and_or_b32 v10, v4, s89, v3
	s_movk_i32 s5, 0xd800
	v_cmp_ne_u32_e64 s[40:41], s5, v9
	s_waitcnt vmcnt(3)
	v_mov_b32_e32 v4, v116
	v_mov_b32_e32 v5, v117
	v_mov_b32_e32 v6, v118
	v_mov_b32_e32 v7, v119
	v_pk_mul_f32 v[2:3], v[6:7], s[90:91] op_sel_hi:[1,0]
	v_lshl_add_u32 v6, v10, 2, 0
	v_lshrrev_b32_e32 v7, 2, v10
	v_lshrrev_b32_e32 v10, 6, v10
	v_and_b32_e32 v7, 0xffc, v7
	v_and_b32_e32 v10, 0xfc, v10
	v_add3_u32 v10, v6, v7, v10
	ds_read_b32 v7, v10
	v_pk_mul_f32 v[4:5], v[4:5], s[90:91] op_sel_hi:[1,0]
	s_waitcnt lgkmcnt(0)
	v_cvt_f32_f16_e32 v6, v7
	v_cvt_f32_f16_sdwa v7, v7 dst_sel:DWORD dst_unused:UNUSED_PAD src0_sel:WORD_1
	s_and_saveexec_b64 s[22:23], s[40:41]
	s_xor_b64 s[22:23], exec, s[22:23]
	s_cbranch_execz .LBB0_732
	v_add_u32_e32 v11, 0x600, v8
	v_bfrev_b32_e32 v11, v11
	v_lshrrev_b32_e32 v13, 19, v11
	v_lshrrev_b32_e32 v11, 17, v11
	v_and_b32_e32 v11, 0x2aaa, v11
	v_and_or_b32 v11, v13, s89, v11
	v_lshl_add_u32 v13, v11, 2, 0
	v_lshrrev_b32_e32 v16, 2, v11
	v_lshrrev_b32_e32 v11, 6, v11
	v_and_b32_e32 v16, 0xffc, v16
	v_and_b32_e32 v11, 0xfc, v11
	v_add3_u32 v11, v13, v16, v11
	ds_read_b32 v13, v11
	v_pk_mul_f32 v[18:19], v[6:7], v[4:5] op_sel:[0,0] op_sel_hi:[0,1]
	s_waitcnt lgkmcnt(0)
	v_cvt_f32_f16_e32 v16, v13
	v_cvt_f32_f16_sdwa v17, -v13 dst_sel:DWORD dst_unused:UNUSED_PAD src0_sel:WORD_1
	v_pk_mul_f32 v[22:23], v[16:17], v[2:3] op_sel:[0,0] op_sel_hi:[0,1]
	v_pk_fma_f32 v[18:19], v[6:7], v[4:5], v[18:19] op_sel:[1,1,0] op_sel_hi:[1,0,1] neg_lo:[0,1,0]
	v_pk_fma_f32 v[22:23], v[16:17], v[2:3], v[22:23] op_sel:[1,1,0] op_sel_hi:[1,0,1] neg_lo:[0,1,0]
	v_pk_add_f32 v[18:19], v[18:19], v[22:23]
	v_pk_mul_f32 v[22:23], v[16:17], v[4:5] op_sel:[0,0] op_sel_hi:[0,1]
	v_pk_fma_f32 v[4:5], v[16:17], v[4:5], v[22:23] op_sel:[1,1,0] op_sel_hi:[1,0,1] neg_lo:[0,1,0]
	v_pk_mul_f32 v[16:17], v[6:7], v[2:3] op_sel:[0,0] op_sel_hi:[0,1]
	v_pk_fma_f32 v[2:3], v[6:7], v[2:3], v[16:17] op_sel:[1,1,0] op_sel_hi:[1,0,1] neg_lo:[0,1,0]
	s_nop 0
	v_pk_add_f32 v[2:3], v[4:5], v[2:3]
	v_cvt_pk_f16_f32 v4, v18, v19
	v_cvt_pk_f16_f32 v2, v2, -v3
	ds_write_b32 v10, v4
	ds_write_b32 v11, v2

; DI int rev4(int pp) { const unsigned br = __brev((unsigned)pp) >> 18; return (int)(((br & 0x2AAAu) >> 1) | ((br & 0x1555u) << 1)); }
; DI void pw_h(LAS hc* X, const f32x4* spec, int tid) {
;     ...
;     for (int r = 0; r < 16; ++r) {
;         const int k = tid + NTHR * r; const int pp = rev4(k);
;         const f32x4 sp = spec[k]; const cf P = (cf){sp[0], sp[1]} * 256.0f, Mq = (cf){sp[2], sp[3]} * 256.0f;
;         const hc zh = X[XI(pp)]; const cf z = (cf){(float)zh.x, (float)zh.y};
;         if (k == 0) { const cf y = cmul(z, P) + cmul((cf){z.x, -z.y}, Mq); X[XI(pp)] = (hc){(_Float16)y.x, (_Float16)y.y}; }
;         else { const int pm = rev4(16384 - k); const hc zmh = X[XI(pm)]; const cf zm = (cf){(float)zmh.x, (float)zmh.y};
;             const cf y = cmul(z, P) + cmul((cf){zm.x, -zm.y}, Mq);
;             const cf t = cmul((cf){zm.x, -zm.y}, P) + cmul(z, Mq);
;             X[XI(pp)] = (hc){(_Float16)y.x, (_Float16)y.y}; X[XI(pm)] = (hc){(_Float16)t.x, (_Float16)(-t.y)}; }
.LBB0_734:
	s_or_b64 exec, exec, s[22:23]
	v_add_u32_e32 v2, 0x2a00, v9
	v_bfrev_b32_e32 v3, v2
	v_lshrrev_b32_e32 v4, 19, v3
	v_lshrrev_b32_e32 v3, 17, v3
	v_and_b32_e32 v3, 0x2aaa, v3
	v_and_or_b32 v10, v4, s89, v3
	s_movk_i32 s5, 0xd600
	v_cmp_ne_u32_e64 s[40:41], s5, v9
	s_waitcnt vmcnt(2)
	v_mov_b32_e32 v4, v120
	v_mov_b32_e32 v5, v121
	v_mov_b32_e32 v6, v122
	v_mov_b32_e32 v7, v123
	v_pk_mul_f32 v[2:3], v[6:7], s[90:91] op_sel_hi:[1,0]
	v_lshl_add_u32 v6, v10, 2, 0
	v_lshrrev_b32_e32 v7, 2, v10
	v_lshrrev_b32_e32 v10, 6, v10
	v_and_b32_e32 v7, 0xffc, v7
	v_and_b32_e32 v10, 0xfc, v10
	v_add3_u32 v10, v6, v7, v10
	ds_read_b32 v7, v10
	v_pk_mul_f32 v[4:5], v[4:5], s[90:91] op_sel_hi:[1,0]
	s_waitcnt lgkmcnt(0)
	v_cvt_f32_f16_e32 v6, v7
	v_cvt_f32_f16_sdwa v7, v7 dst_sel:DWORD dst_unused:UNUSED_PAD src0_sel:WORD_1
	s_and_saveexec_b64 s[22:23], s[40:41]
	s_xor_b64 s[22:23], exec, s[22:23]
	s_cbranch_execz .LBB0_736
	v_add_u32_e32 v11, 0x400, v8
	v_bfrev_b32_e32 v11, v11
	v_lshrrev_b32_e32 v13, 19, v11
	v_lshrrev_b32_e32 v11, 17, v11
	v_and_b32_e32 v11, 0x2aaa, v11
	v_and_or_b32 v11, v13, s89, v11
	v_lshl_add_u32 v13, v11, 2, 0
	v_lshrrev_b32_e32 v16, 2, v11
	v_lshrrev_b32_e32 v11, 6, v11
	v_and_b32_e32 v16, 0xffc, v16
	v_and_b32_e32 v11, 0xfc, v11
	v_add3_u32 v11, v13, v16, v11
	ds_read_b32 v13, v11
	v_pk_mul_f32 v[18:19], v[6:7], v[4:5] op_sel:[0,0] op_sel_hi:[0,1]
	s_waitcnt lgkmcnt(0)
	v_cvt_f32_f16_e32 v16, v13
	v_cvt_f32_f16_sdwa v17, -v13 dst_sel:DWORD dst_unused:UNUSED_PAD src0_sel:WORD_1
	v_pk_mul_f32 v[22:23], v[16:17], v[2:3] op_sel:[0,0] op_sel_hi:[0,1]
	v_pk_fma_f32 v[18:19], v[6:7], v[4:5], v[18:19] op_sel:[1,1,0] op_sel_hi:[1,0,1] neg_lo:[0,1,0]
	v_pk_fma_f32 v[22:23], v[16:17], v[2:3], v[22:23] op_sel:[1,1,0] op_sel_hi:[1,0,1] neg_lo:[0,1,0]
	v_pk_add_f32 v[18:19], v[18:19], v[22:23]
	v_pk_mul_f32 v[22:23], v[16:17], v[4:5] op_sel:[0,0] op_sel_hi:[0,1]
	v_pk_fma_f32 v[4:5], v[16:17], v[4:5], v[22:23] op_sel:[1,1,0] op_sel_hi:[1,0,1] neg_lo:[0,1,0]
	v_pk_mul_f32 v[16:17], v[6:7], v[2:3] op_sel:[0,0] op_sel_hi:[0,1]
	v_pk_fma_f32 v[2:3], v[6:7], v[2:3], v[16:17] op_sel:[1,1,0] op_sel_hi:[1,0,1] neg_lo:[0,1,0]
	s_nop 0
	v_pk_add_f32 v[2:3], v[4:5], v[2:3]
	v_cvt_pk_f16_f32 v4, v18, v19
	v_cvt_pk_f16_f32 v2, v2, -v3
	ds_write_b32 v10, v4
	ds_write_b32 v11, v2

; DI int rev4(int pp) { const unsigned br = __brev((unsigned)pp) >> 18; return (int)(((br & 0x2AAAu) >> 1) | ((br & 0x1555u) << 1)); }
; DI void pw_h(LAS hc* X, const f32x4* spec, int tid) {
;     ...
;     for (int r = 0; r < 16; ++r) {
;         const int k = tid + NTHR * r; const int pp = rev4(k);
;         const f32x4 sp = spec[k]; const cf P = (cf){sp[0], sp[1]} * 256.0f, Mq = (cf){sp[2], sp[3]} * 256.0f;
;         const hc zh = X[XI(pp)]; const cf z = (cf){(float)zh.x, (float)zh.y};
;         if (k == 0) { const cf y = cmul(z, P) + cmul((cf){z.x, -z.y}, Mq); X[XI(pp)] = (hc){(_Float16)y.x, (_Float16)y.y}; }
;         else { const int pm = rev4(16384 - k); const hc zmh = X[XI(pm)]; const cf zm = (cf){(float)zmh.x, (float)zmh.y};
;             const cf y = cmul(z, P) + cmul((cf){zm.x, -zm.y}, Mq);
;             const cf t = cmul((cf){zm.x, -zm.y}, P) + cmul(z, Mq);
;             X[XI(pp)] = (hc){(_Float16)y.x, (_Float16)y.y}; X[XI(pm)] = (hc){(_Float16)t.x, (_Float16)(-t.y)}; }
.LBB0_738:
	s_or_b64 exec, exec, s[22:23]
	v_add_u32_e32 v2, 0x2c00, v9
	v_bfrev_b32_e32 v3, v2
	v_lshrrev_b32_e32 v4, 19, v3
	v_lshrrev_b32_e32 v3, 17, v3
	v_and_b32_e32 v3, 0x2aaa, v3
	v_and_or_b32 v10, v4, s89, v3
	v_cmp_ne_u32_e64 s[40:41], s96, v9
	s_waitcnt vmcnt(1)
	v_mov_b32_e32 v4, v124
	v_mov_b32_e32 v5, v125
	v_mov_b32_e32 v6, v126
	v_mov_b32_e32 v7, v127
	v_pk_mul_f32 v[2:3], v[6:7], s[90:91] op_sel_hi:[1,0]
	v_lshl_add_u32 v6, v10, 2, 0
	v_lshrrev_b32_e32 v7, 2, v10
	v_lshrrev_b32_e32 v10, 6, v10
	v_and_b32_e32 v7, 0xffc, v7
	v_and_b32_e32 v10, 0xfc, v10
	v_add3_u32 v10, v6, v7, v10
	ds_read_b32 v7, v10
	v_pk_mul_f32 v[4:5], v[4:5], s[90:91] op_sel_hi:[1,0]
	s_waitcnt lgkmcnt(0)
	v_cvt_f32_f16_e32 v6, v7
	v_cvt_f32_f16_sdwa v7, v7 dst_sel:DWORD dst_unused:UNUSED_PAD src0_sel:WORD_1
	s_and_saveexec_b64 s[22:23], s[40:41]
	s_xor_b64 s[22:23], exec, s[22:23]
	s_cbranch_execz .LBB0_740
	v_add_u32_e32 v11, 0x200, v8
	v_bfrev_b32_e32 v11, v11
	v_lshrrev_b32_e32 v13, 19, v11
	v_lshrrev_b32_e32 v11, 17, v11
	v_and_b32_e32 v11, 0x2aaa, v11
	v_and_or_b32 v11, v13, s89, v11
	v_lshl_add_u32 v13, v11, 2, 0
	v_lshrrev_b32_e32 v16, 2, v11
	v_lshrrev_b32_e32 v11, 6, v11
	v_and_b32_e32 v16, 0xffc, v16
	v_and_b32_e32 v11, 0xfc, v11
	v_add3_u32 v11, v13, v16, v11
	ds_read_b32 v13, v11
	v_pk_mul_f32 v[18:19], v[6:7], v[4:5] op_sel:[0,0] op_sel_hi:[0,1]
	s_waitcnt lgkmcnt(0)
	v_cvt_f32_f16_e32 v16, v13
	v_cvt_f32_f16_sdwa v17, -v13 dst_sel:DWORD dst_unused:UNUSED_PAD src0_sel:WORD_1
	v_pk_mul_f32 v[22:23], v[16:17], v[2:3] op_sel:[0,0] op_sel_hi:[0,1]
	v_pk_fma_f32 v[18:19], v[6:7], v[4:5], v[18:19] op_sel:[1,1,0] op_sel_hi:[1,0,1] neg_lo:[0,1,0]
	v_pk_fma_f32 v[22:23], v[16:17], v[2:3], v[22:23] op_sel:[1,1,0] op_sel_hi:[1,0,1] neg_lo:[0,1,0]
	v_pk_add_f32 v[18:19], v[18:19], v[22:23]
	v_pk_mul_f32 v[22:23], v[16:17], v[4:5] op_sel:[0,0] op_sel_hi:[0,1]
	v_pk_fma_f32 v[4:5], v[16:17], v[4:5], v[22:23] op_sel:[1,1,0] op_sel_hi:[1,0,1] neg_lo:[0,1,0]
	v_pk_mul_f32 v[16:17], v[6:7], v[2:3] op_sel:[0,0] op_sel_hi:[0,1]
	v_pk_fma_f32 v[2:3], v[6:7], v[2:3], v[16:17] op_sel:[1,1,0] op_sel_hi:[1,0,1] neg_lo:[0,1,0]
	s_nop 0
	v_pk_add_f32 v[2:3], v[4:5], v[2:3]
	v_cvt_pk_f16_f32 v4, v18, v19
	v_cvt_pk_f16_f32 v2, v2, -v3
	ds_write_b32 v10, v4
	ds_write_b32 v11, v2

; DI int rev4(int pp) { const unsigned br = __brev((unsigned)pp) >> 18; return (int)(((br & 0x2AAAu) >> 1) | ((br & 0x1555u) << 1)); }
; DI void pw_h(LAS hc* X, const f32x4* spec, int tid) {
;     ...
;     for (int r = 0; r < 16; ++r) {
;         const int k = tid + NTHR * r; const int pp = rev4(k);
;         const f32x4 sp = spec[k]; const cf P = (cf){sp[0], sp[1]} * 256.0f, Mq = (cf){sp[2], sp[3]} * 256.0f;
;         const hc zh = X[XI(pp)]; const cf z = (cf){(float)zh.x, (float)zh.y};
;         if (k == 0) { const cf y = cmul(z, P) + cmul((cf){z.x, -z.y}, Mq); X[XI(pp)] = (hc){(_Float16)y.x, (_Float16)y.y}; }
;         else { const int pm = rev4(16384 - k); const hc zmh = X[XI(pm)]; const cf zm = (cf){(float)zmh.x, (float)zmh.y};
;             const cf y = cmul(z, P) + cmul((cf){zm.x, -zm.y}, Mq);
;             const cf t = cmul((cf){zm.x, -zm.y}, P) + cmul(z, Mq);
;             X[XI(pp)] = (hc){(_Float16)y.x, (_Float16)y.y}; X[XI(pm)] = (hc){(_Float16)t.x, (_Float16)(-t.y)}; }
.LBB0_742:
	s_or_b64 exec, exec, s[22:23]
	v_add_u32_e32 v2, 0x2e00, v9
	v_bfrev_b32_e32 v3, v2
	v_lshrrev_b32_e32 v4, 19, v3
	v_lshrrev_b32_e32 v3, 17, v3
	v_and_b32_e32 v3, 0x2aaa, v3
	v_and_or_b32 v10, v4, s89, v3
	v_cmp_ne_u32_e64 s[40:41], s84, v9
	s_waitcnt vmcnt(0)
	v_mov_b32_e32 v4, v128
	v_mov_b32_e32 v5, v129
	v_mov_b32_e32 v6, v130
	v_mov_b32_e32 v7, v131
	v_pk_mul_f32 v[2:3], v[6:7], s[90:91] op_sel_hi:[1,0]
	v_lshl_add_u32 v6, v10, 2, 0
	v_lshrrev_b32_e32 v7, 2, v10
	v_lshrrev_b32_e32 v10, 6, v10
	v_and_b32_e32 v7, 0xffc, v7
	v_and_b32_e32 v10, 0xfc, v10
	v_add3_u32 v10, v6, v7, v10
	ds_read_b32 v7, v10
	v_pk_mul_f32 v[4:5], v[4:5], s[90:91] op_sel_hi:[1,0]
	s_waitcnt lgkmcnt(0)
	v_cvt_f32_f16_e32 v6, v7
	v_cvt_f32_f16_sdwa v7, v7 dst_sel:DWORD dst_unused:UNUSED_PAD src0_sel:WORD_1
	s_and_saveexec_b64 s[22:23], s[40:41]
	s_xor_b64 s[22:23], exec, s[22:23]
	s_cbranch_execz .LBB0_744
	v_bfrev_b32_e32 v9, v8
	v_lshrrev_b32_e32 v11, 19, v9
	v_lshrrev_b32_e32 v9, 17, v9
	v_and_b32_e32 v9, 0x2aaa, v9
	v_and_or_b32 v9, v11, s89, v9
	v_lshl_add_u32 v11, v9, 2, 0
	v_lshrrev_b32_e32 v13, 2, v9
	v_lshrrev_b32_e32 v9, 6, v9
	v_and_b32_e32 v13, 0xffc, v13
	v_and_b32_e32 v9, 0xfc, v9
	v_add3_u32 v9, v11, v13, v9
	ds_read_b32 v11, v9
	v_pk_mul_f32 v[18:19], v[6:7], v[4:5] op_sel:[0,0] op_sel_hi:[0,1]
	s_waitcnt lgkmcnt(0)
	v_cvt_f32_f16_e32 v16, v11
	v_cvt_f32_f16_sdwa v17, -v11 dst_sel:DWORD dst_unused:UNUSED_PAD src0_sel:WORD_1
	v_pk_mul_f32 v[22:23], v[16:17], v[2:3] op_sel:[0,0] op_sel_hi:[0,1]
	v_pk_fma_f32 v[18:19], v[6:7], v[4:5], v[18:19] op_sel:[1,1,0] op_sel_hi:[1,0,1] neg_lo:[0,1,0]
	v_pk_fma_f32 v[22:23], v[16:17], v[2:3], v[22:23] op_sel:[1,1,0] op_sel_hi:[1,0,1] neg_lo:[0,1,0]
	v_pk_add_f32 v[18:19], v[18:19], v[22:23]
	v_pk_mul_f32 v[22:23], v[16:17], v[4:5] op_sel:[0,0] op_sel_hi:[0,1]
	v_pk_fma_f32 v[4:5], v[16:17], v[4:5], v[22:23] op_sel:[1,1,0] op_sel_hi:[1,0,1] neg_lo:[0,1,0]
	v_pk_mul_f32 v[16:17], v[6:7], v[2:3] op_sel:[0,0] op_sel_hi:[0,1]
	v_pk_fma_f32 v[2:3], v[6:7], v[2:3], v[16:17] op_sel:[1,1,0] op_sel_hi:[1,0,1] neg_lo:[0,1,0]
	s_nop 0
	v_pk_add_f32 v[2:3], v[4:5], v[2:3]
	v_cvt_pk_f16_f32 v4, v18, v19
	v_cvt_pk_f16_f32 v2, v2, -v3
	ds_write_b32 v10, v4
	ds_write_b32 v9, v2

; #define LAS __attribute__((address_space(3)))
; DI int rev4(int pp) { const unsigned br = __brev((unsigned)pp) >> 18; return (int)(((br & 0x2AAAu) >> 1) | ((br & 0x1555u) << 1)); }
; DI void pw_h(LAS hc* X, const f32x4* spec, int tid) {
; #pragma unroll 8
;     for (int r = 0; r < 16; ++r) {
;         const int k = tid + NTHR * r; const int pp = rev4(k);
;         const f32x4 sp = spec[k]; const cf P = (cf){sp[0], sp[1]} * 256.0f, Mq = (cf){sp[2], sp[3]} * 256.0f;
;         const hc zh = X[XI(pp)]; const cf z = (cf){(float)zh.x, (float)zh.y};
;         if (k == 0) { const cf y = cmul(z, P) + cmul((cf){z.x, -z.y}, Mq); X[XI(pp)] = (hc){(_Float16)y.x, (_Float16)y.y}; }
;         else { const int pm = rev4(16384 - k); const hc zmh = X[XI(pm)]; const cf zm = (cf){(float)zmh.x, (float)zmh.y};
;             const cf y = cmul(z, P) + cmul((cf){zm.x, -zm.y}, Mq);
;             const cf t = cmul((cf){zm.x, -zm.y}, P) + cmul(z, Mq);
;             X[XI(pp)] = (hc){(_Float16)y.x, (_Float16)y.y}; X[XI(pm)] = (hc){(_Float16)t.x, (_Float16)(-t.y)}; }
;     }
.LBB0_750:
	global_load_dwordx4 v[4:7], v[0:1], off
	v_add_u32_e32 v8, s4, v12
	v_add_u32_e32 v2, 0x2000, v8
	v_bfrev_b32_e32 v2, v2
	v_lshrrev_b32_e32 v3, 19, v2
	v_lshrrev_b32_e32 v2, 17, v2
	v_and_b32_e32 v2, 0x2aaa, v2
	v_and_or_b32 v9, v3, s89, v2
	s_movk_i32 s5, 0xe000
	v_cmp_ne_u32_e64 s[40:41], s5, v8
	v_add_u32_e32 v100, 0x2200, v8
	v_ashrrev_i32_e32 v101, 31, v100
	v_lshl_add_u64 v[100:101], v[100:101], 4, s[20:21]
	global_load_dwordx4 v[104:107], v[100:101], off
	v_add_u32_e32 v100, 0x2400, v8
	v_ashrrev_i32_e32 v101, 31, v100
	v_lshl_add_u64 v[100:101], v[100:101], 4, s[20:21]
	global_load_dwordx4 v[108:111], v[100:101], off
	v_add_u32_e32 v100, 0x2600, v8
	v_ashrrev_i32_e32 v101, 31, v100
	v_lshl_add_u64 v[100:101], v[100:101], 4, s[20:21]
	global_load_dwordx4 v[112:115], v[100:101], off
	v_add_u32_e32 v100, 0x2800, v8
	v_ashrrev_i32_e32 v101, 31, v100
	v_lshl_add_u64 v[100:101], v[100:101], 4, s[20:21]
	global_load_dwordx4 v[116:119], v[100:101], off
	v_add_u32_e32 v100, 0x2a00, v8
	v_ashrrev_i32_e32 v101, 31, v100
	v_lshl_add_u64 v[100:101], v[100:101], 4, s[20:21]
	global_load_dwordx4 v[120:123], v[100:101], off
	v_add_u32_e32 v100, 0x2c00, v8
	v_ashrrev_i32_e32 v101, 31, v100
	v_lshl_add_u64 v[100:101], v[100:101], 4, s[20:21]
	global_load_dwordx4 v[124:127], v[100:101], off
	v_add_u32_e32 v100, 0x2e00, v8
	v_ashrrev_i32_e32 v101, 31, v100
	v_lshl_add_u64 v[100:101], v[100:101], 4, s[20:21]
	global_load_dwordx4 v[128:131], v[100:101], off
	s_waitcnt vmcnt(7)
	v_pk_mul_f32 v[2:3], v[6:7], s[90:91] op_sel_hi:[1,0]
	v_lshl_add_u32 v6, v9, 2, s66
	v_lshrrev_b32_e32 v7, 2, v9
	v_lshrrev_b32_e32 v9, 6, v9
	v_and_b32_e32 v7, 0xffc, v7
	v_and_b32_e32 v9, 0xfc, v9
	v_add3_u32 v9, v6, v7, v9
	ds_read_b32 v7, v9
	v_pk_mul_f32 v[4:5], v[4:5], s[90:91] op_sel_hi:[1,0]
	s_waitcnt lgkmcnt(0)
	v_cvt_f32_f16_e32 v6, v7
	v_cvt_f32_f16_sdwa v7, v7 dst_sel:DWORD dst_unused:UNUSED_PAD src0_sel:WORD_1
	s_and_saveexec_b64 s[6:7], s[40:41]
	s_xor_b64 s[22:23], exec, s[6:7]
	s_cbranch_execz .LBB0_752
	v_add_u32_e32 v10, 0xe00, v20
	v_bfrev_b32_e32 v10, v10
	v_lshrrev_b32_e32 v11, 19, v10
	v_lshrrev_b32_e32 v10, 17, v10
	v_and_b32_e32 v10, 0x2aaa, v10
	v_and_or_b32 v10, v11, s89, v10
	v_lshl_add_u32 v11, v10, 2, s66
	v_lshrrev_b32_e32 v13, 2, v10
	v_lshrrev_b32_e32 v10, 6, v10
	v_and_b32_e32 v13, 0xffc, v13
	v_and_b32_e32 v10, 0xfc, v10
	v_add3_u32 v13, v11, v13, v10
	ds_read_b32 v11, v13
	v_pk_mul_f32 v[14:15], v[6:7], v[4:5] op_sel:[0,0] op_sel_hi:[0,1]
	s_waitcnt lgkmcnt(0)
	v_cvt_f32_f16_e32 v10, v11
	v_cvt_f32_f16_sdwa v11, -v11 dst_sel:DWORD dst_unused:UNUSED_PAD src0_sel:WORD_1
	v_pk_mul_f32 v[16:17], v[10:11], v[2:3] op_sel:[0,0] op_sel_hi:[0,1]
	v_pk_fma_f32 v[14:15], v[6:7], v[4:5], v[14:15] op_sel:[1,1,0] op_sel_hi:[1,0,1] neg_lo:[0,1,0]
	v_pk_fma_f32 v[16:17], v[10:11], v[2:3], v[16:17] op_sel:[1,1,0] op_sel_hi:[1,0,1] neg_lo:[0,1,0]
	v_pk_add_f32 v[14:15], v[14:15], v[16:17]
	v_pk_mul_f32 v[16:17], v[10:11], v[4:5] op_sel:[0,0] op_sel_hi:[0,1]
	v_pk_fma_f32 v[4:5], v[10:11], v[4:5], v[16:17] op_sel:[1,1,0] op_sel_hi:[1,0,1] neg_lo:[0,1,0]
	v_pk_mul_f32 v[10:11], v[6:7], v[2:3] op_sel:[0,0] op_sel_hi:[0,1]
	v_pk_fma_f32 v[2:3], v[6:7], v[2:3], v[10:11] op_sel:[1,1,0] op_sel_hi:[1,0,1] neg_lo:[0,1,0]
	s_nop 0
	v_pk_add_f32 v[2:3], v[4:5], v[2:3]
	v_cvt_pk_f16_f32 v4, v14, v15
	v_cvt_pk_f16_f32 v2, v2, -v3
	ds_write_b32 v9, v4
	ds_write_b32 v13, v2

; DI int rev4(int pp) { const unsigned br = __brev((unsigned)pp) >> 18; return (int)(((br & 0x2AAAu) >> 1) | ((br & 0x1555u) << 1)); }
; DI void pw_h(LAS hc* X, const f32x4* spec, int tid) {
;     ...
;     for (int r = 0; r < 16; ++r) {
;         const int k = tid + NTHR * r; const int pp = rev4(k);
;         const f32x4 sp = spec[k]; const cf P = (cf){sp[0], sp[1]} * 256.0f, Mq = (cf){sp[2], sp[3]} * 256.0f;
;         const hc zh = X[XI(pp)]; const cf z = (cf){(float)zh.x, (float)zh.y};
;         if (k == 0) { const cf y = cmul(z, P) + cmul((cf){z.x, -z.y}, Mq); X[XI(pp)] = (hc){(_Float16)y.x, (_Float16)y.y}; }
;         else { const int pm = rev4(16384 - k); const hc zmh = X[XI(pm)]; const cf zm = (cf){(float)zmh.x, (float)zmh.y};
;             const cf y = cmul(z, P) + cmul((cf){zm.x, -zm.y}, Mq);
;             const cf t = cmul((cf){zm.x, -zm.y}, P) + cmul(z, Mq);
;             X[XI(pp)] = (hc){(_Float16)y.x, (_Float16)y.y}; X[XI(pm)] = (hc){(_Float16)t.x, (_Float16)(-t.y)}; }
.LBB0_754:
	s_or_b64 exec, exec, s[22:23]
	v_add_u32_e32 v2, 0x2200, v8
	v_bfrev_b32_e32 v3, v2
	v_lshrrev_b32_e32 v4, 19, v3
	v_lshrrev_b32_e32 v3, 17, v3
	v_and_b32_e32 v3, 0x2aaa, v3
	v_and_or_b32 v9, v4, s89, v3
	s_movk_i32 s5, 0xde00
	v_cmp_ne_u32_e64 s[40:41], s5, v8
	s_waitcnt vmcnt(6)
	v_mov_b32_e32 v4, v104
	v_mov_b32_e32 v5, v105
	v_mov_b32_e32 v6, v106
	v_mov_b32_e32 v7, v107
	v_pk_mul_f32 v[2:3], v[6:7], s[90:91] op_sel_hi:[1,0]
	v_lshl_add_u32 v6, v9, 2, s66
	v_lshrrev_b32_e32 v7, 2, v9
	v_lshrrev_b32_e32 v9, 6, v9
	v_and_b32_e32 v7, 0xffc, v7
	v_and_b32_e32 v9, 0xfc, v9
	v_add3_u32 v9, v6, v7, v9
	ds_read_b32 v7, v9
	v_pk_mul_f32 v[4:5], v[4:5], s[90:91] op_sel_hi:[1,0]
	s_waitcnt lgkmcnt(0)
	v_cvt_f32_f16_e32 v6, v7
	v_cvt_f32_f16_sdwa v7, v7 dst_sel:DWORD dst_unused:UNUSED_PAD src0_sel:WORD_1
	s_and_saveexec_b64 s[6:7], s[40:41]
	s_xor_b64 s[22:23], exec, s[6:7]
	s_cbranch_execz .LBB0_756
	v_add_u32_e32 v10, 0xc00, v20
	v_bfrev_b32_e32 v10, v10
	v_lshrrev_b32_e32 v11, 19, v10
	v_lshrrev_b32_e32 v10, 17, v10
	v_and_b32_e32 v10, 0x2aaa, v10
	v_and_or_b32 v10, v11, s89, v10
	v_lshl_add_u32 v11, v10, 2, s66
	v_lshrrev_b32_e32 v13, 2, v10
	v_lshrrev_b32_e32 v10, 6, v10
	v_and_b32_e32 v13, 0xffc, v13
	v_and_b32_e32 v10, 0xfc, v10
	v_add3_u32 v13, v11, v13, v10
	ds_read_b32 v11, v13
	v_pk_mul_f32 v[14:15], v[6:7], v[4:5] op_sel:[0,0] op_sel_hi:[0,1]
	s_waitcnt lgkmcnt(0)
	v_cvt_f32_f16_e32 v10, v11
	v_cvt_f32_f16_sdwa v11, -v11 dst_sel:DWORD dst_unused:UNUSED_PAD src0_sel:WORD_1
	v_pk_mul_f32 v[16:17], v[10:11], v[2:3] op_sel:[0,0] op_sel_hi:[0,1]
	v_pk_fma_f32 v[14:15], v[6:7], v[4:5], v[14:15] op_sel:[1,1,0] op_sel_hi:[1,0,1] neg_lo:[0,1,0]
	v_pk_fma_f32 v[16:17], v[10:11], v[2:3], v[16:17] op_sel:[1,1,0] op_sel_hi:[1,0,1] neg_lo:[0,1,0]
	v_pk_add_f32 v[14:15], v[14:15], v[16:17]
	v_pk_mul_f32 v[16:17], v[10:11], v[4:5] op_sel:[0,0] op_sel_hi:[0,1]
	v_pk_fma_f32 v[4:5], v[10:11], v[4:5], v[16:17] op_sel:[1,1,0] op_sel_hi:[1,0,1] neg_lo:[0,1,0]
	v_pk_mul_f32 v[10:11], v[6:7], v[2:3] op_sel:[0,0] op_sel_hi:[0,1]
	v_pk_fma_f32 v[2:3], v[6:7], v[2:3], v[10:11] op_sel:[1,1,0] op_sel_hi:[1,0,1] neg_lo:[0,1,0]
	s_nop 0
	v_pk_add_f32 v[2:3], v[4:5], v[2:3]
	v_cvt_pk_f16_f32 v4, v14, v15
	v_cvt_pk_f16_f32 v2, v2, -v3
	ds_write_b32 v9, v4
	ds_write_b32 v13, v2

; DI int rev4(int pp) { const unsigned br = __brev((unsigned)pp) >> 18; return (int)(((br & 0x2AAAu) >> 1) | ((br & 0x1555u) << 1)); }
; DI void pw_h(LAS hc* X, const f32x4* spec, int tid) {
;     ...
;     for (int r = 0; r < 16; ++r) {
;         const int k = tid + NTHR * r; const int pp = rev4(k);
;         const f32x4 sp = spec[k]; const cf P = (cf){sp[0], sp[1]} * 256.0f, Mq = (cf){sp[2], sp[3]} * 256.0f;
;         const hc zh = X[XI(pp)]; const cf z = (cf){(float)zh.x, (float)zh.y};
;         if (k == 0) { const cf y = cmul(z, P) + cmul((cf){z.x, -z.y}, Mq); X[XI(pp)] = (hc){(_Float16)y.x, (_Float16)y.y}; }
;         else { const int pm = rev4(16384 - k); const hc zmh = X[XI(pm)]; const cf zm = (cf){(float)zmh.x, (float)zmh.y};
;             const cf y = cmul(z, P) + cmul((cf){zm.x, -zm.y}, Mq);
;             const cf t = cmul((cf){zm.x, -zm.y}, P) + cmul(z, Mq);
;             X[XI(pp)] = (hc){(_Float16)y.x, (_Float16)y.y}; X[XI(pm)] = (hc){(_Float16)t.x, (_Float16)(-t.y)}; }
.LBB0_758:
	s_or_b64 exec, exec, s[22:23]
	v_add_u32_e32 v2, 0x2400, v8
	v_bfrev_b32_e32 v3, v2
	v_lshrrev_b32_e32 v4, 19, v3
	v_lshrrev_b32_e32 v3, 17, v3
	v_and_b32_e32 v3, 0x2aaa, v3
	v_and_or_b32 v9, v4, s89, v3
	s_movk_i32 s5, 0xdc00
	v_cmp_ne_u32_e64 s[40:41], s5, v8
	s_waitcnt vmcnt(5)
	v_mov_b32_e32 v4, v108
	v_mov_b32_e32 v5, v109
	v_mov_b32_e32 v6, v110
	v_mov_b32_e32 v7, v111
	v_pk_mul_f32 v[2:3], v[6:7], s[90:91] op_sel_hi:[1,0]
	v_lshl_add_u32 v6, v9, 2, s66
	v_lshrrev_b32_e32 v7, 2, v9
	v_lshrrev_b32_e32 v9, 6, v9
	v_and_b32_e32 v7, 0xffc, v7
	v_and_b32_e32 v9, 0xfc, v9
	v_add3_u32 v9, v6, v7, v9
	ds_read_b32 v7, v9
	v_pk_mul_f32 v[4:5], v[4:5], s[90:91] op_sel_hi:[1,0]
	s_waitcnt lgkmcnt(0)
	v_cvt_f32_f16_e32 v6, v7
	v_cvt_f32_f16_sdwa v7, v7 dst_sel:DWORD dst_unused:UNUSED_PAD src0_sel:WORD_1
	s_and_saveexec_b64 s[6:7], s[40:41]
	s_xor_b64 s[22:23], exec, s[6:7]
	s_cbranch_execz .LBB0_760
	v_add_u32_e32 v10, 0xa00, v20
	v_bfrev_b32_e32 v10, v10
	v_lshrrev_b32_e32 v11, 19, v10
	v_lshrrev_b32_e32 v10, 17, v10
	v_and_b32_e32 v10, 0x2aaa, v10
	v_and_or_b32 v10, v11, s89, v10
	v_lshl_add_u32 v11, v10, 2, s66
	v_lshrrev_b32_e32 v13, 2, v10
	v_lshrrev_b32_e32 v10, 6, v10
	v_and_b32_e32 v13, 0xffc, v13
	v_and_b32_e32 v10, 0xfc, v10
	v_add3_u32 v13, v11, v13, v10
	ds_read_b32 v11, v13
	v_pk_mul_f32 v[14:15], v[6:7], v[4:5] op_sel:[0,0] op_sel_hi:[0,1]
	s_waitcnt lgkmcnt(0)
	v_cvt_f32_f16_e32 v10, v11
	v_cvt_f32_f16_sdwa v11, -v11 dst_sel:DWORD dst_unused:UNUSED_PAD src0_sel:WORD_1
	v_pk_mul_f32 v[16:17], v[10:11], v[2:3] op_sel:[0,0] op_sel_hi:[0,1]
	v_pk_fma_f32 v[14:15], v[6:7], v[4:5], v[14:15] op_sel:[1,1,0] op_sel_hi:[1,0,1] neg_lo:[0,1,0]
	v_pk_fma_f32 v[16:17], v[10:11], v[2:3], v[16:17] op_sel:[1,1,0] op_sel_hi:[1,0,1] neg_lo:[0,1,0]
	v_pk_add_f32 v[14:15], v[14:15], v[16:17]
	v_pk_mul_f32 v[16:17], v[10:11], v[4:5] op_sel:[0,0] op_sel_hi:[0,1]
	v_pk_fma_f32 v[4:5], v[10:11], v[4:5], v[16:17] op_sel:[1,1,0] op_sel_hi:[1,0,1] neg_lo:[0,1,0]
	v_pk_mul_f32 v[10:11], v[6:7], v[2:3] op_sel:[0,0] op_sel_hi:[0,1]
	v_pk_fma_f32 v[2:3], v[6:7], v[2:3], v[10:11] op_sel:[1,1,0] op_sel_hi:[1,0,1] neg_lo:[0,1,0]
	s_nop 0
	v_pk_add_f32 v[2:3], v[4:5], v[2:3]
	v_cvt_pk_f16_f32 v4, v14, v15
	v_cvt_pk_f16_f32 v2, v2, -v3
	ds_write_b32 v9, v4
	ds_write_b32 v13, v2

; DI int rev4(int pp) { const unsigned br = __brev((unsigned)pp) >> 18; return (int)(((br & 0x2AAAu) >> 1) | ((br & 0x1555u) << 1)); }
; DI void pw_h(LAS hc* X, const f32x4* spec, int tid) {
;     ...
;     for (int r = 0; r < 16; ++r) {
;         const int k = tid + NTHR * r; const int pp = rev4(k);
;         const f32x4 sp = spec[k]; const cf P = (cf){sp[0], sp[1]} * 256.0f, Mq = (cf){sp[2], sp[3]} * 256.0f;
;         const hc zh = X[XI(pp)]; const cf z = (cf){(float)zh.x, (float)zh.y};
;         if (k == 0) { const cf y = cmul(z, P) + cmul((cf){z.x, -z.y}, Mq); X[XI(pp)] = (hc){(_Float16)y.x, (_Float16)y.y}; }
;         else { const int pm = rev4(16384 - k); const hc zmh = X[XI(pm)]; const cf zm = (cf){(float)zmh.x, (float)zmh.y};
;             const cf y = cmul(z, P) + cmul((cf){zm.x, -zm.y}, Mq);
;             const cf t = cmul((cf){zm.x, -zm.y}, P) + cmul(z, Mq);
;             X[XI(pp)] = (hc){(_Float16)y.x, (_Float16)y.y}; X[XI(pm)] = (hc){(_Float16)t.x, (_Float16)(-t.y)}; }
.LBB0_762:
	s_or_b64 exec, exec, s[22:23]
	v_add_u32_e32 v2, 0x2600, v8
	v_bfrev_b32_e32 v3, v2
	v_lshrrev_b32_e32 v4, 19, v3
	v_lshrrev_b32_e32 v3, 17, v3
	v_and_b32_e32 v3, 0x2aaa, v3
	v_and_or_b32 v9, v4, s89, v3
	s_movk_i32 s5, 0xda00
	v_cmp_ne_u32_e64 s[40:41], s5, v8
	s_waitcnt vmcnt(4)
	v_mov_b32_e32 v4, v112
	v_mov_b32_e32 v5, v113
	v_mov_b32_e32 v6, v114
	v_mov_b32_e32 v7, v115
	v_pk_mul_f32 v[2:3], v[6:7], s[90:91] op_sel_hi:[1,0]
	v_lshl_add_u32 v6, v9, 2, s66
	v_lshrrev_b32_e32 v7, 2, v9
	v_lshrrev_b32_e32 v9, 6, v9
	v_and_b32_e32 v7, 0xffc, v7
	v_and_b32_e32 v9, 0xfc, v9
	v_add3_u32 v9, v6, v7, v9
	ds_read_b32 v7, v9
	v_pk_mul_f32 v[4:5], v[4:5], s[90:91] op_sel_hi:[1,0]
	s_waitcnt lgkmcnt(0)
	v_cvt_f32_f16_e32 v6, v7
	v_cvt_f32_f16_sdwa v7, v7 dst_sel:DWORD dst_unused:UNUSED_PAD src0_sel:WORD_1
	s_and_saveexec_b64 s[6:7], s[40:41]
	s_xor_b64 s[22:23], exec, s[6:7]
	s_cbranch_execz .LBB0_764
	v_add_u32_e32 v10, 0x800, v20
	v_bfrev_b32_e32 v10, v10
	v_lshrrev_b32_e32 v11, 19, v10
	v_lshrrev_b32_e32 v10, 17, v10
	v_and_b32_e32 v10, 0x2aaa, v10
	v_and_or_b32 v10, v11, s89, v10
	v_lshl_add_u32 v11, v10, 2, s66
	v_lshrrev_b32_e32 v13, 2, v10
	v_lshrrev_b32_e32 v10, 6, v10
	v_and_b32_e32 v13, 0xffc, v13
	v_and_b32_e32 v10, 0xfc, v10
	v_add3_u32 v13, v11, v13, v10
	ds_read_b32 v11, v13
	v_pk_mul_f32 v[14:15], v[6:7], v[4:5] op_sel:[0,0] op_sel_hi:[0,1]
	s_waitcnt lgkmcnt(0)
	v_cvt_f32_f16_e32 v10, v11
	v_cvt_f32_f16_sdwa v11, -v11 dst_sel:DWORD dst_unused:UNUSED_PAD src0_sel:WORD_1
	v_pk_mul_f32 v[16:17], v[10:11], v[2:3] op_sel:[0,0] op_sel_hi:[0,1]
	v_pk_fma_f32 v[14:15], v[6:7], v[4:5], v[14:15] op_sel:[1,1,0] op_sel_hi:[1,0,1] neg_lo:[0,1,0]
	v_pk_fma_f32 v[16:17], v[10:11], v[2:3], v[16:17] op_sel:[1,1,0] op_sel_hi:[1,0,1] neg_lo:[0,1,0]
	v_pk_add_f32 v[14:15], v[14:15], v[16:17]
	v_pk_mul_f32 v[16:17], v[10:11], v[4:5] op_sel:[0,0] op_sel_hi:[0,1]
	v_pk_fma_f32 v[4:5], v[10:11], v[4:5], v[16:17] op_sel:[1,1,0] op_sel_hi:[1,0,1] neg_lo:[0,1,0]
	v_pk_mul_f32 v[10:11], v[6:7], v[2:3] op_sel:[0,0] op_sel_hi:[0,1]
	v_pk_fma_f32 v[2:3], v[6:7], v[2:3], v[10:11] op_sel:[1,1,0] op_sel_hi:[1,0,1] neg_lo:[0,1,0]
	s_nop 0
	v_pk_add_f32 v[2:3], v[4:5], v[2:3]
	v_cvt_pk_f16_f32 v4, v14, v15
	v_cvt_pk_f16_f32 v2, v2, -v3
	ds_write_b32 v9, v4
	ds_write_b32 v13, v2

; DI int rev4(int pp) { const unsigned br = __brev((unsigned)pp) >> 18; return (int)(((br & 0x2AAAu) >> 1) | ((br & 0x1555u) << 1)); }
; DI void pw_h(LAS hc* X, const f32x4* spec, int tid) {
;     ...
;     for (int r = 0; r < 16; ++r) {
;         const int k = tid + NTHR * r; const int pp = rev4(k);
;         const f32x4 sp = spec[k]; const cf P = (cf){sp[0], sp[1]} * 256.0f, Mq = (cf){sp[2], sp[3]} * 256.0f;
;         const hc zh = X[XI(pp)]; const cf z = (cf){(float)zh.x, (float)zh.y};
;         if (k == 0) { const cf y = cmul(z, P) + cmul((cf){z.x, -z.y}, Mq); X[XI(pp)] = (hc){(_Float16)y.x, (_Float16)y.y}; }
;         else { const int pm = rev4(16384 - k); const hc zmh = X[XI(pm)]; const cf zm = (cf){(float)zmh.x, (float)zmh.y};
;             const cf y = cmul(z, P) + cmul((cf){zm.x, -zm.y}, Mq);
;             const cf t = cmul((cf){zm.x, -zm.y}, P) + cmul(z, Mq);
;             X[XI(pp)] = (hc){(_Float16)y.x, (_Float16)y.y}; X[XI(pm)] = (hc){(_Float16)t.x, (_Float16)(-t.y)}; }
.LBB0_766:
	s_or_b64 exec, exec, s[22:23]
	v_add_u32_e32 v2, 0x2800, v8
	v_bfrev_b32_e32 v3, v2
	v_lshrrev_b32_e32 v4, 19, v3
	v_lshrrev_b32_e32 v3, 17, v3
	v_and_b32_e32 v3, 0x2aaa, v3
	v_and_or_b32 v9, v4, s89, v3
	s_movk_i32 s5, 0xd800
	v_cmp_ne_u32_e64 s[40:41], s5, v8
	s_waitcnt vmcnt(3)
	v_mov_b32_e32 v4, v116
	v_mov_b32_e32 v5, v117
	v_mov_b32_e32 v6, v118
	v_mov_b32_e32 v7, v119
	v_pk_mul_f32 v[2:3], v[6:7], s[90:91] op_sel_hi:[1,0]
	v_lshl_add_u32 v6, v9, 2, s66
	v_lshrrev_b32_e32 v7, 2, v9
	v_lshrrev_b32_e32 v9, 6, v9
	v_and_b32_e32 v7, 0xffc, v7
	v_and_b32_e32 v9, 0xfc, v9
	v_add3_u32 v9, v6, v7, v9
	ds_read_b32 v7, v9
	v_pk_mul_f32 v[4:5], v[4:5], s[90:91] op_sel_hi:[1,0]
	s_waitcnt lgkmcnt(0)
	v_cvt_f32_f16_e32 v6, v7
	v_cvt_f32_f16_sdwa v7, v7 dst_sel:DWORD dst_unused:UNUSED_PAD src0_sel:WORD_1
	s_and_saveexec_b64 s[6:7], s[40:41]
	s_xor_b64 s[22:23], exec, s[6:7]
	s_cbranch_execz .LBB0_768
	v_add_u32_e32 v10, 0x600, v20
	v_bfrev_b32_e32 v10, v10
	v_lshrrev_b32_e32 v11, 19, v10
	v_lshrrev_b32_e32 v10, 17, v10
	v_and_b32_e32 v10, 0x2aaa, v10
	v_and_or_b32 v10, v11, s89, v10
	v_lshl_add_u32 v11, v10, 2, s66
	v_lshrrev_b32_e32 v13, 2, v10
	v_lshrrev_b32_e32 v10, 6, v10
	v_and_b32_e32 v13, 0xffc, v13
	v_and_b32_e32 v10, 0xfc, v10
	v_add3_u32 v13, v11, v13, v10
	ds_read_b32 v11, v13
	v_pk_mul_f32 v[14:15], v[6:7], v[4:5] op_sel:[0,0] op_sel_hi:[0,1]
	s_waitcnt lgkmcnt(0)
	v_cvt_f32_f16_e32 v10, v11
	v_cvt_f32_f16_sdwa v11, -v11 dst_sel:DWORD dst_unused:UNUSED_PAD src0_sel:WORD_1
	v_pk_mul_f32 v[16:17], v[10:11], v[2:3] op_sel:[0,0] op_sel_hi:[0,1]
	v_pk_fma_f32 v[14:15], v[6:7], v[4:5], v[14:15] op_sel:[1,1,0] op_sel_hi:[1,0,1] neg_lo:[0,1,0]
	v_pk_fma_f32 v[16:17], v[10:11], v[2:3], v[16:17] op_sel:[1,1,0] op_sel_hi:[1,0,1] neg_lo:[0,1,0]
	v_pk_add_f32 v[14:15], v[14:15], v[16:17]
	v_pk_mul_f32 v[16:17], v[10:11], v[4:5] op_sel:[0,0] op_sel_hi:[0,1]
	v_pk_fma_f32 v[4:5], v[10:11], v[4:5], v[16:17] op_sel:[1,1,0] op_sel_hi:[1,0,1] neg_lo:[0,1,0]
	v_pk_mul_f32 v[10:11], v[6:7], v[2:3] op_sel:[0,0] op_sel_hi:[0,1]
	v_pk_fma_f32 v[2:3], v[6:7], v[2:3], v[10:11] op_sel:[1,1,0] op_sel_hi:[1,0,1] neg_lo:[0,1,0]
	s_nop 0
	v_pk_add_f32 v[2:3], v[4:5], v[2:3]
	v_cvt_pk_f16_f32 v4, v14, v15
	v_cvt_pk_f16_f32 v2, v2, -v3
	ds_write_b32 v9, v4
	ds_write_b32 v13, v2

; DI int rev4(int pp) { const unsigned br = __brev((unsigned)pp) >> 18; return (int)(((br & 0x2AAAu) >> 1) | ((br & 0x1555u) << 1)); }
; DI void pw_h(LAS hc* X, const f32x4* spec, int tid) {
;     ...
;     for (int r = 0; r < 16; ++r) {
;         const int k = tid + NTHR * r; const int pp = rev4(k);
;         const f32x4 sp = spec[k]; const cf P = (cf){sp[0], sp[1]} * 256.0f, Mq = (cf){sp[2], sp[3]} * 256.0f;
;         const hc zh = X[XI(pp)]; const cf z = (cf){(float)zh.x, (float)zh.y};
;         if (k == 0) { const cf y = cmul(z, P) + cmul((cf){z.x, -z.y}, Mq); X[XI(pp)] = (hc){(_Float16)y.x, (_Float16)y.y}; }
;         else { const int pm = rev4(16384 - k); const hc zmh = X[XI(pm)]; const cf zm = (cf){(float)zmh.x, (float)zmh.y};
;             const cf y = cmul(z, P) + cmul((cf){zm.x, -zm.y}, Mq);
;             const cf t = cmul((cf){zm.x, -zm.y}, P) + cmul(z, Mq);
;             X[XI(pp)] = (hc){(_Float16)y.x, (_Float16)y.y}; X[XI(pm)] = (hc){(_Float16)t.x, (_Float16)(-t.y)}; }
.LBB0_770:
	s_or_b64 exec, exec, s[22:23]
	v_add_u32_e32 v2, 0x2a00, v8
	v_bfrev_b32_e32 v3, v2
	v_lshrrev_b32_e32 v4, 19, v3
	v_lshrrev_b32_e32 v3, 17, v3
	v_and_b32_e32 v3, 0x2aaa, v3
	v_and_or_b32 v9, v4, s89, v3
	s_movk_i32 s5, 0xd600
	v_cmp_ne_u32_e64 s[40:41], s5, v8
	s_waitcnt vmcnt(2)
	v_mov_b32_e32 v4, v120
	v_mov_b32_e32 v5, v121
	v_mov_b32_e32 v6, v122
	v_mov_b32_e32 v7, v123
	v_pk_mul_f32 v[2:3], v[6:7], s[90:91] op_sel_hi:[1,0]
	v_lshl_add_u32 v6, v9, 2, s66
	v_lshrrev_b32_e32 v7, 2, v9
	v_lshrrev_b32_e32 v9, 6, v9
	v_and_b32_e32 v7, 0xffc, v7
	v_and_b32_e32 v9, 0xfc, v9
	v_add3_u32 v9, v6, v7, v9
	ds_read_b32 v7, v9
	v_pk_mul_f32 v[4:5], v[4:5], s[90:91] op_sel_hi:[1,0]
	s_waitcnt lgkmcnt(0)
	v_cvt_f32_f16_e32 v6, v7
	v_cvt_f32_f16_sdwa v7, v7 dst_sel:DWORD dst_unused:UNUSED_PAD src0_sel:WORD_1
	s_and_saveexec_b64 s[6:7], s[40:41]
	s_xor_b64 s[22:23], exec, s[6:7]
	s_cbranch_execz .LBB0_772
	v_add_u32_e32 v10, 0x400, v20
	v_bfrev_b32_e32 v10, v10
	v_lshrrev_b32_e32 v11, 19, v10
	v_lshrrev_b32_e32 v10, 17, v10
	v_and_b32_e32 v10, 0x2aaa, v10
	v_and_or_b32 v10, v11, s89, v10
	v_lshl_add_u32 v11, v10, 2, s66
	v_lshrrev_b32_e32 v13, 2, v10
	v_lshrrev_b32_e32 v10, 6, v10
	v_and_b32_e32 v13, 0xffc, v13
	v_and_b32_e32 v10, 0xfc, v10
	v_add3_u32 v13, v11, v13, v10
	ds_read_b32 v11, v13
	v_pk_mul_f32 v[14:15], v[6:7], v[4:5] op_sel:[0,0] op_sel_hi:[0,1]
	s_waitcnt lgkmcnt(0)
	v_cvt_f32_f16_e32 v10, v11
	v_cvt_f32_f16_sdwa v11, -v11 dst_sel:DWORD dst_unused:UNUSED_PAD src0_sel:WORD_1
	v_pk_mul_f32 v[16:17], v[10:11], v[2:3] op_sel:[0,0] op_sel_hi:[0,1]
	v_pk_fma_f32 v[14:15], v[6:7], v[4:5], v[14:15] op_sel:[1,1,0] op_sel_hi:[1,0,1] neg_lo:[0,1,0]
	v_pk_fma_f32 v[16:17], v[10:11], v[2:3], v[16:17] op_sel:[1,1,0] op_sel_hi:[1,0,1] neg_lo:[0,1,0]
	v_pk_add_f32 v[14:15], v[14:15], v[16:17]
	v_pk_mul_f32 v[16:17], v[10:11], v[4:5] op_sel:[0,0] op_sel_hi:[0,1]
	v_pk_fma_f32 v[4:5], v[10:11], v[4:5], v[16:17] op_sel:[1,1,0] op_sel_hi:[1,0,1] neg_lo:[0,1,0]
	v_pk_mul_f32 v[10:11], v[6:7], v[2:3] op_sel:[0,0] op_sel_hi:[0,1]
	v_pk_fma_f32 v[2:3], v[6:7], v[2:3], v[10:11] op_sel:[1,1,0] op_sel_hi:[1,0,1] neg_lo:[0,1,0]
	s_nop 0
	v_pk_add_f32 v[2:3], v[4:5], v[2:3]
	v_cvt_pk_f16_f32 v4, v14, v15
	v_cvt_pk_f16_f32 v2, v2, -v3
	ds_write_b32 v9, v4
	ds_write_b32 v13, v2

; DI int rev4(int pp) { const unsigned br = __brev((unsigned)pp) >> 18; return (int)(((br & 0x2AAAu) >> 1) | ((br & 0x1555u) << 1)); }
; DI void pw_h(LAS hc* X, const f32x4* spec, int tid) {
;     ...
;     for (int r = 0; r < 16; ++r) {
;         const int k = tid + NTHR * r; const int pp = rev4(k);
;         const f32x4 sp = spec[k]; const cf P = (cf){sp[0], sp[1]} * 256.0f, Mq = (cf){sp[2], sp[3]} * 256.0f;
;         const hc zh = X[XI(pp)]; const cf z = (cf){(float)zh.x, (float)zh.y};
;         if (k == 0) { const cf y = cmul(z, P) + cmul((cf){z.x, -z.y}, Mq); X[XI(pp)] = (hc){(_Float16)y.x, (_Float16)y.y}; }
;         else { const int pm = rev4(16384 - k); const hc zmh = X[XI(pm)]; const cf zm = (cf){(float)zmh.x, (float)zmh.y};
;             const cf y = cmul(z, P) + cmul((cf){zm.x, -zm.y}, Mq);
;             const cf t = cmul((cf){zm.x, -zm.y}, P) + cmul(z, Mq);
;             X[XI(pp)] = (hc){(_Float16)y.x, (_Float16)y.y}; X[XI(pm)] = (hc){(_Float16)t.x, (_Float16)(-t.y)}; }
.LBB0_774:
	s_or_b64 exec, exec, s[22:23]
	v_add_u32_e32 v2, 0x2c00, v8
	v_bfrev_b32_e32 v3, v2
	v_lshrrev_b32_e32 v4, 19, v3
	v_lshrrev_b32_e32 v3, 17, v3
	v_and_b32_e32 v3, 0x2aaa, v3
	v_and_or_b32 v9, v4, s89, v3
	v_cmp_ne_u32_e64 s[40:41], s96, v8
	s_waitcnt vmcnt(1)
	v_mov_b32_e32 v4, v124
	v_mov_b32_e32 v5, v125
	v_mov_b32_e32 v6, v126
	v_mov_b32_e32 v7, v127
	v_pk_mul_f32 v[2:3], v[6:7], s[90:91] op_sel_hi:[1,0]
	v_lshl_add_u32 v6, v9, 2, s66
	v_lshrrev_b32_e32 v7, 2, v9
	v_lshrrev_b32_e32 v9, 6, v9
	v_and_b32_e32 v7, 0xffc, v7
	v_and_b32_e32 v9, 0xfc, v9
	v_add3_u32 v9, v6, v7, v9
	ds_read_b32 v7, v9
	v_pk_mul_f32 v[4:5], v[4:5], s[90:91] op_sel_hi:[1,0]
	s_waitcnt lgkmcnt(0)
	v_cvt_f32_f16_e32 v6, v7
	v_cvt_f32_f16_sdwa v7, v7 dst_sel:DWORD dst_unused:UNUSED_PAD src0_sel:WORD_1
	s_and_saveexec_b64 s[6:7], s[40:41]
	s_xor_b64 s[22:23], exec, s[6:7]
	s_cbranch_execz .LBB0_776
	v_add_u32_e32 v10, 0x200, v20
	v_bfrev_b32_e32 v10, v10
	v_lshrrev_b32_e32 v11, 19, v10
	v_lshrrev_b32_e32 v10, 17, v10
	v_and_b32_e32 v10, 0x2aaa, v10
	v_and_or_b32 v10, v11, s89, v10
	v_lshl_add_u32 v11, v10, 2, s66
	v_lshrrev_b32_e32 v13, 2, v10
	v_lshrrev_b32_e32 v10, 6, v10
	v_and_b32_e32 v13, 0xffc, v13
	v_and_b32_e32 v10, 0xfc, v10
	v_add3_u32 v13, v11, v13, v10
	ds_read_b32 v11, v13
	v_pk_mul_f32 v[14:15], v[6:7], v[4:5] op_sel:[0,0] op_sel_hi:[0,1]
	s_waitcnt lgkmcnt(0)
	v_cvt_f32_f16_e32 v10, v11
	v_cvt_f32_f16_sdwa v11, -v11 dst_sel:DWORD dst_unused:UNUSED_PAD src0_sel:WORD_1
	v_pk_mul_f32 v[16:17], v[10:11], v[2:3] op_sel:[0,0] op_sel_hi:[0,1]
	v_pk_fma_f32 v[14:15], v[6:7], v[4:5], v[14:15] op_sel:[1,1,0] op_sel_hi:[1,0,1] neg_lo:[0,1,0]
	v_pk_fma_f32 v[16:17], v[10:11], v[2:3], v[16:17] op_sel:[1,1,0] op_sel_hi:[1,0,1] neg_lo:[0,1,0]
	v_pk_add_f32 v[14:15], v[14:15], v[16:17]
	v_pk_mul_f32 v[16:17], v[10:11], v[4:5] op_sel:[0,0] op_sel_hi:[0,1]
	v_pk_fma_f32 v[4:5], v[10:11], v[4:5], v[16:17] op_sel:[1,1,0] op_sel_hi:[1,0,1] neg_lo:[0,1,0]
	v_pk_mul_f32 v[10:11], v[6:7], v[2:3] op_sel:[0,0] op_sel_hi:[0,1]
	v_pk_fma_f32 v[2:3], v[6:7], v[2:3], v[10:11] op_sel:[1,1,0] op_sel_hi:[1,0,1] neg_lo:[0,1,0]
	s_nop 0
	v_pk_add_f32 v[2:3], v[4:5], v[2:3]
	v_cvt_pk_f16_f32 v4, v14, v15
	v_cvt_pk_f16_f32 v2, v2, -v3
	ds_write_b32 v9, v4
	ds_write_b32 v13, v2

; DI int rev4(int pp) { const unsigned br = __brev((unsigned)pp) >> 18; return (int)(((br & 0x2AAAu) >> 1) | ((br & 0x1555u) << 1)); }
; DI void pw_h(LAS hc* X, const f32x4* spec, int tid) {
;     ...
;     for (int r = 0; r < 16; ++r) {
;         const int k = tid + NTHR * r; const int pp = rev4(k);
;         const f32x4 sp = spec[k]; const cf P = (cf){sp[0], sp[1]} * 256.0f, Mq = (cf){sp[2], sp[3]} * 256.0f;
;         const hc zh = X[XI(pp)]; const cf z = (cf){(float)zh.x, (float)zh.y};
;         if (k == 0) { const cf y = cmul(z, P) + cmul((cf){z.x, -z.y}, Mq); X[XI(pp)] = (hc){(_Float16)y.x, (_Float16)y.y}; }
;         else { const int pm = rev4(16384 - k); const hc zmh = X[XI(pm)]; const cf zm = (cf){(float)zmh.x, (float)zmh.y};
;             const cf y = cmul(z, P) + cmul((cf){zm.x, -zm.y}, Mq);
;             const cf t = cmul((cf){zm.x, -zm.y}, P) + cmul(z, Mq);
;             X[XI(pp)] = (hc){(_Float16)y.x, (_Float16)y.y}; X[XI(pm)] = (hc){(_Float16)t.x, (_Float16)(-t.y)}; }
.LBB0_778:
	s_or_b64 exec, exec, s[22:23]
	v_add_u32_e32 v2, 0x2e00, v8
	v_bfrev_b32_e32 v3, v2
	v_lshrrev_b32_e32 v4, 19, v3
	v_lshrrev_b32_e32 v3, 17, v3
	v_and_b32_e32 v3, 0x2aaa, v3
	v_and_or_b32 v9, v4, s89, v3
	v_cmp_ne_u32_e64 s[40:41], s84, v8
	s_waitcnt vmcnt(0)
	v_mov_b32_e32 v4, v128
	v_mov_b32_e32 v5, v129
	v_mov_b32_e32 v6, v130
	v_mov_b32_e32 v7, v131
	v_pk_mul_f32 v[2:3], v[6:7], s[90:91] op_sel_hi:[1,0]
	v_lshl_add_u32 v6, v9, 2, s66
	v_lshrrev_b32_e32 v7, 2, v9
	v_lshrrev_b32_e32 v9, 6, v9
	v_and_b32_e32 v7, 0xffc, v7
	v_and_b32_e32 v9, 0xfc, v9
	v_add3_u32 v9, v6, v7, v9
	ds_read_b32 v7, v9
	v_pk_mul_f32 v[4:5], v[4:5], s[90:91] op_sel_hi:[1,0]
	s_waitcnt lgkmcnt(0)
	v_cvt_f32_f16_e32 v6, v7
	v_cvt_f32_f16_sdwa v7, v7 dst_sel:DWORD dst_unused:UNUSED_PAD src0_sel:WORD_1
	s_and_saveexec_b64 s[6:7], s[40:41]
	s_xor_b64 s[22:23], exec, s[6:7]
	s_cbranch_execz .LBB0_780
	v_bfrev_b32_e32 v8, v20
	v_lshrrev_b32_e32 v10, 19, v8
	v_lshrrev_b32_e32 v8, 17, v8
	v_and_b32_e32 v8, 0x2aaa, v8
	v_and_or_b32 v8, v10, s89, v8
	v_lshl_add_u32 v10, v8, 2, s66
	v_lshrrev_b32_e32 v11, 2, v8
	v_lshrrev_b32_e32 v8, 6, v8
	v_and_b32_e32 v11, 0xffc, v11
	v_and_b32_e32 v8, 0xfc, v8
	v_add3_u32 v8, v10, v11, v8
	ds_read_b32 v11, v8
	v_pk_mul_f32 v[14:15], v[6:7], v[4:5] op_sel:[0,0] op_sel_hi:[0,1]
	s_waitcnt lgkmcnt(0)
	v_cvt_f32_f16_e32 v10, v11
	v_cvt_f32_f16_sdwa v11, -v11 dst_sel:DWORD dst_unused:UNUSED_PAD src0_sel:WORD_1
	v_pk_mul_f32 v[16:17], v[10:11], v[2:3] op_sel:[0,0] op_sel_hi:[0,1]
	v_pk_fma_f32 v[14:15], v[6:7], v[4:5], v[14:15] op_sel:[1,1,0] op_sel_hi:[1,0,1] neg_lo:[0,1,0]
	v_pk_fma_f32 v[16:17], v[10:11], v[2:3], v[16:17] op_sel:[1,1,0] op_sel_hi:[1,0,1] neg_lo:[0,1,0]
	v_pk_add_f32 v[14:15], v[14:15], v[16:17]
	v_pk_mul_f32 v[16:17], v[10:11], v[4:5] op_sel:[0,0] op_sel_hi:[0,1]
	v_pk_fma_f32 v[4:5], v[10:11], v[4:5], v[16:17] op_sel:[1,1,0] op_sel_hi:[1,0,1] neg_lo:[0,1,0]
	v_pk_mul_f32 v[10:11], v[6:7], v[2:3] op_sel:[0,0] op_sel_hi:[0,1]
	v_pk_fma_f32 v[2:3], v[6:7], v[2:3], v[10:11] op_sel:[1,1,0] op_sel_hi:[1,0,1] neg_lo:[0,1,0]
	s_nop 0
	v_pk_add_f32 v[2:3], v[4:5], v[2:3]
	v_cvt_pk_f16_f32 v4, v14, v15
	v_cvt_pk_f16_f32 v2, v2, -v3
	ds_write_b32 v9, v4
	ds_write_b32 v8, v2

; DI void hyena_item(const Params& p, int l, int dpr, LAS unsigned char* lds) {
;     ...
; #pragma unroll 4
;     for (int r = 0; r < 16; ++r) { const int t = tid + NTHR * r; const hc y0 = X0[XI(t)], y1 = X1[XI(t)];
;         const float yv[4] = {(float)y0.x, (float)y0.y, (float)y1.x, (float)y1.y};
; #pragma unroll
;         for (int c = 0; c < 4; ++c) z2t[(size_t)(a + c) * S + t] = yv[c] * (1.0f / 64.0f) * conv3(bint + (size_t)(2048 + a + c) * S, t, w[c][0], w[c][1], w[c][2]); }
.LBB0_797:
	v_add_u32_e32 v14, s7, v12
	v_mov_b32_e32 v140, v14
	v_ashrrev_i32_e32 v141, 31, v140
	v_lshlrev_b64 v[140:141], 2, v[140:141]
	v_lshl_add_u64 v[142:143], s[24:25], 0, v[140:141]
	global_load_dword v144, v[142:143], off
	v_lshl_add_u64 v[142:143], s[22:23], 0, v[140:141]
	global_load_dword v145, v[142:143], off
	v_lshl_add_u64 v[142:143], s[18:19], 0, v[140:141]
	global_load_dword v146, v[142:143], off
	v_lshl_add_u64 v[142:143], s[16:17], 0, v[140:141]
	global_load_dword v147, v[142:143], off
	v_add_u32_e32 v140, 0x200, v14
	v_ashrrev_i32_e32 v141, 31, v140
	v_lshlrev_b64 v[140:141], 2, v[140:141]
	v_lshl_add_u64 v[142:143], s[24:25], 0, v[140:141]
	global_load_dword v148, v[142:143], off
	v_lshl_add_u64 v[142:143], s[22:23], 0, v[140:141]
	global_load_dword v149, v[142:143], off
	v_lshl_add_u64 v[142:143], s[18:19], 0, v[140:141]
	global_load_dword v150, v[142:143], off
	v_lshl_add_u64 v[142:143], s[16:17], 0, v[140:141]
	global_load_dword v151, v[142:143], off
	v_add_u32_e32 v140, 0x400, v14
	v_ashrrev_i32_e32 v141, 31, v140
	v_lshlrev_b64 v[140:141], 2, v[140:141]
	v_lshl_add_u64 v[142:143], s[24:25], 0, v[140:141]
	global_load_dword v152, v[142:143], off
	v_lshl_add_u64 v[142:143], s[22:23], 0, v[140:141]
	global_load_dword v153, v[142:143], off
	v_lshl_add_u64 v[142:143], s[18:19], 0, v[140:141]
	global_load_dword v154, v[142:143], off
	v_lshl_add_u64 v[142:143], s[16:17], 0, v[140:141]
	global_load_dword v155, v[142:143], off
	v_add_u32_e32 v140, 0x600, v14
	v_ashrrev_i32_e32 v141, 31, v140
	v_lshlrev_b64 v[140:141], 2, v[140:141]
	v_lshl_add_u64 v[142:143], s[24:25], 0, v[140:141]
	global_load_dword v156, v[142:143], off
	v_lshl_add_u64 v[142:143], s[22:23], 0, v[140:141]
	global_load_dword v157, v[142:143], off
	v_lshl_add_u64 v[142:143], s[18:19], 0, v[140:141]
	global_load_dword v158, v[142:143], off
	v_lshl_add_u64 v[142:143], s[16:17], 0, v[140:141]
	global_load_dword v159, v[142:143], off
	v_ashrrev_i32_e32 v13, 4, v14
	v_ashrrev_i32_e32 v15, 8, v14
	v_add_u32_e32 v13, v13, v15
	v_add_lshl_u32 v13, v14, v13, 2
	v_add_u32_e32 v15, 0, v13
	ds_read_b32 v15, v15
	v_add_u32_e32 v13, s66, v13
	ds_read_b32 v13, v13
	v_max_i32_e32 v96, 1, v14
	v_min_i32_e32 v18, 0x1ffe, v14
	s_waitcnt lgkmcnt(1)
	v_cvt_f32_f16_e32 v20, v15
	v_cvt_f32_f16_sdwa v26, v15 dst_sel:DWORD dst_unused:UNUSED_PAD src0_sel:WORD_1
	v_ashrrev_i32_e32 v15, 31, v14
	v_lshlrev_b64 v[22:23], 2, v[14:15]
	v_mul_f32_e32 v15, 0x3c800000, v20
	v_lshl_add_u64 v[20:21], s[24:25], 0, v[22:23]
	global_load_dword v28, v[20:21], off
	v_lshlrev_b64 v[20:21], 2, v[96:97]
	v_ashrrev_i32_e32 v19, 31, v18
	v_lshl_add_u64 v[24:25], s[24:25], 0, v[20:21]
	global_load_dword v29, v[24:25], off offset:-4
	v_lshlrev_b64 v[18:19], 2, v[18:19]
	v_lshl_add_u64 v[24:25], s[24:25], 0, v[18:19]
	global_load_dword v24, v[24:25], off offset:4
	v_cmp_lt_i32_e32 vcc, 0, v14
	v_cmp_gt_i32_e64 s[40:41], s29, v14
	v_lshl_add_u64 v[16:17], s[20:21], 0, v[22:23]
	s_waitcnt lgkmcnt(0)
	v_cvt_f32_f16_e32 v27, v13
	v_cvt_f32_f16_sdwa v13, v13 dst_sel:DWORD dst_unused:UNUSED_PAD src0_sel:WORD_1
	s_addk_i32 s7, 0x800
	s_cmpk_lg_i32 s7, 0x2000
	v_mul_f32_e32 v13, 0x3c800000, v13
	s_waitcnt vmcnt(1)
	v_cndmask_b32_e32 v25, 0, v29, vcc
	v_mul_f32_e32 v25, v0, v25
	v_fmac_f32_e32 v25, v4, v28
	s_waitcnt vmcnt(0)
	v_cndmask_b32_e64 v24, 0, v24, s[40:41]
	v_fmac_f32_e32 v25, v8, v24
	v_mul_f32_e32 v15, v15, v25
	v_lshl_add_u64 v[24:25], v[16:17], 0, s[50:51]
	global_store_dword v[24:25], v15, off
	v_lshl_add_u64 v[24:25], s[22:23], 0, v[22:23]
	v_mul_f32_e32 v15, 0x3c800000, v26
	global_load_dword v26, v[24:25], off
	v_lshl_add_u64 v[24:25], s[22:23], 0, v[20:21]
	global_load_dword v28, v[24:25], off offset:-4
	v_lshl_add_u64 v[24:25], s[22:23], 0, v[18:19]
	global_load_dword v24, v[24:25], off offset:4
	s_waitcnt vmcnt(1)
	v_cndmask_b32_e32 v25, 0, v28, vcc
	v_mul_f32_e32 v25, v1, v25
	s_waitcnt vmcnt(0)
	v_cndmask_b32_e64 v24, 0, v24, s[40:41]
	v_fmac_f32_e32 v25, v5, v26
	v_fmac_f32_e32 v25, v9, v24
	v_mul_f32_e32 v15, v15, v25
	v_lshl_add_u64 v[24:25], v[16:17], 0, s[52:53]
	global_store_dword v[24:25], v15, off
	v_lshl_add_u64 v[24:25], s[18:19], 0, v[22:23]
	global_load_dword v26, v[24:25], off
	v_lshl_add_u64 v[24:25], s[18:19], 0, v[20:21]
	v_mul_f32_e32 v15, 0x3c800000, v27
	global_load_dword v27, v[24:25], off offset:-4
	v_lshl_add_u64 v[24:25], s[18:19], 0, v[18:19]
	global_load_dword v24, v[24:25], off offset:4
	v_lshl_add_u64 v[22:23], s[16:17], 0, v[22:23]
	v_lshl_add_u64 v[20:21], s[16:17], 0, v[20:21]
	v_lshl_add_u64 v[18:19], s[16:17], 0, v[18:19]
	s_waitcnt vmcnt(1)
	v_cndmask_b32_e32 v25, 0, v27, vcc
	v_mul_f32_e32 v25, v2, v25
	s_waitcnt vmcnt(0)
	v_cndmask_b32_e64 v24, 0, v24, s[40:41]
	v_fmac_f32_e32 v25, v6, v26
	v_fmac_f32_e32 v25, v10, v24
	v_mul_f32_e32 v15, v15, v25
	v_lshl_add_u64 v[24:25], v[16:17], 0, s[54:55]
	global_store_dword v[24:25], v15, off
	global_load_dword v15, v[22:23], off
	v_lshl_add_u64 v[16:17], v[16:17], 0, s[56:57]
	global_load_dword v20, v[20:21], off offset:-4
	s_nop 0
	global_load_dword v18, v[18:19], off offset:4
	s_waitcnt vmcnt(1)
	v_cndmask_b32_e32 v19, 0, v20, vcc
	v_mul_f32_e32 v19, v3, v19
	s_waitcnt vmcnt(0)
	v_cndmask_b32_e64 v18, 0, v18, s[40:41]
	v_fmac_f32_e32 v19, v7, v15
	v_fmac_f32_e32 v19, v11, v18
	v_mul_f32_e32 v13, v13, v19
	global_store_dword v[16:17], v13, off
	v_add_u32_e32 v16, 0x200, v14
	v_ashrrev_i32_e32 v13, 4, v16
	v_ashrrev_i32_e32 v15, 8, v16
	v_add_u32_e32 v13, v13, v15
	v_add_lshl_u32 v13, v14, v13, 2
	v_add_u32_e32 v15, 0, v13
	ds_read_b32 v15, v15 offset:2048
	v_add_u32_e32 v13, s66, v13
	ds_read_b32 v13, v13 offset:2048
	v_ashrrev_i32_e32 v17, 31, v16
	v_cmp_lt_i32_e32 vcc, 0, v16
	s_waitcnt lgkmcnt(1)
; DI void hyena_item(const Params& p, int l, int dpr, LAS unsigned char* lds) {
;     ...
; #pragma unroll 4
;     for (int r = 0; r < 16; ++r) { const int t = tid + NTHR * r; const hc y0 = X0[XI(t)], y1 = X1[XI(t)];
;         const float yv[4] = {(float)y0.x, (float)y0.y, (float)y1.x, (float)y1.y};
; #pragma unroll
;         for (int c = 0; c < 4; ++c) z2t[(size_t)(a + c) * S + t] = yv[c] * (1.0f / 64.0f) * conv3(bint + (size_t)(2048 + a + c) * S, t, w[c][0], w[c][1], w[c][2]); }
	v_cvt_f32_f16_e32 v18, v15
	v_max_i32_e32 v96, 1, v16
	v_cmp_gt_i32_e64 s[40:41], s29, v16
	v_min_i32_e32 v20, 0x1ffe, v16
	v_lshlrev_b64 v[16:17], 2, v[16:17]
	v_mul_f32_e32 v25, 0x3c800000, v18
	v_lshl_add_u64 v[18:19], s[24:25], 0, v[16:17]
	global_load_dword v26, v[18:19], off
	v_lshlrev_b64 v[18:19], 2, v[96:97]
	v_ashrrev_i32_e32 v21, 31, v20
	v_lshl_add_u64 v[22:23], s[24:25], 0, v[18:19]
	global_load_dword v27, v[22:23], off offset:-4
	v_lshlrev_b64 v[20:21], 2, v[20:21]
	v_lshl_add_u64 v[22:23], s[24:25], 0, v[20:21]
	global_load_dword v22, v[22:23], off offset:4
	v_cvt_f32_f16_sdwa v15, v15 dst_sel:DWORD dst_unused:UNUSED_PAD src0_sel:WORD_1
	s_waitcnt lgkmcnt(0)
	v_cvt_f32_f16_e32 v24, v13
	v_cvt_f32_f16_sdwa v13, v13 dst_sel:DWORD dst_unused:UNUSED_PAD src0_sel:WORD_1
	v_mul_f32_e32 v15, 0x3c800000, v15
	v_mul_f32_e32 v13, 0x3c800000, v13
	s_waitcnt vmcnt(1)
	v_cndmask_b32_e32 v23, 0, v27, vcc
	v_mul_f32_e32 v23, v0, v23
	v_fmac_f32_e32 v23, v4, v26
	s_waitcnt vmcnt(0)
	v_cndmask_b32_e64 v22, 0, v22, s[40:41]
	v_fmac_f32_e32 v23, v8, v22
	v_mul_f32_e32 v25, v25, v23
	v_lshl_add_u64 v[22:23], s[26:27], 0, v[16:17]
	global_store_dword v[22:23], v25, off
	v_lshl_add_u64 v[22:23], s[22:23], 0, v[16:17]
	global_load_dword v25, v[22:23], off
	v_lshl_add_u64 v[22:23], s[22:23], 0, v[18:19]
	global_load_dword v26, v[22:23], off offset:-4
	v_lshl_add_u64 v[22:23], s[22:23], 0, v[20:21]
	global_load_dword v22, v[22:23], off offset:4
	s_waitcnt vmcnt(1)
	v_cndmask_b32_e32 v23, 0, v26, vcc
	v_mul_f32_e32 v23, v1, v23
	s_waitcnt vmcnt(0)
	v_cndmask_b32_e64 v22, 0, v22, s[40:41]
	v_fmac_f32_e32 v23, v5, v25
	v_fmac_f32_e32 v23, v9, v22
	v_mul_f32_e32 v15, v15, v23
	v_lshl_add_u64 v[22:23], s[42:43], 0, v[16:17]
	global_store_dword v[22:23], v15, off
	v_lshl_add_u64 v[22:23], s[18:19], 0, v[16:17]
	v_mul_f32_e32 v15, 0x3c800000, v24
	global_load_dword v24, v[22:23], off
	v_lshl_add_u64 v[22:23], s[18:19], 0, v[18:19]
	global_load_dword v25, v[22:23], off offset:-4
	v_lshl_add_u64 v[22:23], s[18:19], 0, v[20:21]
	global_load_dword v22, v[22:23], off offset:4
	v_lshl_add_u64 v[18:19], s[16:17], 0, v[18:19]
	s_waitcnt vmcnt(1)
	v_cndmask_b32_e32 v23, 0, v25, vcc
	v_mul_f32_e32 v23, v2, v23
	s_waitcnt vmcnt(0)
	v_cndmask_b32_e64 v22, 0, v22, s[40:41]
	v_fmac_f32_e32 v23, v6, v24
	v_fmac_f32_e32 v23, v10, v22
	v_mul_f32_e32 v15, v15, v23
	v_lshl_add_u64 v[22:23], s[58:59], 0, v[16:17]
	global_store_dword v[22:23], v15, off
	v_lshl_add_u64 v[22:23], s[16:17], 0, v[16:17]
	global_load_dword v15, v[22:23], off
	v_lshl_add_u64 v[16:17], s[60:61], 0, v[16:17]
	global_load_dword v22, v[18:19], off offset:-4
	v_lshl_add_u64 v[18:19], s[16:17], 0, v[20:21]
	global_load_dword v18, v[18:19], off offset:4
	s_waitcnt vmcnt(1)
	v_cndmask_b32_e32 v19, 0, v22, vcc
	v_mul_f32_e32 v19, v3, v19
	s_waitcnt vmcnt(0)
	v_cndmask_b32_e64 v18, 0, v18, s[40:41]
	v_fmac_f32_e32 v19, v7, v15
	v_fmac_f32_e32 v19, v11, v18
	v_mul_f32_e32 v13, v13, v19
	global_store_dword v[16:17], v13, off
	v_add_u32_e32 v16, 0x400, v14
	v_ashrrev_i32_e32 v13, 4, v16
	v_ashrrev_i32_e32 v15, 8, v16
	v_add_u32_e32 v13, v13, v15
	v_add_lshl_u32 v13, v14, v13, 2
	v_add_u32_e32 v15, 0, v13
	ds_read_b32 v15, v15 offset:4096
	v_add_u32_e32 v13, s66, v13
	ds_read_b32 v13, v13 offset:4096
	v_ashrrev_i32_e32 v17, 31, v16
	v_lshlrev_b64 v[22:23], 2, v[16:17]
	s_waitcnt lgkmcnt(1)
	v_cvt_f32_f16_e32 v18, v15
	v_max_i32_e32 v96, 1, v16
	v_min_i32_e32 v20, 0x1ffe, v16
	v_ashrrev_i32_e32 v21, 31, v20
	v_mul_f32_e32 v27, 0x3c800000, v18
	v_lshl_add_u64 v[18:19], s[24:25], 0, v[22:23]
	global_load_dword v28, v[18:19], off
	v_lshlrev_b64 v[18:19], 2, v[96:97]
	v_lshl_add_u64 v[24:25], s[24:25], 0, v[18:19]
	global_load_dword v29, v[24:25], off offset:-4
	v_lshlrev_b64 v[20:21], 2, v[20:21]
	v_lshl_add_u64 v[24:25], s[24:25], 0, v[20:21]
	global_load_dword v24, v[24:25], off offset:4
	v_cmp_lt_i32_e32 vcc, 0, v16
	v_cmp_gt_i32_e64 s[40:41], s29, v16
	v_lshl_add_u64 v[16:17], s[20:21], 0, v[22:23]
	v_cvt_f32_f16_sdwa v15, v15 dst_sel:DWORD dst_unused:UNUSED_PAD src0_sel:WORD_1
	s_waitcnt lgkmcnt(0)
	v_cvt_f32_f16_e32 v26, v13
	v_cvt_f32_f16_sdwa v13, v13 dst_sel:DWORD dst_unused:UNUSED_PAD src0_sel:WORD_1
	v_mul_f32_e32 v15, 0x3c800000, v15
	v_mul_f32_e32 v13, 0x3c800000, v13
	s_waitcnt vmcnt(1)
	v_cndmask_b32_e32 v25, 0, v29, vcc
	v_mul_f32_e32 v25, v0, v25
	v_fmac_f32_e32 v25, v4, v28
	s_waitcnt vmcnt(0)
	v_cndmask_b32_e64 v24, 0, v24, s[40:41]
	v_fmac_f32_e32 v25, v8, v24
	v_mul_f32_e32 v27, v27, v25
	v_lshl_add_u64 v[24:25], v[16:17], 0, s[50:51]
	global_store_dword v[24:25], v27, off
	v_lshl_add_u64 v[24:25], s[22:23], 0, v[22:23]
	global_load_dword v27, v[24:25], off
	v_lshl_add_u64 v[24:25], s[22:23], 0, v[18:19]
	global_load_dword v28, v[24:25], off offset:-4
	v_lshl_add_u64 v[24:25], s[22:23], 0, v[20:21]
	global_load_dword v24, v[24:25], off offset:4
	s_waitcnt vmcnt(1)
	v_cndmask_b32_e32 v25, 0, v28, vcc
	v_mul_f32_e32 v25, v1, v25
	s_waitcnt vmcnt(0)
; DI void hyena_item(const Params& p, int l, int dpr, LAS unsigned char* lds) {
;     ...
; #pragma unroll 4
;     for (int r = 0; r < 16; ++r) { const int t = tid + NTHR * r; const hc y0 = X0[XI(t)], y1 = X1[XI(t)];
;         const float yv[4] = {(float)y0.x, (float)y0.y, (float)y1.x, (float)y1.y};
; #pragma unroll
;         for (int c = 0; c < 4; ++c) z2t[(size_t)(a + c) * S + t] = yv[c] * (1.0f / 64.0f) * conv3(bint + (size_t)(2048 + a + c) * S, t, w[c][0], w[c][1], w[c][2]); }
;     __syncthreads();
	v_cndmask_b32_e64 v24, 0, v24, s[40:41]
	v_fmac_f32_e32 v25, v5, v27
	v_fmac_f32_e32 v25, v9, v24
	v_mul_f32_e32 v15, v15, v25
	v_lshl_add_u64 v[24:25], v[16:17], 0, s[52:53]
	global_store_dword v[24:25], v15, off
	v_lshl_add_u64 v[24:25], s[18:19], 0, v[22:23]
	v_mul_f32_e32 v15, 0x3c800000, v26
	global_load_dword v26, v[24:25], off
	v_lshl_add_u64 v[24:25], s[18:19], 0, v[18:19]
	global_load_dword v27, v[24:25], off offset:-4
	v_lshl_add_u64 v[24:25], s[18:19], 0, v[20:21]
	global_load_dword v24, v[24:25], off offset:4
	v_lshl_add_u64 v[22:23], s[16:17], 0, v[22:23]
	v_lshl_add_u64 v[18:19], s[16:17], 0, v[18:19]
	s_waitcnt vmcnt(1)
	v_cndmask_b32_e32 v25, 0, v27, vcc
	v_mul_f32_e32 v25, v2, v25
	s_waitcnt vmcnt(0)
	v_cndmask_b32_e64 v24, 0, v24, s[40:41]
	v_fmac_f32_e32 v25, v6, v26
	v_fmac_f32_e32 v25, v10, v24
	v_mul_f32_e32 v15, v15, v25
	v_lshl_add_u64 v[24:25], v[16:17], 0, s[54:55]
	global_store_dword v[24:25], v15, off
	global_load_dword v15, v[22:23], off
	v_lshl_add_u64 v[16:17], v[16:17], 0, s[56:57]
	global_load_dword v22, v[18:19], off offset:-4
	v_lshl_add_u64 v[18:19], s[16:17], 0, v[20:21]
	global_load_dword v18, v[18:19], off offset:4
	s_waitcnt vmcnt(1)
	v_cndmask_b32_e32 v19, 0, v22, vcc
	v_mul_f32_e32 v19, v3, v19
	s_waitcnt vmcnt(0)
	v_cndmask_b32_e64 v18, 0, v18, s[40:41]
	v_fmac_f32_e32 v19, v7, v15
	v_fmac_f32_e32 v19, v11, v18
	v_mul_f32_e32 v13, v13, v19
	global_store_dword v[16:17], v13, off
	v_add_u32_e32 v16, 0x600, v14
	v_ashrrev_i32_e32 v13, 4, v16
	v_ashrrev_i32_e32 v15, 8, v16
	v_add_u32_e32 v13, v13, v15
	v_add_lshl_u32 v13, v14, v13, 2
	v_add_u32_e32 v14, 0, v13
	ds_read_b32 v14, v14 offset:6144
	v_add_u32_e32 v13, s66, v13
	ds_read_b32 v13, v13 offset:6144
	v_ashrrev_i32_e32 v17, 31, v16
	v_max_i32_e32 v96, 1, v16
	s_waitcnt lgkmcnt(1)
	v_cvt_f32_f16_e32 v20, v14
	v_lshlrev_b64 v[18:19], 2, v[16:17]
	v_cmp_lt_i32_e32 vcc, 0, v16
	v_cmp_gt_i32_e64 s[40:41], s29, v16
	v_min_i32_e32 v22, 0x1ffe, v16
	v_mul_f32_e32 v26, 0x3c800000, v20
	v_lshl_add_u64 v[16:17], s[24:25], 0, v[18:19]
	v_lshlrev_b64 v[20:21], 2, v[96:97]
	v_ashrrev_i32_e32 v23, 31, v22
	global_load_dword v27, v[16:17], off
	v_lshl_add_u64 v[16:17], s[24:25], 0, v[20:21]
	global_load_dword v28, v[16:17], off offset:-4
	v_lshlrev_b64 v[16:17], 2, v[22:23]
	v_lshl_add_u64 v[22:23], s[24:25], 0, v[16:17]
	global_load_dword v22, v[22:23], off offset:4
	v_cvt_f32_f16_sdwa v24, v14 dst_sel:DWORD dst_unused:UNUSED_PAD src0_sel:WORD_1
	v_lshl_add_u64 v[14:15], s[20:21], 0, v[18:19]
	s_waitcnt lgkmcnt(0)
	v_cvt_f32_f16_e32 v25, v13
	v_cvt_f32_f16_sdwa v13, v13 dst_sel:DWORD dst_unused:UNUSED_PAD src0_sel:WORD_1
	v_mul_f32_e32 v24, 0x3c800000, v24
	v_mul_f32_e32 v13, 0x3c800000, v13
	s_waitcnt vmcnt(1)
	v_cndmask_b32_e32 v23, 0, v28, vcc
	v_mul_f32_e32 v23, v0, v23
	v_fmac_f32_e32 v23, v4, v27
	s_waitcnt vmcnt(0)
	v_cndmask_b32_e64 v22, 0, v22, s[40:41]
	v_fmac_f32_e32 v23, v8, v22
	v_mul_f32_e32 v26, v26, v23
	v_lshl_add_u64 v[22:23], v[14:15], 0, s[50:51]
	global_store_dword v[22:23], v26, off
	v_lshl_add_u64 v[22:23], s[22:23], 0, v[18:19]
	global_load_dword v26, v[22:23], off
	v_lshl_add_u64 v[22:23], s[22:23], 0, v[20:21]
	global_load_dword v27, v[22:23], off offset:-4
	v_lshl_add_u64 v[22:23], s[22:23], 0, v[16:17]
	global_load_dword v22, v[22:23], off offset:4
	s_waitcnt vmcnt(1)
	v_cndmask_b32_e32 v23, 0, v27, vcc
	v_mul_f32_e32 v23, v1, v23
	s_waitcnt vmcnt(0)
	v_cndmask_b32_e64 v22, 0, v22, s[40:41]
	v_fmac_f32_e32 v23, v5, v26
	v_fmac_f32_e32 v23, v9, v22
	v_mul_f32_e32 v24, v24, v23
	v_lshl_add_u64 v[22:23], v[14:15], 0, s[52:53]
	global_store_dword v[22:23], v24, off
	v_lshl_add_u64 v[22:23], s[18:19], 0, v[18:19]
	v_mul_f32_e32 v24, 0x3c800000, v25
	global_load_dword v25, v[22:23], off
	v_lshl_add_u64 v[22:23], s[18:19], 0, v[20:21]
	global_load_dword v26, v[22:23], off offset:-4
	v_lshl_add_u64 v[22:23], s[18:19], 0, v[16:17]
	global_load_dword v22, v[22:23], off offset:4
	v_lshl_add_u64 v[18:19], s[16:17], 0, v[18:19]
	v_lshl_add_u64 v[16:17], s[16:17], 0, v[16:17]
	s_waitcnt vmcnt(1)
	v_cndmask_b32_e32 v23, 0, v26, vcc
	v_mul_f32_e32 v23, v2, v23
	s_waitcnt vmcnt(0)
	v_cndmask_b32_e64 v22, 0, v22, s[40:41]
	v_fmac_f32_e32 v23, v6, v25
	v_fmac_f32_e32 v23, v10, v22
	v_mul_f32_e32 v24, v24, v23
	v_lshl_add_u64 v[22:23], v[14:15], 0, s[54:55]
	global_store_dword v[22:23], v24, off
	global_load_dword v22, v[18:19], off
	v_lshl_add_u64 v[18:19], s[16:17], 0, v[20:21]
	global_load_dword v18, v[18:19], off offset:-4
	v_lshl_add_u64 v[14:15], v[14:15], 0, s[56:57]
	global_load_dword v16, v[16:17], off offset:4
	s_waitcnt vmcnt(1)
	v_cndmask_b32_e32 v17, 0, v18, vcc
	v_mul_f32_e32 v17, v3, v17
	s_waitcnt vmcnt(0)
	v_cndmask_b32_e64 v16, 0, v16, s[40:41]
	v_fmac_f32_e32 v17, v7, v22
	v_fmac_f32_e32 v17, v11, v16
	v_mul_f32_e32 v13, v13, v17
	global_store_dword v[14:15], v13, off
	s_cbranch_scc1 .LBB0_797
	v_readlane_b32 s62, v255, 31
	v_readlane_b32 s54, v255, 58
	v_readlane_b32 s63, v255, 32
	v_readlane_b32 s52, v255, 48
	v_readlane_b32 s55, v255, 59
	v_readlane_b32 s61, v255, 33
	s_movk_i32 s63, 0x2000
	s_mov_b32 s26, 0x800000
	s_mov_b32 s60, 0x78a5c000
	s_mov_b32 s27, 0x9000000
	s_mov_b32 s51, 0x409b43d5
	v_readlane_b32 s53, v255, 49
	v_readlane_b32 s50, v255, 52
	v_readlane_b32 s56, v255, 56
	v_readlane_b32 s58, v255, 54
	s_mov_b32 s55, s2
	s_barrier
	v_readlane_b32 s57, v255, 57
	v_readlane_b32 s59, v255, 55

; DI void xcd_barrier(const XcdBarrier& b) {
;     asm volatile("s_waitcnt vmcnt(0)" ::: "memory");
;     __syncthreads();
;     if (threadIdx.x == 0) {
;         unsigned* bar = b.bar;
;         __builtin_amdgcn_s_waitcnt(0);
;         unsigned nloc = b.st[0], nx = b.st[1];
;         if (nloc == 0u) { xcd_barrier_complete(bar, b.x, nloc, nx); b.st[0] = nloc; b.st[1] = nx; }
; __global__ void __launch_bounds__(512, 2) mega_kernel(Params p) {
;     ...
;     for (int ph = ph_lo; ph < ph_hi; ++ph) {
;         ParamsK pc = (ParamsK)__builtin_amdgcn_kernarg_segment_ptr();
;         run_phase(pc, ph, lds);
;         if (ph + 1 < ph_hi) { if (ph == ph_lo) grid.sync(); else xcd_barrier(xb); }
.LBB0_962:
	v_readlane_b32 s4, v253, 1
	v_readlane_b32 s5, v253, 2
	v_readlane_b32 s6, v253, 3
	s_cmp_lg_u32 s8, s6
	s_mov_b64 s[4:5], -1
	v_readlane_b32 s7, v253, 4
	s_waitcnt vmcnt(0)
	s_barrier
	s_mov_b64 s[4:5], exec
	v_readlane_b32 s6, v253, 9
	v_readlane_b32 s7, v253, 10
	s_and_b64 s[6:7], s[4:5], s[6:7]
	s_mov_b64 exec, s[6:7]
	s_cbranch_execz .LBB0_1015
	v_readlane_b32 s6, v255, 21
	s_waitcnt vmcnt(0) expcnt(0) lgkmcnt(0)
	s_nop 0
	v_mov_b32_e32 v0, s6
	ds_read_b32 v2, v0
	v_readlane_b32 s6, v255, 22
	s_waitcnt lgkmcnt(0)
	v_cmp_ne_u32_e32 vcc, 0, v2
	v_mov_b32_e32 v0, s6
	ds_read_b32 v0, v0
	s_cbranch_vccnz .LBB0_979
	s_mov_b32 s12, 1
	s_branch .LBB0_967
